# RMW epilogues (4x FFN2, 2x out-proj): de-serialise the 32-step load-wait-store ladder - prefetch residual loads 16 steps deep into free fragment registers with counted vmcnt, hoist gate loads
# speedup vs baseline: 1.0103x; 1.0103x over previous
; DI float dppx1(float v) { return __int_as_float(__builtin_amdgcn_update_dpp(0, __float_as_int(v), 0xB1, 0xF, 0xF, true)); }
; DI void rmw_pair_f32(float* xo_even, const float* xi_even, long ld, bool odd, float v0, float v1, float v2, float v3) {
;   const float sx = odd ? v0 : v2, sy = odd ? v1 : v3;
;   const float rx = dppx1(sx), ry = dppx1(sy);
;   const long off = odd ? 2 * ld : 0;
;   const float2 a0 = *(const float2*)(xi_even + off), a1 = *(const float2*)(xi_even + off + ld);
;   float2 o0, o1;
;   if (odd) { o0 = float2{a0.x + rx, a0.y + v2}; o1 = float2{a1.x + ry, a1.y + v3}; }
;   else     { o0 = float2{a0.x + v0, a0.y + rx}; o1 = float2{a1.x + v1, a1.y + ry}; }
;   *(float2*)(xo_even + off) = o0;
;   *(float2*)(xo_even + off + ld) = o1;
; }
; __global__ void __launch_bounds__(NTHR) fwd_kernel(Params pk) {
;     ...
;           const int b = (pm * 256) >> 13;
; #pragma unroll
;           for (int bj = 0; bj < 2; ++bj)
; #pragma unroll
;             for (int n = 0; n < 2; ++n) {
;               const int col = pn * 256 + bj * 128 + wc * 32 + n * 16 + fr;
;               const float gv = 0.5f * gate[(long)b * 9216 + col];
; #pragma unroll
;               for (int ai = 0; ai < 2; ++ai)
; #pragma unroll
;                 for (int m = 0; m < 4; ++m) {
;                   const long row0 = (long)pm * 256 + ai * 128 + wr * 64 + m * 16 + fq * 4;
;                   const f32x4 a = acc[ai][bj][m][n];
;                   rmw_pair_f32(xo + row0 * DM + (col & ~1), xin + row0 * DM + (col & ~1), DM, col & 1, gv * a[0], gv * a[1], gv * a[2], gv * a[3]);
.LBB0_201:
	s_ashr_i32 s4, s8, 5
	s_lshl_b32 s3, s3, 8
	s_ashr_i32 s9, s8, 31
	v_lshl_or_b32 v134, v150, 5, s3
	s_mul_hi_i32 s3, s4, 0x9000
	s_mul_i32 s66, s4, 0x9000
	s_lshl_b64 s[4:5], s[8:9], 8
	v_ashrrev_i32_e32 v133, 31, v132
	v_or_b32_e32 v136, v134, v141
	v_lshl_add_u64 v[130:131], s[4:5], 0, v[132:133]
	s_add_u32 s4, s6, s66
	v_ashrrev_i32_e32 v137, 31, v136
	s_addc_u32 s5, s7, s3
	v_lshl_add_u64 v[138:139], v[136:137], 2, s[4:5]
	v_lshl_or_b32 v130, v149, 2, v130
	global_load_dword v244, v[138:139], off
	global_load_dword v245, v[138:139], off offset:64
	global_load_dword v246, v[138:139], off offset:512
	global_load_dword v247, v[138:139], off offset:576
	v_bitop3_b32 v132, v134, s77, v141 bitop3:0xc8
	v_ashrrev_i32_e32 v133, 31, v132
	v_lshlrev_b64 v[142:143], 12, v[130:131]
	v_bfe_i32 v128, v146, 0, 1
	v_lshlrev_b64 v[140:141], 2, v[132:133]
	v_lshl_add_u64 v[132:133], s[12:13], 0, v[142:143]
	v_and_b32_e32 v128, 0x2000, v128
	v_lshl_add_u64 v[130:131], v[132:133], 0, v[140:141]
	v_lshl_add_u64 v[130:131], v[130:131], 0, v[128:129]
	v_add_co_u32_e32 v134, vcc, s75, v130
	v_and_b32_e32 v161, 1, v146
	s_nop 0
	v_addc_co_u32_e32 v135, vcc, 0, v131, vcc
	v_mov_b64_e32 v[248:249], v[130:131]
	global_load_dwordx2 v[168:169], v[248:249], off
	s_mov_b32 s98, 0x1000
	s_mov_b32 s99, 0
	v_lshl_add_u64 v[250:251], v[248:249], 0, s[98:99]
	global_load_dwordx2 v[170:171], v[250:251], off
	s_mov_b32 s98, 0x10000
	s_mov_b32 s99, 0
	v_lshl_add_u64 v[250:251], v[248:249], 0, s[98:99]
	global_load_dwordx2 v[172:173], v[250:251], off
	s_mov_b32 s98, 0x11000
	s_mov_b32 s99, 0
	v_lshl_add_u64 v[250:251], v[248:249], 0, s[98:99]
	global_load_dwordx2 v[174:175], v[250:251], off
	s_mov_b32 s98, 0x20000
	s_mov_b32 s99, 0
	v_lshl_add_u64 v[250:251], v[248:249], 0, s[98:99]
	global_load_dwordx2 v[176:177], v[250:251], off
	s_mov_b32 s98, 0x21000
	s_mov_b32 s99, 0
	v_lshl_add_u64 v[250:251], v[248:249], 0, s[98:99]
	global_load_dwordx2 v[178:179], v[250:251], off
	s_mov_b32 s98, 0x30000
	s_mov_b32 s99, 0
	v_lshl_add_u64 v[250:251], v[248:249], 0, s[98:99]
	global_load_dwordx2 v[180:181], v[250:251], off
	s_mov_b32 s98, 0x31000
	s_mov_b32 s99, 0
	v_lshl_add_u64 v[250:251], v[248:249], 0, s[98:99]
	global_load_dwordx2 v[182:183], v[250:251], off
	s_mov_b32 s98, 0x80000
	s_mov_b32 s99, 0
	v_lshl_add_u64 v[250:251], v[248:249], 0, s[98:99]
	global_load_dwordx2 v[184:185], v[250:251], off
	s_mov_b32 s98, 0x81000
	s_mov_b32 s99, 0
	v_lshl_add_u64 v[250:251], v[248:249], 0, s[98:99]
	global_load_dwordx2 v[186:187], v[250:251], off
	s_mov_b32 s98, 0x90000
	s_mov_b32 s99, 0
	v_lshl_add_u64 v[250:251], v[248:249], 0, s[98:99]
	global_load_dwordx2 v[188:189], v[250:251], off
	s_mov_b32 s98, 0x91000
	s_mov_b32 s99, 0
	v_lshl_add_u64 v[250:251], v[248:249], 0, s[98:99]
	global_load_dwordx2 v[190:191], v[250:251], off
	s_mov_b32 s98, 0xa0000
	s_mov_b32 s99, 0
	v_lshl_add_u64 v[250:251], v[248:249], 0, s[98:99]
	global_load_dwordx2 v[192:193], v[250:251], off
	s_mov_b32 s98, 0xa1000
	s_mov_b32 s99, 0
	v_lshl_add_u64 v[250:251], v[248:249], 0, s[98:99]
	global_load_dwordx2 v[196:197], v[250:251], off
	s_mov_b32 s98, 0xb0000
	s_mov_b32 s99, 0
	v_lshl_add_u64 v[250:251], v[248:249], 0, s[98:99]
	global_load_dwordx2 v[198:199], v[250:251], off
	s_mov_b32 s98, 0xb1000
	s_mov_b32 s99, 0
	v_lshl_add_u64 v[250:251], v[248:249], 0, s[98:99]
	global_load_dwordx2 v[200:201], v[250:251], off
	s_mov_b32 s98, 0x40
	s_mov_b32 s99, 0
	v_lshl_add_u64 v[250:251], v[248:249], 0, s[98:99]
	global_load_dwordx2 v[202:203], v[250:251], off
	s_mov_b32 s98, 0x1040
	s_mov_b32 s99, 0
	v_lshl_add_u64 v[250:251], v[248:249], 0, s[98:99]
	global_load_dwordx2 v[204:205], v[250:251], off
	s_mov_b32 s98, 0x10040
	s_mov_b32 s99, 0
	v_lshl_add_u64 v[250:251], v[248:249], 0, s[98:99]
	global_load_dwordx2 v[206:207], v[250:251], off
	s_mov_b32 s98, 0x11040
	s_mov_b32 s99, 0
	v_lshl_add_u64 v[250:251], v[248:249], 0, s[98:99]
	global_load_dwordx2 v[208:209], v[250:251], off
	s_mov_b32 s98, 0x20040
	s_mov_b32 s99, 0
	v_lshl_add_u64 v[250:251], v[248:249], 0, s[98:99]
	global_load_dwordx2 v[210:211], v[250:251], off
	s_mov_b32 s98, 0x21040
	s_mov_b32 s99, 0
	v_lshl_add_u64 v[250:251], v[248:249], 0, s[98:99]
	global_load_dwordx2 v[212:213], v[250:251], off
	s_mov_b32 s98, 0x30040
	s_mov_b32 s99, 0
	v_lshl_add_u64 v[250:251], v[248:249], 0, s[98:99]
	global_load_dwordx2 v[214:215], v[250:251], off
	s_mov_b32 s98, 0x31040
	s_mov_b32 s99, 0
	v_lshl_add_u64 v[250:251], v[248:249], 0, s[98:99]
	global_load_dwordx2 v[216:217], v[250:251], off
	s_mov_b32 s98, 0x80040
	s_mov_b32 s99, 0
	v_lshl_add_u64 v[250:251], v[248:249], 0, s[98:99]
	global_load_dwordx2 v[218:219], v[250:251], off
	s_mov_b32 s98, 0x81040
	s_mov_b32 s99, 0
	v_lshl_add_u64 v[250:251], v[248:249], 0, s[98:99]
	global_load_dwordx2 v[220:221], v[250:251], off
	s_mov_b32 s98, 0x90040
	s_mov_b32 s99, 0
	v_lshl_add_u64 v[250:251], v[248:249], 0, s[98:99]
	global_load_dwordx2 v[222:223], v[250:251], off
	s_mov_b32 s98, 0x91040
	s_mov_b32 s99, 0
	v_lshl_add_u64 v[250:251], v[248:249], 0, s[98:99]
	global_load_dwordx2 v[224:225], v[250:251], off
	s_mov_b32 s98, 0xa0040
	s_mov_b32 s99, 0
	v_lshl_add_u64 v[250:251], v[248:249], 0, s[98:99]
	global_load_dwordx2 v[226:227], v[250:251], off
	s_mov_b32 s98, 0xa1040
	s_mov_b32 s99, 0
	v_lshl_add_u64 v[250:251], v[248:249], 0, s[98:99]
	global_load_dwordx2 v[228:229], v[250:251], off
	s_mov_b32 s98, 0xb0040
	s_mov_b32 s99, 0
	v_lshl_add_u64 v[250:251], v[248:249], 0, s[98:99]
	global_load_dwordx2 v[230:231], v[250:251], off
	s_mov_b32 s98, 0xb1040
	s_mov_b32 s99, 0
	v_lshl_add_u64 v[250:251], v[248:249], 0, s[98:99]
	global_load_dwordx2 v[232:233], v[250:251], off
	v_cmp_eq_u32_e64 s[8:9], 0, v161
	v_lshl_add_u64 v[130:131], s[14:15], 0, v[142:143]
	v_or_b32_e32 v146, 0x10000, v142
	v_mov_b32_e32 v147, v143
	v_lshl_add_u64 v[152:153], v[130:131], 0, v[140:141]
	v_lshl_add_u64 v[134:135], s[12:13], 0, v[146:147]
	v_lshl_add_u64 v[152:153], v[152:153], 0, v[128:129]
	v_lshl_add_u64 v[154:155], v[134:135], 0, v[140:141]
	v_add_co_u32_e32 v156, vcc, s75, v152
	v_lshl_add_u64 v[154:155], v[154:155], 0, v[128:129]
	s_nop 0
	v_addc_co_u32_e32 v157, vcc, 0, v153, vcc
	v_add_co_u32_e32 v158, vcc, s75, v154
	s_mov_b64 s[72:73], 0
	s_nop 0
	v_addc_co_u32_e32 v159, vcc, 0, v155, vcc
	s_mov_b32 s3, s83
	s_mov_b64 s[70:71], s[62:63]
	s_mov_b64 s[68:69], s[60:61]
	s_waitcnt vmcnt(30)
; DI float dppx1(float v) { return __int_as_float(__builtin_amdgcn_update_dpp(0, __float_as_int(v), 0xB1, 0xF, 0xF, true)); }
; DI void rmw_pair_f32(float* xo_even, const float* xi_even, long ld, bool odd, float v0, float v1, float v2, float v3) {
;   const float sx = odd ? v0 : v2, sy = odd ? v1 : v3;
;   const float rx = dppx1(sx), ry = dppx1(sy);
;   const long off = odd ? 2 * ld : 0;
;   const float2 a0 = *(const float2*)(xi_even + off), a1 = *(const float2*)(xi_even + off + ld);
;   float2 o0, o1;
;   if (odd) { o0 = float2{a0.x + rx, a0.y + v2}; o1 = float2{a1.x + ry, a1.y + v3}; }
;   else     { o0 = float2{a0.x + v0, a0.y + rx}; o1 = float2{a1.x + v1, a1.y + ry}; }
;   *(float2*)(xo_even + off) = o0;
;   *(float2*)(xo_even + off + ld) = o1;
; }
; __global__ void __launch_bounds__(NTHR) fwd_kernel(Params pk) {
;     ...
;                 for (int m = 0; m < 4; ++m) {
;                   const long row0 = (long)pm * 256 + ai * 128 + wr * 64 + m * 16 + fq * 4;
;                   const f32x4 a = acc[ai][bj][m][n];
;                   rmw_pair_f32(xo + row0 * DM + (col & ~1), xin + row0 * DM + (col & ~1), DM, col & 1, gv * a[0], gv * a[1], gv * a[2], gv * a[3]);
	v_mov_b64_e32 v[148:149], v[168:169]
	v_mov_b64_e32 v[150:151], v[170:171]
	v_mov_b32_e32 v137, v244
	v_mul_f32_e32 v137, 0.5, v137
	v_mul_f32_e32 v124, v124, v137
	v_mul_f32_e32 v163, v126, v137
	v_mul_f32_e32 v160, v125, v137
	v_mul_f32_e32 v127, v127, v137
	v_cndmask_b32_e64 v125, v124, v163, s[8:9]
	v_cndmask_b32_e64 v126, v160, v127, s[8:9]
	v_mul_f32_e32 v120, v120, v137
	v_mov_b32_dpp v125, v125 quad_perm:[1,0,3,2] row_mask:0xf bank_mask:0xf bound_ctrl:1
	v_mov_b32_dpp v161, v126 quad_perm:[1,0,3,2] row_mask:0xf bank_mask:0xf bound_ctrl:1
	v_mov_b32_e32 v162, v125
	v_mov_b32_e32 v126, v161
	v_mul_f32_e32 v123, v123, v137
	v_mul_f32_e32 v116, v116, v137
	v_pk_add_f32 v[164:165], v[124:125], v[148:149]
	v_pk_add_f32 v[124:125], v[148:149], v[162:163]
	v_pk_add_f32 v[166:167], v[160:161], v[150:151]
	v_pk_add_f32 v[126:127], v[150:151], v[126:127]
	v_cndmask_b32_e64 v125, v125, v165, s[8:9]
	v_cndmask_b32_e64 v124, v124, v164, s[8:9]
	v_cndmask_b32_e64 v127, v127, v167, s[8:9]
	v_cndmask_b32_e64 v126, v126, v166, s[8:9]
	global_store_dwordx2 v[152:153], v[124:125], off
	global_store_dwordx2 v[156:157], v[126:127], off
	v_mul_f32_e32 v163, v122, v137
	v_mul_f32_e32 v160, v121, v137
	v_cndmask_b32_e64 v121, v120, v163, s[8:9]
	v_lshl_add_u64 v[126:127], s[14:15], 0, v[146:147]
	v_cndmask_b32_e64 v122, v160, v123, s[8:9]
	v_mov_b32_dpp v121, v121 quad_perm:[1,0,3,2] row_mask:0xf bank_mask:0xf bound_ctrl:1
	v_or_b32_e32 v152, 0x20000, v142
	v_mov_b32_e32 v153, v143
	v_lshl_add_u64 v[146:147], v[126:127], 0, v[140:141]
	v_mov_b32_dpp v161, v122 quad_perm:[1,0,3,2] row_mask:0xf bank_mask:0xf bound_ctrl:1
	v_mov_b32_e32 v162, v121
	v_lshl_add_u64 v[124:125], s[12:13], 0, v[152:153]
	v_lshl_add_u64 v[146:147], v[146:147], 0, v[128:129]
	v_mov_b32_e32 v122, v161
	v_lshl_add_u64 v[154:155], v[124:125], 0, v[140:141]
	v_add_co_u32_e32 v156, vcc, s75, v146
	v_lshl_add_u64 v[154:155], v[154:155], 0, v[128:129]
	s_nop 0
	v_addc_co_u32_e32 v157, vcc, 0, v147, vcc
	v_add_co_u32_e32 v158, vcc, s75, v154
	v_mul_f32_e32 v119, v119, v137
	s_nop 0
	v_addc_co_u32_e32 v159, vcc, 0, v155, vcc
	v_or_b32_e32 v142, 0x30000, v142
	v_mul_f32_e32 v112, v112, v137
	v_mul_f32_e32 v115, v115, v137
	v_mul_f32_e32 v108, v108, v137
	v_mul_f32_e32 v111, v111, v137
	v_mul_f32_e32 v104, v104, v137
	v_mul_f32_e32 v107, v107, v137
	v_mul_f32_e32 v100, v100, v137
	v_mul_f32_e32 v103, v103, v137
	v_mul_f32_e32 v96, v96, v137
	v_mul_f32_e32 v99, v99, v137
	s_waitcnt vmcnt(30)
	v_mov_b64_e32 v[148:149], v[172:173]
	v_mov_b64_e32 v[150:151], v[174:175]
	v_pk_add_f32 v[120:121], v[120:121], v[148:149]
	v_pk_add_f32 v[148:149], v[148:149], v[162:163]
	v_pk_add_f32 v[160:161], v[160:161], v[150:151]
	v_pk_add_f32 v[122:123], v[150:151], v[122:123]
	v_cndmask_b32_e64 v121, v149, v121, s[8:9]
	v_cndmask_b32_e64 v120, v148, v120, s[8:9]
	v_cndmask_b32_e64 v123, v123, v161, s[8:9]
	v_cndmask_b32_e64 v122, v122, v160, s[8:9]
	global_store_dwordx2 v[146:147], v[120:121], off
	global_store_dwordx2 v[156:157], v[122:123], off
	v_mul_f32_e32 v161, v118, v137
	v_mul_f32_e32 v158, v117, v137
	v_cndmask_b32_e64 v117, v116, v161, s[8:9]
	v_lshl_add_u64 v[122:123], s[14:15], 0, v[152:153]
	v_cndmask_b32_e64 v118, v158, v119, s[8:9]
	v_mov_b32_dpp v117, v117 quad_perm:[1,0,3,2] row_mask:0xf bank_mask:0xf bound_ctrl:1
	v_lshl_add_u64 v[150:151], v[122:123], 0, v[140:141]
	v_mov_b32_dpp v159, v118 quad_perm:[1,0,3,2] row_mask:0xf bank_mask:0xf bound_ctrl:1
	v_mov_b32_e32 v160, v117
	v_lshl_add_u64 v[120:121], s[12:13], 0, v[142:143]
	v_lshl_add_u64 v[150:151], v[150:151], 0, v[128:129]
	v_mov_b32_e32 v118, v159
	v_lshl_add_u64 v[152:153], v[120:121], 0, v[140:141]
	v_add_co_u32_e32 v154, vcc, s75, v150
	v_lshl_add_u64 v[152:153], v[152:153], 0, v[128:129]
	s_nop 0
	v_addc_co_u32_e32 v155, vcc, 0, v151, vcc
	v_add_co_u32_e32 v156, vcc, s75, v152
	s_waitcnt vmcnt(30)
	v_mov_b64_e32 v[146:147], v[176:177]
	v_mov_b64_e32 v[148:149], v[178:179]
	v_pk_add_f32 v[116:117], v[116:117], v[146:147]
	v_pk_add_f32 v[146:147], v[146:147], v[160:161]
	v_pk_add_f32 v[158:159], v[158:159], v[148:149]
	v_pk_add_f32 v[118:119], v[148:149], v[118:119]
	v_cndmask_b32_e64 v117, v147, v117, s[8:9]
	v_cndmask_b32_e64 v116, v146, v116, s[8:9]
	v_cndmask_b32_e64 v119, v119, v159, s[8:9]
	v_cndmask_b32_e64 v118, v118, v158, s[8:9]
	global_store_dwordx2 v[150:151], v[116:117], off
	global_store_dwordx2 v[154:155], v[118:119], off
	v_addc_co_u32_e32 v157, vcc, 0, v153, vcc
	v_mul_f32_e32 v159, v114, v137
	v_mul_f32_e32 v156, v113, v137
	v_cndmask_b32_e64 v113, v112, v159, s[8:9]
	v_lshl_add_u64 v[116:117], s[14:15], 0, v[142:143]
	v_cndmask_b32_e64 v114, v156, v115, s[8:9]
	v_mov_b32_dpp v113, v113 quad_perm:[1,0,3,2] row_mask:0xf bank_mask:0xf bound_ctrl:1
	v_lshl_add_u64 v[142:143], v[116:117], 0, v[140:141]
	v_mov_b32_dpp v157, v114 quad_perm:[1,0,3,2] row_mask:0xf bank_mask:0xf bound_ctrl:1
	v_mov_b32_e32 v158, v113
	v_lshl_add_u64 v[118:119], v[132:133], 0, s[54:55]
	v_lshl_add_u64 v[142:143], v[142:143], 0, v[128:129]
	v_mov_b32_e32 v114, v157
	v_lshl_add_u64 v[150:151], v[118:119], 0, v[140:141]
	v_add_co_u32_e32 v152, vcc, s75, v142
	v_lshl_add_u64 v[150:151], v[150:151], 0, v[128:129]
	s_nop 0
	v_addc_co_u32_e32 v153, vcc, 0, v143, vcc
	v_add_co_u32_e32 v154, vcc, s75, v150
	s_waitcnt vmcnt(30)
; DI float dppx1(float v) { return __int_as_float(__builtin_amdgcn_update_dpp(0, __float_as_int(v), 0xB1, 0xF, 0xF, true)); }
; DI void rmw_pair_f32(float* xo_even, const float* xi_even, long ld, bool odd, float v0, float v1, float v2, float v3) {
;   const float sx = odd ? v0 : v2, sy = odd ? v1 : v3;
;   const float rx = dppx1(sx), ry = dppx1(sy);
;   const long off = odd ? 2 * ld : 0;
;   const float2 a0 = *(const float2*)(xi_even + off), a1 = *(const float2*)(xi_even + off + ld);
;   float2 o0, o1;
;   if (odd) { o0 = float2{a0.x + rx, a0.y + v2}; o1 = float2{a1.x + ry, a1.y + v3}; }
;   else     { o0 = float2{a0.x + v0, a0.y + rx}; o1 = float2{a1.x + v1, a1.y + ry}; }
;   *(float2*)(xo_even + off) = o0;
;   *(float2*)(xo_even + off + ld) = o1;
; }
; __global__ void __launch_bounds__(NTHR) fwd_kernel(Params pk) {
;     ...
;                 for (int m = 0; m < 4; ++m) {
;                   const long row0 = (long)pm * 256 + ai * 128 + wr * 64 + m * 16 + fq * 4;
;                   const f32x4 a = acc[ai][bj][m][n];
;                   rmw_pair_f32(xo + row0 * DM + (col & ~1), xin + row0 * DM + (col & ~1), DM, col & 1, gv * a[0], gv * a[1], gv * a[2], gv * a[3]);
	v_mov_b64_e32 v[146:147], v[180:181]
	v_mov_b64_e32 v[148:149], v[182:183]
	v_pk_add_f32 v[112:113], v[112:113], v[146:147]
	v_pk_add_f32 v[146:147], v[146:147], v[158:159]
	v_pk_add_f32 v[156:157], v[156:157], v[148:149]
	v_pk_add_f32 v[114:115], v[148:149], v[114:115]
	v_cndmask_b32_e64 v113, v147, v113, s[8:9]
	v_cndmask_b32_e64 v112, v146, v112, s[8:9]
	v_cndmask_b32_e64 v115, v115, v157, s[8:9]
	v_cndmask_b32_e64 v114, v114, v156, s[8:9]
	global_store_dwordx2 v[142:143], v[112:113], off
	global_store_dwordx2 v[152:153], v[114:115], off
	v_addc_co_u32_e32 v155, vcc, 0, v151, vcc
	v_mul_f32_e32 v159, v110, v137
	v_mul_f32_e32 v156, v109, v137
	v_cndmask_b32_e64 v109, v108, v159, s[8:9]
	v_lshl_add_u64 v[112:113], v[130:131], 0, s[54:55]
	v_cndmask_b32_e64 v110, v156, v111, s[8:9]
	v_mov_b32_dpp v109, v109 quad_perm:[1,0,3,2] row_mask:0xf bank_mask:0xf bound_ctrl:1
	v_lshl_add_u64 v[148:149], v[112:113], 0, v[140:141]
	v_mov_b32_dpp v157, v110 quad_perm:[1,0,3,2] row_mask:0xf bank_mask:0xf bound_ctrl:1
	v_mov_b32_e32 v158, v109
	v_lshl_add_u64 v[114:115], v[132:133], 0, s[56:57]
	v_lshl_add_u64 v[148:149], v[148:149], 0, v[128:129]
	v_mov_b32_e32 v110, v157
	v_lshl_add_u64 v[150:151], v[114:115], 0, v[140:141]
	v_add_co_u32_e32 v152, vcc, s75, v148
	v_lshl_add_u64 v[150:151], v[150:151], 0, v[128:129]
	s_nop 0
	v_addc_co_u32_e32 v153, vcc, 0, v149, vcc
	v_add_co_u32_e32 v154, vcc, s75, v150
	s_waitcnt vmcnt(30)
	v_mov_b64_e32 v[142:143], v[184:185]
	v_mov_b64_e32 v[146:147], v[186:187]
	v_pk_add_f32 v[108:109], v[108:109], v[142:143]
	v_pk_add_f32 v[142:143], v[142:143], v[158:159]
	v_pk_add_f32 v[156:157], v[156:157], v[146:147]
	v_pk_add_f32 v[110:111], v[146:147], v[110:111]
	v_cndmask_b32_e64 v109, v143, v109, s[8:9]
	v_cndmask_b32_e64 v108, v142, v108, s[8:9]
	v_cndmask_b32_e64 v111, v111, v157, s[8:9]
	v_cndmask_b32_e64 v110, v110, v156, s[8:9]
	global_store_dwordx2 v[148:149], v[108:109], off
	global_store_dwordx2 v[152:153], v[110:111], off
	v_addc_co_u32_e32 v155, vcc, 0, v151, vcc
	v_mul_f32_e32 v159, v106, v137
	v_mul_f32_e32 v156, v105, v137
	v_cndmask_b32_e64 v105, v104, v159, s[8:9]
	v_lshl_add_u64 v[108:109], v[130:131], 0, s[56:57]
	v_cndmask_b32_e64 v106, v156, v107, s[8:9]
	v_mov_b32_dpp v105, v105 quad_perm:[1,0,3,2] row_mask:0xf bank_mask:0xf bound_ctrl:1
	v_lshl_add_u64 v[148:149], v[108:109], 0, v[140:141]
	v_mov_b32_dpp v157, v106 quad_perm:[1,0,3,2] row_mask:0xf bank_mask:0xf bound_ctrl:1
	v_mov_b32_e32 v158, v105
	v_lshl_add_u64 v[110:111], v[132:133], 0, s[58:59]
	v_lshl_add_u64 v[148:149], v[148:149], 0, v[128:129]
	v_mov_b32_e32 v106, v157
	v_lshl_add_u64 v[150:151], v[110:111], 0, v[140:141]
	v_add_co_u32_e32 v152, vcc, s75, v148
	v_lshl_add_u64 v[150:151], v[150:151], 0, v[128:129]
	s_nop 0
	v_addc_co_u32_e32 v153, vcc, 0, v149, vcc
	v_add_co_u32_e32 v154, vcc, s75, v150
	s_waitcnt vmcnt(30)
	v_mov_b64_e32 v[142:143], v[188:189]
	v_mov_b64_e32 v[146:147], v[190:191]
	v_pk_add_f32 v[104:105], v[104:105], v[142:143]
	v_pk_add_f32 v[142:143], v[142:143], v[158:159]
	v_pk_add_f32 v[156:157], v[156:157], v[146:147]
	v_pk_add_f32 v[106:107], v[146:147], v[106:107]
	v_cndmask_b32_e64 v105, v143, v105, s[8:9]
	v_cndmask_b32_e64 v104, v142, v104, s[8:9]
	v_cndmask_b32_e64 v107, v107, v157, s[8:9]
	v_cndmask_b32_e64 v106, v106, v156, s[8:9]
	global_store_dwordx2 v[148:149], v[104:105], off
	global_store_dwordx2 v[152:153], v[106:107], off
	v_addc_co_u32_e32 v155, vcc, 0, v151, vcc
	v_mul_f32_e32 v159, v102, v137
	v_mul_f32_e32 v156, v101, v137
	v_cndmask_b32_e64 v101, v100, v159, s[8:9]
	v_lshl_add_u64 v[104:105], v[130:131], 0, s[58:59]
	v_cndmask_b32_e64 v102, v156, v103, s[8:9]
	v_mov_b32_dpp v101, v101 quad_perm:[1,0,3,2] row_mask:0xf bank_mask:0xf bound_ctrl:1
	v_lshl_add_u64 v[148:149], v[104:105], 0, v[140:141]
	v_mov_b32_dpp v157, v102 quad_perm:[1,0,3,2] row_mask:0xf bank_mask:0xf bound_ctrl:1
	v_mov_b32_e32 v158, v101
	v_lshl_add_u64 v[106:107], v[132:133], 0, s[22:23]
	v_lshl_add_u64 v[148:149], v[148:149], 0, v[128:129]
	v_mov_b32_e32 v102, v157
	v_lshl_add_u64 v[150:151], v[106:107], 0, v[140:141]
	v_add_co_u32_e32 v152, vcc, s75, v148
	v_lshl_add_u64 v[150:151], v[150:151], 0, v[128:129]
	s_nop 0
	v_addc_co_u32_e32 v153, vcc, 0, v149, vcc
	v_add_co_u32_e32 v154, vcc, s75, v150
	s_waitcnt vmcnt(30)
	v_mov_b64_e32 v[142:143], v[192:193]
	v_mov_b64_e32 v[146:147], v[196:197]
	v_pk_add_f32 v[100:101], v[100:101], v[142:143]
	v_pk_add_f32 v[142:143], v[142:143], v[158:159]
	v_pk_add_f32 v[156:157], v[156:157], v[146:147]
	v_pk_add_f32 v[102:103], v[146:147], v[102:103]
	v_cndmask_b32_e64 v101, v143, v101, s[8:9]
	v_cndmask_b32_e64 v100, v142, v100, s[8:9]
	v_cndmask_b32_e64 v103, v103, v157, s[8:9]
	v_cndmask_b32_e64 v102, v102, v156, s[8:9]
	global_store_dwordx2 v[148:149], v[100:101], off
	global_store_dwordx2 v[152:153], v[102:103], off
	v_addc_co_u32_e32 v155, vcc, 0, v151, vcc
	v_mul_f32_e32 v153, v98, v137
	v_mul_f32_e32 v150, v97, v137
	v_cndmask_b32_e64 v97, v96, v153, s[8:9]
	v_lshl_add_u64 v[100:101], v[130:131], 0, s[22:23]
	v_cndmask_b32_e64 v98, v150, v99, s[8:9]
	v_mov_b32_dpp v97, v97 quad_perm:[1,0,3,2] row_mask:0xf bank_mask:0xf bound_ctrl:1
	v_lshl_add_u64 v[140:141], v[100:101], 0, v[140:141]
	v_mov_b32_dpp v151, v98 quad_perm:[1,0,3,2] row_mask:0xf bank_mask:0xf bound_ctrl:1
	v_mov_b32_e32 v152, v97
	v_lshl_add_u64 v[140:141], v[140:141], 0, v[128:129]
	v_mov_b32_e32 v98, v151
	v_add_co_u32_e32 v148, vcc, s75, v140
	v_bitop3_b32 v146, v136, s80, 16 bitop3:0xc8
	s_nop 0
	v_addc_co_u32_e32 v149, vcc, 0, v141, vcc
	v_ashrrev_i32_e32 v147, 31, v146
	s_waitcnt vmcnt(30)
; DI float dppx1(float v) { return __int_as_float(__builtin_amdgcn_update_dpp(0, __float_as_int(v), 0xB1, 0xF, 0xF, true)); }
; DI void rmw_pair_f32(float* xo_even, const float* xi_even, long ld, bool odd, float v0, float v1, float v2, float v3) {
;   const float sx = odd ? v0 : v2, sy = odd ? v1 : v3;
;   const float rx = dppx1(sx), ry = dppx1(sy);
;   const long off = odd ? 2 * ld : 0;
;   const float2 a0 = *(const float2*)(xi_even + off), a1 = *(const float2*)(xi_even + off + ld);
;   float2 o0, o1;
;   if (odd) { o0 = float2{a0.x + rx, a0.y + v2}; o1 = float2{a1.x + ry, a1.y + v3}; }
;   else     { o0 = float2{a0.x + v0, a0.y + rx}; o1 = float2{a1.x + v1, a1.y + ry}; }
;   *(float2*)(xo_even + off) = o0;
;   *(float2*)(xo_even + off + ld) = o1;
; }
; __global__ void __launch_bounds__(NTHR) fwd_kernel(Params pk) {
;     ...
;                 for (int m = 0; m < 4; ++m) {
;                   const long row0 = (long)pm * 256 + ai * 128 + wr * 64 + m * 16 + fq * 4;
;                   const f32x4 a = acc[ai][bj][m][n];
;                   rmw_pair_f32(xo + row0 * DM + (col & ~1), xin + row0 * DM + (col & ~1), DM, col & 1, gv * a[0], gv * a[1], gv * a[2], gv * a[3]);
	v_mov_b64_e32 v[102:103], v[198:199]
	v_mov_b64_e32 v[142:143], v[200:201]
	v_pk_add_f32 v[96:97], v[96:97], v[102:103]
	v_pk_add_f32 v[102:103], v[102:103], v[152:153]
	v_pk_add_f32 v[150:151], v[150:151], v[142:143]
	v_pk_add_f32 v[98:99], v[142:143], v[98:99]
	v_cndmask_b32_e64 v97, v103, v97, s[8:9]
	v_cndmask_b32_e64 v96, v102, v96, s[8:9]
	v_cndmask_b32_e64 v99, v99, v151, s[8:9]
	v_cndmask_b32_e64 v98, v98, v150, s[8:9]
	global_store_dwordx2 v[140:141], v[96:97], off
	global_store_dwordx2 v[148:149], v[98:99], off
	v_lshlrev_b64 v[96:97], 2, v[146:147]
	v_lshl_add_u64 v[98:99], v[132:133], 0, v[96:97]
	v_lshl_add_u64 v[98:99], v[98:99], 0, v[128:129]
	v_add_co_u32_e32 v102, vcc, s75, v98
	s_nop 1
	v_addc_co_u32_e32 v103, vcc, 0, v99, vcc
	s_mov_b32 s98, 0x200
	s_mov_b32 s99, 0
	v_lshl_add_u64 v[250:251], v[248:249], 0, s[98:99]
	global_load_dwordx2 v[168:169], v[250:251], off
	s_mov_b32 s98, 0x1200
	s_mov_b32 s99, 0
	v_lshl_add_u64 v[250:251], v[248:249], 0, s[98:99]
	global_load_dwordx2 v[170:171], v[250:251], off
	s_mov_b32 s98, 0x10200
	s_mov_b32 s99, 0
	v_lshl_add_u64 v[250:251], v[248:249], 0, s[98:99]
	global_load_dwordx2 v[172:173], v[250:251], off
	s_mov_b32 s98, 0x11200
	s_mov_b32 s99, 0
	v_lshl_add_u64 v[250:251], v[248:249], 0, s[98:99]
	global_load_dwordx2 v[174:175], v[250:251], off
	s_mov_b32 s98, 0x20200
	s_mov_b32 s99, 0
	v_lshl_add_u64 v[250:251], v[248:249], 0, s[98:99]
	global_load_dwordx2 v[176:177], v[250:251], off
	s_mov_b32 s98, 0x21200
	s_mov_b32 s99, 0
	v_lshl_add_u64 v[250:251], v[248:249], 0, s[98:99]
	global_load_dwordx2 v[178:179], v[250:251], off
	s_mov_b32 s98, 0x30200
	s_mov_b32 s99, 0
	v_lshl_add_u64 v[250:251], v[248:249], 0, s[98:99]
	global_load_dwordx2 v[180:181], v[250:251], off
	s_mov_b32 s98, 0x31200
	s_mov_b32 s99, 0
	v_lshl_add_u64 v[250:251], v[248:249], 0, s[98:99]
	global_load_dwordx2 v[182:183], v[250:251], off
	s_mov_b32 s98, 0x80200
	s_mov_b32 s99, 0
	v_lshl_add_u64 v[250:251], v[248:249], 0, s[98:99]
	global_load_dwordx2 v[184:185], v[250:251], off
	s_mov_b32 s98, 0x81200
	s_mov_b32 s99, 0
	v_lshl_add_u64 v[250:251], v[248:249], 0, s[98:99]
	global_load_dwordx2 v[186:187], v[250:251], off
	s_mov_b32 s98, 0x90200
	s_mov_b32 s99, 0
	v_lshl_add_u64 v[250:251], v[248:249], 0, s[98:99]
	global_load_dwordx2 v[188:189], v[250:251], off
	s_mov_b32 s98, 0x91200
	s_mov_b32 s99, 0
	v_lshl_add_u64 v[250:251], v[248:249], 0, s[98:99]
	global_load_dwordx2 v[190:191], v[250:251], off
	s_mov_b32 s98, 0xa0200
	s_mov_b32 s99, 0
	v_lshl_add_u64 v[250:251], v[248:249], 0, s[98:99]
	global_load_dwordx2 v[192:193], v[250:251], off
	s_mov_b32 s98, 0xa1200
	s_mov_b32 s99, 0
	v_lshl_add_u64 v[250:251], v[248:249], 0, s[98:99]
	global_load_dwordx2 v[196:197], v[250:251], off
	s_mov_b32 s98, 0xb0200
	s_mov_b32 s99, 0
	v_lshl_add_u64 v[250:251], v[248:249], 0, s[98:99]
	global_load_dwordx2 v[198:199], v[250:251], off
	s_mov_b32 s98, 0xb1200
	s_mov_b32 s99, 0
	v_lshl_add_u64 v[250:251], v[248:249], 0, s[98:99]
	global_load_dwordx2 v[200:201], v[250:251], off
	s_nop 0
	v_lshl_add_u64 v[98:99], v[130:131], 0, v[96:97]
	v_lshl_add_u64 v[142:143], v[98:99], 0, v[128:129]
	v_lshl_add_u64 v[98:99], v[134:135], 0, v[96:97]
	v_lshl_add_u64 v[148:149], v[98:99], 0, v[128:129]
	v_add_co_u32_e32 v146, vcc, s75, v142
	s_waitcnt vmcnt(46)
	v_mov_b64_e32 v[140:141], v[202:203]
	v_mov_b64_e32 v[102:103], v[204:205]
	v_mov_b32_e32 v137, v245
	v_mul_f32_e32 v98, 0.5, v137
	v_mul_f32_e32 v92, v92, v98
	v_mul_f32_e32 v155, v94, v98
	v_mul_f32_e32 v152, v93, v98
	v_mul_f32_e32 v95, v95, v98
	v_cndmask_b32_e64 v93, v92, v155, s[8:9]
	v_cndmask_b32_e64 v94, v152, v95, s[8:9]
	v_addc_co_u32_e32 v147, vcc, 0, v143, vcc
	v_mov_b32_dpp v93, v93 quad_perm:[1,0,3,2] row_mask:0xf bank_mask:0xf bound_ctrl:1
	v_mov_b32_dpp v153, v94 quad_perm:[1,0,3,2] row_mask:0xf bank_mask:0xf bound_ctrl:1
	v_mov_b32_e32 v154, v93
	v_pk_add_f32 v[156:157], v[92:93], v[140:141]
	v_mov_b32_e32 v94, v153
	v_pk_add_f32 v[92:93], v[140:141], v[154:155]
	v_pk_add_f32 v[158:159], v[152:153], v[102:103]
	v_pk_add_f32 v[94:95], v[102:103], v[94:95]
	v_cndmask_b32_e64 v93, v93, v157, s[8:9]
	v_cndmask_b32_e64 v92, v92, v156, s[8:9]
	v_cndmask_b32_e64 v95, v95, v159, s[8:9]
	v_cndmask_b32_e64 v94, v94, v158, s[8:9]
	global_store_dwordx2 v[142:143], v[92:93], off
	global_store_dwordx2 v[146:147], v[94:95], off
	v_add_co_u32_e32 v150, vcc, s75, v148
	v_mul_f32_e32 v88, v88, v98
	s_nop 0
	v_addc_co_u32_e32 v151, vcc, 0, v149, vcc
	v_mul_f32_e32 v151, v90, v98
	v_mul_f32_e32 v148, v89, v98
	v_mul_f32_e32 v91, v91, v98
	v_cndmask_b32_e64 v89, v88, v151, s[8:9]
	v_cndmask_b32_e64 v90, v148, v91, s[8:9]
	v_lshl_add_u64 v[102:103], v[126:127], 0, v[96:97]
	v_mov_b32_dpp v89, v89 quad_perm:[1,0,3,2] row_mask:0xf bank_mask:0xf bound_ctrl:1
	v_mov_b32_dpp v149, v90 quad_perm:[1,0,3,2] row_mask:0xf bank_mask:0xf bound_ctrl:1
	v_mov_b32_e32 v150, v89
	v_lshl_add_u64 v[102:103], v[102:103], 0, v[128:129]
	v_mov_b32_e32 v90, v149
	v_lshl_add_u64 v[140:141], v[124:125], 0, v[96:97]
	v_add_co_u32_e32 v142, vcc, s75, v102
	v_lshl_add_u64 v[140:141], v[140:141], 0, v[128:129]
	s_nop 0
	v_addc_co_u32_e32 v143, vcc, 0, v103, vcc
	v_add_co_u32_e32 v146, vcc, s75, v140
	v_mul_f32_e32 v84, v84, v98
	s_nop 0
	v_addc_co_u32_e32 v147, vcc, 0, v141, vcc
	v_mul_f32_e32 v87, v87, v98
	v_mul_f32_e32 v80, v80, v98
	v_mul_f32_e32 v83, v83, v98
	v_mul_f32_e32 v76, v76, v98
	v_mul_f32_e32 v79, v79, v98
	v_mul_f32_e32 v72, v72, v98
	v_mul_f32_e32 v75, v75, v98
	v_mul_f32_e32 v68, v68, v98
	v_mul_f32_e32 v71, v71, v98
	v_mul_f32_e32 v64, v64, v98
	v_mul_f32_e32 v67, v67, v98
	s_waitcnt vmcnt(46)
; DI float dppx1(float v) { return __int_as_float(__builtin_amdgcn_update_dpp(0, __float_as_int(v), 0xB1, 0xF, 0xF, true)); }
; DI void rmw_pair_f32(float* xo_even, const float* xi_even, long ld, bool odd, float v0, float v1, float v2, float v3) {
;   const float sx = odd ? v0 : v2, sy = odd ? v1 : v3;
;   const float rx = dppx1(sx), ry = dppx1(sy);
;   const long off = odd ? 2 * ld : 0;
;   const float2 a0 = *(const float2*)(xi_even + off), a1 = *(const float2*)(xi_even + off + ld);
;   float2 o0, o1;
;   if (odd) { o0 = float2{a0.x + rx, a0.y + v2}; o1 = float2{a1.x + ry, a1.y + v3}; }
;   else     { o0 = float2{a0.x + v0, a0.y + rx}; o1 = float2{a1.x + v1, a1.y + ry}; }
;   *(float2*)(xo_even + off) = o0;
;   *(float2*)(xo_even + off + ld) = o1;
; }
; __global__ void __launch_bounds__(NTHR) fwd_kernel(Params pk) {
;     ...
;                 for (int m = 0; m < 4; ++m) {
;                   const long row0 = (long)pm * 256 + ai * 128 + wr * 64 + m * 16 + fq * 4;
;                   const f32x4 a = acc[ai][bj][m][n];
;                   rmw_pair_f32(xo + row0 * DM + (col & ~1), xin + row0 * DM + (col & ~1), DM, col & 1, gv * a[0], gv * a[1], gv * a[2], gv * a[3]);
	v_mov_b64_e32 v[92:93], v[206:207]
	v_mov_b64_e32 v[94:95], v[208:209]
	v_pk_add_f32 v[88:89], v[88:89], v[92:93]
	v_pk_add_f32 v[92:93], v[92:93], v[150:151]
	v_pk_add_f32 v[148:149], v[148:149], v[94:95]
	v_pk_add_f32 v[90:91], v[94:95], v[90:91]
	v_cndmask_b32_e64 v89, v93, v89, s[8:9]
	v_cndmask_b32_e64 v88, v92, v88, s[8:9]
	v_cndmask_b32_e64 v91, v91, v149, s[8:9]
	v_cndmask_b32_e64 v90, v90, v148, s[8:9]
	global_store_dwordx2 v[102:103], v[88:89], off
	global_store_dwordx2 v[142:143], v[90:91], off
	v_mul_f32_e32 v147, v86, v98
	v_mul_f32_e32 v142, v85, v98
	v_cndmask_b32_e64 v85, v84, v147, s[8:9]
	v_cndmask_b32_e64 v86, v142, v87, s[8:9]
	v_lshl_add_u64 v[92:93], v[122:123], 0, v[96:97]
	v_mov_b32_dpp v85, v85 quad_perm:[1,0,3,2] row_mask:0xf bank_mask:0xf bound_ctrl:1
	v_mov_b32_dpp v143, v86 quad_perm:[1,0,3,2] row_mask:0xf bank_mask:0xf bound_ctrl:1
	v_mov_b32_e32 v146, v85
	v_lshl_add_u64 v[92:93], v[92:93], 0, v[128:129]
	v_mov_b32_e32 v86, v143
	v_lshl_add_u64 v[94:95], v[120:121], 0, v[96:97]
	v_add_co_u32_e32 v102, vcc, s75, v92
	v_lshl_add_u64 v[94:95], v[94:95], 0, v[128:129]
	s_nop 0
	v_addc_co_u32_e32 v103, vcc, 0, v93, vcc
	v_add_co_u32_e32 v140, vcc, s75, v94
	s_waitcnt vmcnt(46)
	v_mov_b64_e32 v[88:89], v[210:211]
	v_mov_b64_e32 v[90:91], v[212:213]
	v_pk_add_f32 v[84:85], v[84:85], v[88:89]
	v_pk_add_f32 v[88:89], v[88:89], v[146:147]
	v_pk_add_f32 v[142:143], v[142:143], v[90:91]
	v_pk_add_f32 v[86:87], v[90:91], v[86:87]
	v_cndmask_b32_e64 v85, v89, v85, s[8:9]
	v_cndmask_b32_e64 v84, v88, v84, s[8:9]
	v_cndmask_b32_e64 v87, v87, v143, s[8:9]
	v_cndmask_b32_e64 v86, v86, v142, s[8:9]
	global_store_dwordx2 v[92:93], v[84:85], off
	global_store_dwordx2 v[102:103], v[86:87], off
	v_addc_co_u32_e32 v141, vcc, 0, v95, vcc
	v_mul_f32_e32 v141, v82, v98
	v_mul_f32_e32 v102, v81, v98
	v_cndmask_b32_e64 v81, v80, v141, s[8:9]
	v_cndmask_b32_e64 v82, v102, v83, s[8:9]
	v_lshl_add_u64 v[88:89], v[116:117], 0, v[96:97]
	v_mov_b32_dpp v81, v81 quad_perm:[1,0,3,2] row_mask:0xf bank_mask:0xf bound_ctrl:1
	v_mov_b32_dpp v103, v82 quad_perm:[1,0,3,2] row_mask:0xf bank_mask:0xf bound_ctrl:1
	v_mov_b32_e32 v140, v81
	v_lshl_add_u64 v[88:89], v[88:89], 0, v[128:129]
	v_mov_b32_e32 v82, v103
	v_lshl_add_u64 v[90:91], v[118:119], 0, v[96:97]
	v_add_co_u32_e32 v92, vcc, s75, v88
	v_lshl_add_u64 v[90:91], v[90:91], 0, v[128:129]
	s_nop 0
	v_addc_co_u32_e32 v93, vcc, 0, v89, vcc
	v_add_co_u32_e32 v94, vcc, s75, v90
	s_waitcnt vmcnt(46)
	v_mov_b64_e32 v[84:85], v[214:215]
	v_mov_b64_e32 v[86:87], v[216:217]
	v_pk_add_f32 v[80:81], v[80:81], v[84:85]
	v_pk_add_f32 v[84:85], v[84:85], v[140:141]
	v_pk_add_f32 v[102:103], v[102:103], v[86:87]
	v_pk_add_f32 v[82:83], v[86:87], v[82:83]
	v_cndmask_b32_e64 v81, v85, v81, s[8:9]
	v_cndmask_b32_e64 v80, v84, v80, s[8:9]
	v_cndmask_b32_e64 v83, v83, v103, s[8:9]
	v_cndmask_b32_e64 v82, v82, v102, s[8:9]
	global_store_dwordx2 v[88:89], v[80:81], off
	global_store_dwordx2 v[92:93], v[82:83], off
	v_addc_co_u32_e32 v95, vcc, 0, v91, vcc
	v_mul_f32_e32 v95, v78, v98
	v_mul_f32_e32 v92, v77, v98
	v_cndmask_b32_e64 v77, v76, v95, s[8:9]
	v_cndmask_b32_e64 v78, v92, v79, s[8:9]
	v_lshl_add_u64 v[84:85], v[112:113], 0, v[96:97]
	v_mov_b32_dpp v77, v77 quad_perm:[1,0,3,2] row_mask:0xf bank_mask:0xf bound_ctrl:1
	v_mov_b32_dpp v93, v78 quad_perm:[1,0,3,2] row_mask:0xf bank_mask:0xf bound_ctrl:1
	v_mov_b32_e32 v94, v77
	v_lshl_add_u64 v[84:85], v[84:85], 0, v[128:129]
	v_mov_b32_e32 v78, v93
	v_lshl_add_u64 v[86:87], v[114:115], 0, v[96:97]
	v_add_co_u32_e32 v88, vcc, s75, v84
	v_lshl_add_u64 v[86:87], v[86:87], 0, v[128:129]
	s_nop 0
	v_addc_co_u32_e32 v89, vcc, 0, v85, vcc
	v_add_co_u32_e32 v90, vcc, s75, v86
	s_waitcnt vmcnt(46)
	v_mov_b64_e32 v[80:81], v[218:219]
	v_mov_b64_e32 v[82:83], v[220:221]
	v_pk_add_f32 v[76:77], v[76:77], v[80:81]
	v_pk_add_f32 v[80:81], v[80:81], v[94:95]
	v_pk_add_f32 v[92:93], v[92:93], v[82:83]
	v_pk_add_f32 v[78:79], v[82:83], v[78:79]
	v_cndmask_b32_e64 v77, v81, v77, s[8:9]
	v_cndmask_b32_e64 v76, v80, v76, s[8:9]
	v_cndmask_b32_e64 v79, v79, v93, s[8:9]
	v_cndmask_b32_e64 v78, v78, v92, s[8:9]
	global_store_dwordx2 v[84:85], v[76:77], off
	global_store_dwordx2 v[88:89], v[78:79], off
	v_addc_co_u32_e32 v91, vcc, 0, v87, vcc
	v_mul_f32_e32 v91, v74, v98
	v_mul_f32_e32 v88, v73, v98
	v_cndmask_b32_e64 v73, v72, v91, s[8:9]
	v_cndmask_b32_e64 v74, v88, v75, s[8:9]
	v_lshl_add_u64 v[80:81], v[108:109], 0, v[96:97]
	v_mov_b32_dpp v73, v73 quad_perm:[1,0,3,2] row_mask:0xf bank_mask:0xf bound_ctrl:1
	v_mov_b32_dpp v89, v74 quad_perm:[1,0,3,2] row_mask:0xf bank_mask:0xf bound_ctrl:1
	v_mov_b32_e32 v90, v73
	v_lshl_add_u64 v[80:81], v[80:81], 0, v[128:129]
	v_mov_b32_e32 v74, v89
	v_lshl_add_u64 v[82:83], v[110:111], 0, v[96:97]
	v_add_co_u32_e32 v84, vcc, s75, v80
	v_lshl_add_u64 v[82:83], v[82:83], 0, v[128:129]
	s_nop 0
	v_addc_co_u32_e32 v85, vcc, 0, v81, vcc
	v_add_co_u32_e32 v86, vcc, s75, v82
	s_waitcnt vmcnt(46)
	v_mov_b64_e32 v[76:77], v[222:223]
	v_mov_b64_e32 v[78:79], v[224:225]
	v_pk_add_f32 v[72:73], v[72:73], v[76:77]
	v_pk_add_f32 v[76:77], v[76:77], v[90:91]
	v_pk_add_f32 v[88:89], v[88:89], v[78:79]
	v_pk_add_f32 v[74:75], v[78:79], v[74:75]
	v_cndmask_b32_e64 v73, v77, v73, s[8:9]
	v_cndmask_b32_e64 v72, v76, v72, s[8:9]
	v_cndmask_b32_e64 v75, v75, v89, s[8:9]
	v_cndmask_b32_e64 v74, v74, v88, s[8:9]
	global_store_dwordx2 v[80:81], v[72:73], off
	global_store_dwordx2 v[84:85], v[74:75], off
	v_addc_co_u32_e32 v87, vcc, 0, v83, vcc
	v_mul_f32_e32 v87, v70, v98
	v_mul_f32_e32 v84, v69, v98
	v_cndmask_b32_e64 v69, v68, v87, s[8:9]
	v_cndmask_b32_e64 v70, v84, v71, s[8:9]
	v_lshl_add_u64 v[76:77], v[104:105], 0, v[96:97]
	v_mov_b32_dpp v69, v69 quad_perm:[1,0,3,2] row_mask:0xf bank_mask:0xf bound_ctrl:1
	v_mov_b32_dpp v85, v70 quad_perm:[1,0,3,2] row_mask:0xf bank_mask:0xf bound_ctrl:1
	v_mov_b32_e32 v86, v69
	v_lshl_add_u64 v[76:77], v[76:77], 0, v[128:129]
	v_mov_b32_e32 v70, v85
	v_lshl_add_u64 v[78:79], v[106:107], 0, v[96:97]
	v_add_co_u32_e32 v80, vcc, s75, v76
	v_lshl_add_u64 v[78:79], v[78:79], 0, v[128:129]
	s_nop 0
	v_addc_co_u32_e32 v81, vcc, 0, v77, vcc
	v_add_co_u32_e32 v82, vcc, s75, v78
	s_waitcnt vmcnt(46)
; DI float dppx1(float v) { return __int_as_float(__builtin_amdgcn_update_dpp(0, __float_as_int(v), 0xB1, 0xF, 0xF, true)); }
; DI void rmw_pair_f32(float* xo_even, const float* xi_even, long ld, bool odd, float v0, float v1, float v2, float v3) {
;   const float sx = odd ? v0 : v2, sy = odd ? v1 : v3;
;   const float rx = dppx1(sx), ry = dppx1(sy);
;   const long off = odd ? 2 * ld : 0;
;   const float2 a0 = *(const float2*)(xi_even + off), a1 = *(const float2*)(xi_even + off + ld);
;   float2 o0, o1;
;   if (odd) { o0 = float2{a0.x + rx, a0.y + v2}; o1 = float2{a1.x + ry, a1.y + v3}; }
;   else     { o0 = float2{a0.x + v0, a0.y + rx}; o1 = float2{a1.x + v1, a1.y + ry}; }
;   *(float2*)(xo_even + off) = o0;
;   *(float2*)(xo_even + off + ld) = o1;
; }
; __global__ void __launch_bounds__(NTHR) fwd_kernel(Params pk) {
;     ...
;                 for (int m = 0; m < 4; ++m) {
;                   const long row0 = (long)pm * 256 + ai * 128 + wr * 64 + m * 16 + fq * 4;
;                   const f32x4 a = acc[ai][bj][m][n];
;                   rmw_pair_f32(xo + row0 * DM + (col & ~1), xin + row0 * DM + (col & ~1), DM, col & 1, gv * a[0], gv * a[1], gv * a[2], gv * a[3]);
	v_mov_b64_e32 v[72:73], v[226:227]
	v_mov_b64_e32 v[74:75], v[228:229]
	v_pk_add_f32 v[68:69], v[68:69], v[72:73]
	v_pk_add_f32 v[72:73], v[72:73], v[86:87]
	v_pk_add_f32 v[84:85], v[84:85], v[74:75]
	v_pk_add_f32 v[70:71], v[74:75], v[70:71]
	v_cndmask_b32_e64 v69, v73, v69, s[8:9]
	v_cndmask_b32_e64 v68, v72, v68, s[8:9]
	v_cndmask_b32_e64 v71, v71, v85, s[8:9]
	v_cndmask_b32_e64 v70, v70, v84, s[8:9]
	global_store_dwordx2 v[76:77], v[68:69], off
	global_store_dwordx2 v[80:81], v[70:71], off
	v_addc_co_u32_e32 v83, vcc, 0, v79, vcc
	v_mul_f32_e32 v81, v66, v98
	v_mul_f32_e32 v78, v65, v98
	v_cndmask_b32_e64 v65, v64, v81, s[8:9]
	v_cndmask_b32_e64 v66, v78, v67, s[8:9]
	v_lshl_add_u64 v[74:75], v[100:101], 0, v[96:97]
	v_mov_b32_dpp v65, v65 quad_perm:[1,0,3,2] row_mask:0xf bank_mask:0xf bound_ctrl:1
	v_mov_b32_dpp v79, v66 quad_perm:[1,0,3,2] row_mask:0xf bank_mask:0xf bound_ctrl:1
	v_mov_b32_e32 v80, v65
	v_lshl_add_u64 v[74:75], v[74:75], 0, v[128:129]
	v_mov_b32_e32 v66, v79
	v_add_co_u32_e32 v76, vcc, s75, v74
	v_bitop3_b32 v72, v136, s81, v144 bitop3:0xc8
	s_nop 0
	v_addc_co_u32_e32 v77, vcc, 0, v75, vcc
	v_ashrrev_i32_e32 v73, 31, v72
	s_waitcnt vmcnt(46)
	v_mov_b64_e32 v[68:69], v[230:231]
	v_mov_b64_e32 v[70:71], v[232:233]
	v_pk_add_f32 v[64:65], v[64:65], v[68:69]
	v_pk_add_f32 v[68:69], v[68:69], v[80:81]
	v_pk_add_f32 v[78:79], v[78:79], v[70:71]
	v_pk_add_f32 v[66:67], v[70:71], v[66:67]
	v_cndmask_b32_e64 v65, v69, v65, s[8:9]
	v_cndmask_b32_e64 v64, v68, v64, s[8:9]
	v_cndmask_b32_e64 v67, v67, v79, s[8:9]
	v_cndmask_b32_e64 v66, v66, v78, s[8:9]
	global_store_dwordx2 v[74:75], v[64:65], off
	global_store_dwordx2 v[76:77], v[66:67], off
	v_lshlrev_b64 v[64:65], 2, v[72:73]
	v_lshl_add_u64 v[66:67], v[132:133], 0, v[64:65]
	v_lshl_add_u64 v[66:67], v[66:67], 0, v[128:129]
	v_add_co_u32_e32 v68, vcc, s75, v66
	s_nop 1
	v_addc_co_u32_e32 v69, vcc, 0, v67, vcc
	s_mov_b32 s98, 0x240
	s_mov_b32 s99, 0
	v_lshl_add_u64 v[250:251], v[248:249], 0, s[98:99]
	global_load_dwordx2 v[202:203], v[250:251], off
	s_mov_b32 s98, 0x1240
	s_mov_b32 s99, 0
	v_lshl_add_u64 v[250:251], v[248:249], 0, s[98:99]
	global_load_dwordx2 v[204:205], v[250:251], off
	s_mov_b32 s98, 0x10240
	s_mov_b32 s99, 0
	v_lshl_add_u64 v[250:251], v[248:249], 0, s[98:99]
	global_load_dwordx2 v[206:207], v[250:251], off
	s_mov_b32 s98, 0x11240
	s_mov_b32 s99, 0
	v_lshl_add_u64 v[250:251], v[248:249], 0, s[98:99]
	global_load_dwordx2 v[208:209], v[250:251], off
	s_mov_b32 s98, 0x20240
	s_mov_b32 s99, 0
	v_lshl_add_u64 v[250:251], v[248:249], 0, s[98:99]
	global_load_dwordx2 v[210:211], v[250:251], off
	s_mov_b32 s98, 0x21240
	s_mov_b32 s99, 0
	v_lshl_add_u64 v[250:251], v[248:249], 0, s[98:99]
	global_load_dwordx2 v[212:213], v[250:251], off
	s_mov_b32 s98, 0x30240
	s_mov_b32 s99, 0
	v_lshl_add_u64 v[250:251], v[248:249], 0, s[98:99]
	global_load_dwordx2 v[214:215], v[250:251], off
	s_mov_b32 s98, 0x31240
	s_mov_b32 s99, 0
	v_lshl_add_u64 v[250:251], v[248:249], 0, s[98:99]
	global_load_dwordx2 v[216:217], v[250:251], off
	s_mov_b32 s98, 0x80240
	s_mov_b32 s99, 0
	v_lshl_add_u64 v[250:251], v[248:249], 0, s[98:99]
	global_load_dwordx2 v[218:219], v[250:251], off
	s_mov_b32 s98, 0x81240
	s_mov_b32 s99, 0
	v_lshl_add_u64 v[250:251], v[248:249], 0, s[98:99]
	global_load_dwordx2 v[220:221], v[250:251], off
	s_mov_b32 s98, 0x90240
	s_mov_b32 s99, 0
	v_lshl_add_u64 v[250:251], v[248:249], 0, s[98:99]
	global_load_dwordx2 v[222:223], v[250:251], off
	s_mov_b32 s98, 0x91240
	s_mov_b32 s99, 0
	v_lshl_add_u64 v[250:251], v[248:249], 0, s[98:99]
	global_load_dwordx2 v[224:225], v[250:251], off
	s_mov_b32 s98, 0xa0240
	s_mov_b32 s99, 0
	v_lshl_add_u64 v[250:251], v[248:249], 0, s[98:99]
	global_load_dwordx2 v[226:227], v[250:251], off
	s_mov_b32 s98, 0xa1240
	s_mov_b32 s99, 0
	v_lshl_add_u64 v[250:251], v[248:249], 0, s[98:99]
	global_load_dwordx2 v[228:229], v[250:251], off
	s_mov_b32 s98, 0xb0240
	s_mov_b32 s99, 0
	v_lshl_add_u64 v[250:251], v[248:249], 0, s[98:99]
	global_load_dwordx2 v[230:231], v[250:251], off
	s_mov_b32 s98, 0xb1240
	s_mov_b32 s99, 0
	v_lshl_add_u64 v[250:251], v[248:249], 0, s[98:99]
	global_load_dwordx2 v[232:233], v[250:251], off
	s_nop 0
	v_lshl_add_u64 v[66:67], v[130:131], 0, v[64:65]
	v_lshl_add_u64 v[72:73], v[66:67], 0, v[128:129]
	v_lshl_add_u64 v[66:67], v[134:135], 0, v[64:65]
	v_lshl_add_u64 v[76:77], v[66:67], 0, v[128:129]
	v_add_co_u32_e32 v74, vcc, s75, v72
	s_waitcnt vmcnt(46)
	v_mov_b64_e32 v[70:71], v[168:169]
	v_mov_b64_e32 v[68:69], v[170:171]
	v_mov_b32_e32 v80, v246
	v_mul_f32_e32 v66, 0.5, v80
	v_mul_f32_e32 v60, v60, v66
	v_mul_f32_e32 v83, v62, v66
	v_mul_f32_e32 v80, v61, v66
	v_mul_f32_e32 v63, v63, v66
	v_cndmask_b32_e64 v61, v60, v83, s[8:9]
	v_cndmask_b32_e64 v62, v80, v63, s[8:9]
	v_addc_co_u32_e32 v75, vcc, 0, v73, vcc
	v_mov_b32_dpp v61, v61 quad_perm:[1,0,3,2] row_mask:0xf bank_mask:0xf bound_ctrl:1
	v_mov_b32_dpp v81, v62 quad_perm:[1,0,3,2] row_mask:0xf bank_mask:0xf bound_ctrl:1
	v_mov_b32_e32 v82, v61
	v_pk_add_f32 v[84:85], v[60:61], v[70:71]
	v_mov_b32_e32 v62, v81
	v_pk_add_f32 v[60:61], v[70:71], v[82:83]
	v_pk_add_f32 v[86:87], v[80:81], v[68:69]
	v_pk_add_f32 v[62:63], v[68:69], v[62:63]
	v_cndmask_b32_e64 v61, v61, v85, s[8:9]
	v_cndmask_b32_e64 v60, v60, v84, s[8:9]
	v_cndmask_b32_e64 v63, v63, v87, s[8:9]
	v_cndmask_b32_e64 v62, v62, v86, s[8:9]
	global_store_dwordx2 v[72:73], v[60:61], off
	global_store_dwordx2 v[74:75], v[62:63], off
	v_add_co_u32_e32 v78, vcc, s75, v76
	v_mul_f32_e32 v56, v56, v66
	s_nop 0
	v_addc_co_u32_e32 v79, vcc, 0, v77, vcc
	v_mul_f32_e32 v79, v58, v66
	v_mul_f32_e32 v76, v57, v66
	v_mul_f32_e32 v59, v59, v66
	v_cndmask_b32_e64 v57, v56, v79, s[8:9]
	v_cndmask_b32_e64 v58, v76, v59, s[8:9]
	v_lshl_add_u64 v[68:69], v[126:127], 0, v[64:65]
	v_mov_b32_dpp v57, v57 quad_perm:[1,0,3,2] row_mask:0xf bank_mask:0xf bound_ctrl:1
	v_mov_b32_dpp v77, v58 quad_perm:[1,0,3,2] row_mask:0xf bank_mask:0xf bound_ctrl:1
	v_mov_b32_e32 v78, v57
	v_lshl_add_u64 v[68:69], v[68:69], 0, v[128:129]
	v_mov_b32_e32 v58, v77
	v_lshl_add_u64 v[70:71], v[124:125], 0, v[64:65]
	v_add_co_u32_e32 v72, vcc, s75, v68
	v_lshl_add_u64 v[70:71], v[70:71], 0, v[128:129]
	s_nop 0
	v_addc_co_u32_e32 v73, vcc, 0, v69, vcc
	v_add_co_u32_e32 v74, vcc, s75, v70
	v_mul_f32_e32 v52, v52, v66
	s_nop 0
	v_addc_co_u32_e32 v75, vcc, 0, v71, vcc
	v_mul_f32_e32 v55, v55, v66
	v_mul_f32_e32 v48, v48, v66
	v_mul_f32_e32 v51, v51, v66
	v_mul_f32_e32 v44, v44, v66
	v_mul_f32_e32 v47, v47, v66
	v_mul_f32_e32 v40, v40, v66
	v_mul_f32_e32 v43, v43, v66
	v_mul_f32_e32 v36, v36, v66
	v_mul_f32_e32 v39, v39, v66
	v_mul_f32_e32 v32, v32, v66
	v_mul_f32_e32 v35, v35, v66
	s_waitcnt vmcnt(46)
; DI float dppx1(float v) { return __int_as_float(__builtin_amdgcn_update_dpp(0, __float_as_int(v), 0xB1, 0xF, 0xF, true)); }
; DI void rmw_pair_f32(float* xo_even, const float* xi_even, long ld, bool odd, float v0, float v1, float v2, float v3) {
;   const float sx = odd ? v0 : v2, sy = odd ? v1 : v3;
;   const float rx = dppx1(sx), ry = dppx1(sy);
;   const long off = odd ? 2 * ld : 0;
;   const float2 a0 = *(const float2*)(xi_even + off), a1 = *(const float2*)(xi_even + off + ld);
;   float2 o0, o1;
;   if (odd) { o0 = float2{a0.x + rx, a0.y + v2}; o1 = float2{a1.x + ry, a1.y + v3}; }
;   else     { o0 = float2{a0.x + v0, a0.y + rx}; o1 = float2{a1.x + v1, a1.y + ry}; }
;   *(float2*)(xo_even + off) = o0;
;   *(float2*)(xo_even + off + ld) = o1;
; }
; __global__ void __launch_bounds__(NTHR) fwd_kernel(Params pk) {
;     ...
;                 for (int m = 0; m < 4; ++m) {
;                   const long row0 = (long)pm * 256 + ai * 128 + wr * 64 + m * 16 + fq * 4;
;                   const f32x4 a = acc[ai][bj][m][n];
;                   rmw_pair_f32(xo + row0 * DM + (col & ~1), xin + row0 * DM + (col & ~1), DM, col & 1, gv * a[0], gv * a[1], gv * a[2], gv * a[3]);
	v_mov_b64_e32 v[60:61], v[172:173]
	v_mov_b64_e32 v[62:63], v[174:175]
	v_pk_add_f32 v[56:57], v[56:57], v[60:61]
	v_pk_add_f32 v[60:61], v[60:61], v[78:79]
	v_pk_add_f32 v[76:77], v[76:77], v[62:63]
	v_pk_add_f32 v[58:59], v[62:63], v[58:59]
	v_cndmask_b32_e64 v57, v61, v57, s[8:9]
	v_cndmask_b32_e64 v56, v60, v56, s[8:9]
	v_cndmask_b32_e64 v59, v59, v77, s[8:9]
	v_cndmask_b32_e64 v58, v58, v76, s[8:9]
	global_store_dwordx2 v[68:69], v[56:57], off
	global_store_dwordx2 v[72:73], v[58:59], off
	v_mul_f32_e32 v75, v54, v66
	v_mul_f32_e32 v72, v53, v66
	v_cndmask_b32_e64 v53, v52, v75, s[8:9]
	v_cndmask_b32_e64 v54, v72, v55, s[8:9]
	v_lshl_add_u64 v[60:61], v[122:123], 0, v[64:65]
	v_mov_b32_dpp v53, v53 quad_perm:[1,0,3,2] row_mask:0xf bank_mask:0xf bound_ctrl:1
	v_mov_b32_dpp v73, v54 quad_perm:[1,0,3,2] row_mask:0xf bank_mask:0xf bound_ctrl:1
	v_mov_b32_e32 v74, v53
	v_lshl_add_u64 v[60:61], v[60:61], 0, v[128:129]
	v_mov_b32_e32 v54, v73
	v_lshl_add_u64 v[62:63], v[120:121], 0, v[64:65]
	v_add_co_u32_e32 v68, vcc, s75, v60
	v_lshl_add_u64 v[62:63], v[62:63], 0, v[128:129]
	s_nop 0
	v_addc_co_u32_e32 v69, vcc, 0, v61, vcc
	v_add_co_u32_e32 v70, vcc, s75, v62
	s_waitcnt vmcnt(46)
	v_mov_b64_e32 v[56:57], v[176:177]
	v_mov_b64_e32 v[58:59], v[178:179]
	v_pk_add_f32 v[52:53], v[52:53], v[56:57]
	v_pk_add_f32 v[56:57], v[56:57], v[74:75]
	v_pk_add_f32 v[72:73], v[72:73], v[58:59]
	v_pk_add_f32 v[54:55], v[58:59], v[54:55]
	v_cndmask_b32_e64 v53, v57, v53, s[8:9]
	v_cndmask_b32_e64 v52, v56, v52, s[8:9]
	v_cndmask_b32_e64 v55, v55, v73, s[8:9]
	v_cndmask_b32_e64 v54, v54, v72, s[8:9]
	global_store_dwordx2 v[60:61], v[52:53], off
	global_store_dwordx2 v[68:69], v[54:55], off
	v_addc_co_u32_e32 v71, vcc, 0, v63, vcc
	v_mul_f32_e32 v71, v50, v66
	v_mul_f32_e32 v68, v49, v66
	v_cndmask_b32_e64 v49, v48, v71, s[8:9]
	v_cndmask_b32_e64 v50, v68, v51, s[8:9]
	v_lshl_add_u64 v[56:57], v[116:117], 0, v[64:65]
	v_mov_b32_dpp v49, v49 quad_perm:[1,0,3,2] row_mask:0xf bank_mask:0xf bound_ctrl:1
	v_mov_b32_dpp v69, v50 quad_perm:[1,0,3,2] row_mask:0xf bank_mask:0xf bound_ctrl:1
	v_mov_b32_e32 v70, v49
	v_lshl_add_u64 v[56:57], v[56:57], 0, v[128:129]
	v_mov_b32_e32 v50, v69
	v_lshl_add_u64 v[58:59], v[118:119], 0, v[64:65]
	v_add_co_u32_e32 v60, vcc, s75, v56
	v_lshl_add_u64 v[58:59], v[58:59], 0, v[128:129]
	s_nop 0
	v_addc_co_u32_e32 v61, vcc, 0, v57, vcc
	v_add_co_u32_e32 v62, vcc, s75, v58
	s_waitcnt vmcnt(46)
	v_mov_b64_e32 v[52:53], v[180:181]
	v_mov_b64_e32 v[54:55], v[182:183]
	v_pk_add_f32 v[48:49], v[48:49], v[52:53]
	v_pk_add_f32 v[52:53], v[52:53], v[70:71]
	v_pk_add_f32 v[68:69], v[68:69], v[54:55]
	v_pk_add_f32 v[50:51], v[54:55], v[50:51]
	v_cndmask_b32_e64 v49, v53, v49, s[8:9]
	v_cndmask_b32_e64 v48, v52, v48, s[8:9]
	v_cndmask_b32_e64 v51, v51, v69, s[8:9]
	v_cndmask_b32_e64 v50, v50, v68, s[8:9]
	global_store_dwordx2 v[56:57], v[48:49], off
	global_store_dwordx2 v[60:61], v[50:51], off
	v_addc_co_u32_e32 v63, vcc, 0, v59, vcc
	v_mul_f32_e32 v63, v46, v66
	v_mul_f32_e32 v60, v45, v66
	v_cndmask_b32_e64 v45, v44, v63, s[8:9]
	v_cndmask_b32_e64 v46, v60, v47, s[8:9]
	v_lshl_add_u64 v[52:53], v[112:113], 0, v[64:65]
	v_mov_b32_dpp v45, v45 quad_perm:[1,0,3,2] row_mask:0xf bank_mask:0xf bound_ctrl:1
	v_mov_b32_dpp v61, v46 quad_perm:[1,0,3,2] row_mask:0xf bank_mask:0xf bound_ctrl:1
	v_mov_b32_e32 v62, v45
	v_lshl_add_u64 v[52:53], v[52:53], 0, v[128:129]
	v_mov_b32_e32 v46, v61
	v_lshl_add_u64 v[54:55], v[114:115], 0, v[64:65]
	v_add_co_u32_e32 v56, vcc, s75, v52
	v_lshl_add_u64 v[54:55], v[54:55], 0, v[128:129]
	s_nop 0
	v_addc_co_u32_e32 v57, vcc, 0, v53, vcc
	v_add_co_u32_e32 v58, vcc, s75, v54
	s_waitcnt vmcnt(46)
	v_mov_b64_e32 v[48:49], v[184:185]
	v_mov_b64_e32 v[50:51], v[186:187]
	v_pk_add_f32 v[44:45], v[44:45], v[48:49]
	v_pk_add_f32 v[48:49], v[48:49], v[62:63]
	v_pk_add_f32 v[60:61], v[60:61], v[50:51]
	v_pk_add_f32 v[46:47], v[50:51], v[46:47]
	v_cndmask_b32_e64 v45, v49, v45, s[8:9]
	v_cndmask_b32_e64 v44, v48, v44, s[8:9]
	v_cndmask_b32_e64 v47, v47, v61, s[8:9]
	v_cndmask_b32_e64 v46, v46, v60, s[8:9]
	global_store_dwordx2 v[52:53], v[44:45], off
	global_store_dwordx2 v[56:57], v[46:47], off
	v_addc_co_u32_e32 v59, vcc, 0, v55, vcc
	v_mul_f32_e32 v59, v42, v66
	v_mul_f32_e32 v56, v41, v66
	v_cndmask_b32_e64 v41, v40, v59, s[8:9]
	v_cndmask_b32_e64 v42, v56, v43, s[8:9]
	v_lshl_add_u64 v[48:49], v[108:109], 0, v[64:65]
	v_mov_b32_dpp v41, v41 quad_perm:[1,0,3,2] row_mask:0xf bank_mask:0xf bound_ctrl:1
	v_mov_b32_dpp v57, v42 quad_perm:[1,0,3,2] row_mask:0xf bank_mask:0xf bound_ctrl:1
	v_mov_b32_e32 v58, v41
	v_lshl_add_u64 v[48:49], v[48:49], 0, v[128:129]
	v_mov_b32_e32 v42, v57
	v_lshl_add_u64 v[50:51], v[110:111], 0, v[64:65]
	v_add_co_u32_e32 v52, vcc, s75, v48
	v_lshl_add_u64 v[50:51], v[50:51], 0, v[128:129]
	s_nop 0
	v_addc_co_u32_e32 v53, vcc, 0, v49, vcc
	v_add_co_u32_e32 v54, vcc, s75, v50
	s_waitcnt vmcnt(46)
	v_mov_b64_e32 v[44:45], v[188:189]
	v_mov_b64_e32 v[46:47], v[190:191]
	v_pk_add_f32 v[40:41], v[40:41], v[44:45]
	v_pk_add_f32 v[44:45], v[44:45], v[58:59]
	v_pk_add_f32 v[56:57], v[56:57], v[46:47]
	v_pk_add_f32 v[42:43], v[46:47], v[42:43]
	v_cndmask_b32_e64 v41, v45, v41, s[8:9]
	v_cndmask_b32_e64 v40, v44, v40, s[8:9]
	v_cndmask_b32_e64 v43, v43, v57, s[8:9]
	v_cndmask_b32_e64 v42, v42, v56, s[8:9]
	global_store_dwordx2 v[48:49], v[40:41], off
	global_store_dwordx2 v[52:53], v[42:43], off
	v_addc_co_u32_e32 v55, vcc, 0, v51, vcc
	v_mul_f32_e32 v55, v38, v66
	v_mul_f32_e32 v52, v37, v66
	v_cndmask_b32_e64 v37, v36, v55, s[8:9]
	v_cndmask_b32_e64 v38, v52, v39, s[8:9]
	v_lshl_add_u64 v[44:45], v[104:105], 0, v[64:65]
	v_mov_b32_dpp v37, v37 quad_perm:[1,0,3,2] row_mask:0xf bank_mask:0xf bound_ctrl:1
	v_mov_b32_dpp v53, v38 quad_perm:[1,0,3,2] row_mask:0xf bank_mask:0xf bound_ctrl:1
	v_mov_b32_e32 v54, v37
	v_lshl_add_u64 v[44:45], v[44:45], 0, v[128:129]
	v_mov_b32_e32 v38, v53
	v_lshl_add_u64 v[46:47], v[106:107], 0, v[64:65]
	v_add_co_u32_e32 v48, vcc, s75, v44
	v_lshl_add_u64 v[46:47], v[46:47], 0, v[128:129]
	s_nop 0
	v_addc_co_u32_e32 v49, vcc, 0, v45, vcc
	v_add_co_u32_e32 v50, vcc, s75, v46
	s_waitcnt vmcnt(46)
; DI float dppx1(float v) { return __int_as_float(__builtin_amdgcn_update_dpp(0, __float_as_int(v), 0xB1, 0xF, 0xF, true)); }
; DI void rmw_pair_f32(float* xo_even, const float* xi_even, long ld, bool odd, float v0, float v1, float v2, float v3) {
;   const float sx = odd ? v0 : v2, sy = odd ? v1 : v3;
;   const float rx = dppx1(sx), ry = dppx1(sy);
;   const long off = odd ? 2 * ld : 0;
;   const float2 a0 = *(const float2*)(xi_even + off), a1 = *(const float2*)(xi_even + off + ld);
;   float2 o0, o1;
;   if (odd) { o0 = float2{a0.x + rx, a0.y + v2}; o1 = float2{a1.x + ry, a1.y + v3}; }
;   else     { o0 = float2{a0.x + v0, a0.y + rx}; o1 = float2{a1.x + v1, a1.y + ry}; }
;   *(float2*)(xo_even + off) = o0;
;   *(float2*)(xo_even + off + ld) = o1;
; }
; __global__ void __launch_bounds__(NTHR) fwd_kernel(Params pk) {
;     ...
;                 for (int m = 0; m < 4; ++m) {
;                   const long row0 = (long)pm * 256 + ai * 128 + wr * 64 + m * 16 + fq * 4;
;                   const f32x4 a = acc[ai][bj][m][n];
;                   rmw_pair_f32(xo + row0 * DM + (col & ~1), xin + row0 * DM + (col & ~1), DM, col & 1, gv * a[0], gv * a[1], gv * a[2], gv * a[3]);
	v_mov_b64_e32 v[40:41], v[192:193]
	v_mov_b64_e32 v[42:43], v[196:197]
	v_pk_add_f32 v[36:37], v[36:37], v[40:41]
	v_pk_add_f32 v[40:41], v[40:41], v[54:55]
	v_pk_add_f32 v[52:53], v[52:53], v[42:43]
	v_pk_add_f32 v[38:39], v[42:43], v[38:39]
	v_cndmask_b32_e64 v37, v41, v37, s[8:9]
	v_cndmask_b32_e64 v36, v40, v36, s[8:9]
	v_cndmask_b32_e64 v39, v39, v53, s[8:9]
	v_cndmask_b32_e64 v38, v38, v52, s[8:9]
	global_store_dwordx2 v[44:45], v[36:37], off
	global_store_dwordx2 v[48:49], v[38:39], off
	v_addc_co_u32_e32 v51, vcc, 0, v47, vcc
	v_mul_f32_e32 v49, v34, v66
	v_mul_f32_e32 v46, v33, v66
	v_cndmask_b32_e64 v33, v32, v49, s[8:9]
	v_cndmask_b32_e64 v34, v46, v35, s[8:9]
	v_lshl_add_u64 v[42:43], v[100:101], 0, v[64:65]
	v_mov_b32_dpp v33, v33 quad_perm:[1,0,3,2] row_mask:0xf bank_mask:0xf bound_ctrl:1
	v_mov_b32_dpp v47, v34 quad_perm:[1,0,3,2] row_mask:0xf bank_mask:0xf bound_ctrl:1
	v_mov_b32_e32 v48, v33
	v_lshl_add_u64 v[42:43], v[42:43], 0, v[128:129]
	v_mov_b32_e32 v34, v47
	v_add_co_u32_e32 v44, vcc, s75, v42
	v_bitop3_b32 v40, v136, -2, v145 bitop3:0xc8
	s_nop 0
	v_addc_co_u32_e32 v45, vcc, 0, v43, vcc
	v_ashrrev_i32_e32 v41, 31, v40
	s_waitcnt vmcnt(46)
	v_mov_b64_e32 v[36:37], v[198:199]
	v_mov_b64_e32 v[38:39], v[200:201]
	v_pk_add_f32 v[32:33], v[32:33], v[36:37]
	v_pk_add_f32 v[36:37], v[36:37], v[48:49]
	v_pk_add_f32 v[46:47], v[46:47], v[38:39]
	v_pk_add_f32 v[34:35], v[38:39], v[34:35]
	v_cndmask_b32_e64 v33, v37, v33, s[8:9]
	v_cndmask_b32_e64 v32, v36, v32, s[8:9]
	v_cndmask_b32_e64 v35, v35, v47, s[8:9]
	v_cndmask_b32_e64 v34, v34, v46, s[8:9]
	global_store_dwordx2 v[42:43], v[32:33], off
	global_store_dwordx2 v[44:45], v[34:35], off
	v_lshlrev_b64 v[32:33], 2, v[40:41]
	v_lshl_add_u64 v[34:35], v[132:133], 0, v[32:33]
	v_lshl_add_u64 v[34:35], v[34:35], 0, v[128:129]
	v_add_co_u32_e32 v36, vcc, s75, v34
	s_nop 1
	v_addc_co_u32_e32 v37, vcc, 0, v35, vcc
	s_nop 0
	v_lshl_add_u64 v[34:35], v[130:131], 0, v[32:33]
	v_lshl_add_u64 v[40:41], v[34:35], 0, v[128:129]
	v_lshl_add_u64 v[34:35], v[134:135], 0, v[32:33]
	v_lshl_add_u64 v[44:45], v[34:35], 0, v[128:129]
	v_add_co_u32_e32 v42, vcc, s75, v40
	s_waitcnt vmcnt(30)
	v_mov_b64_e32 v[38:39], v[202:203]
	v_mov_b64_e32 v[36:37], v[204:205]
	v_mov_b32_e32 v48, v247
	v_mul_f32_e32 v34, 0.5, v48
	v_mul_f32_e32 v28, v28, v34
	v_mul_f32_e32 v51, v30, v34
	v_mul_f32_e32 v48, v29, v34
	v_mul_f32_e32 v31, v31, v34
	v_cndmask_b32_e64 v29, v28, v51, s[8:9]
	v_cndmask_b32_e64 v30, v48, v31, s[8:9]
	v_addc_co_u32_e32 v43, vcc, 0, v41, vcc
	v_mov_b32_dpp v29, v29 quad_perm:[1,0,3,2] row_mask:0xf bank_mask:0xf bound_ctrl:1
	v_mov_b32_dpp v49, v30 quad_perm:[1,0,3,2] row_mask:0xf bank_mask:0xf bound_ctrl:1
	v_mov_b32_e32 v50, v29
	v_pk_add_f32 v[52:53], v[28:29], v[38:39]
	v_mov_b32_e32 v30, v49
	v_pk_add_f32 v[28:29], v[38:39], v[50:51]
	v_pk_add_f32 v[54:55], v[48:49], v[36:37]
	v_pk_add_f32 v[30:31], v[36:37], v[30:31]
	v_cndmask_b32_e64 v29, v29, v53, s[8:9]
	v_cndmask_b32_e64 v28, v28, v52, s[8:9]
	v_cndmask_b32_e64 v31, v31, v55, s[8:9]
	v_cndmask_b32_e64 v30, v30, v54, s[8:9]
	global_store_dwordx2 v[40:41], v[28:29], off
	global_store_dwordx2 v[42:43], v[30:31], off
	v_add_co_u32_e32 v46, vcc, s75, v44
	v_mul_f32_e32 v24, v24, v34
	s_nop 0
	v_addc_co_u32_e32 v47, vcc, 0, v45, vcc
	v_mul_f32_e32 v47, v26, v34
	v_mul_f32_e32 v44, v25, v34
	v_mul_f32_e32 v27, v27, v34
	v_cndmask_b32_e64 v25, v24, v47, s[8:9]
	v_cndmask_b32_e64 v26, v44, v27, s[8:9]
	v_lshl_add_u64 v[36:37], v[126:127], 0, v[32:33]
	v_mov_b32_dpp v25, v25 quad_perm:[1,0,3,2] row_mask:0xf bank_mask:0xf bound_ctrl:1
	v_mov_b32_dpp v45, v26 quad_perm:[1,0,3,2] row_mask:0xf bank_mask:0xf bound_ctrl:1
	v_mov_b32_e32 v46, v25
	v_lshl_add_u64 v[36:37], v[36:37], 0, v[128:129]
	v_mov_b32_e32 v26, v45
	v_lshl_add_u64 v[38:39], v[124:125], 0, v[32:33]
	v_add_co_u32_e32 v40, vcc, s75, v36
	v_lshl_add_u64 v[38:39], v[38:39], 0, v[128:129]
	s_nop 0
	v_addc_co_u32_e32 v41, vcc, 0, v37, vcc
	v_add_co_u32_e32 v42, vcc, s75, v38
	v_mul_f32_e32 v20, v20, v34
	s_nop 0
	v_addc_co_u32_e32 v43, vcc, 0, v39, vcc
	v_mul_f32_e32 v23, v23, v34
	v_mul_f32_e32 v16, v16, v34
	v_mul_f32_e32 v19, v19, v34
	v_mul_f32_e32 v12, v12, v34
	v_mul_f32_e32 v15, v15, v34
	v_mul_f32_e32 v8, v8, v34
	v_mul_f32_e32 v11, v11, v34
	v_mul_f32_e32 v4, v4, v34
	v_mul_f32_e32 v7, v7, v34
	v_mul_f32_e32 v0, v0, v34
	v_mul_f32_e32 v3, v3, v34
	s_waitcnt vmcnt(30)
	v_mov_b64_e32 v[28:29], v[206:207]
	v_mov_b64_e32 v[30:31], v[208:209]
	v_pk_add_f32 v[24:25], v[24:25], v[28:29]
	v_pk_add_f32 v[28:29], v[28:29], v[46:47]
	v_pk_add_f32 v[44:45], v[44:45], v[30:31]
	v_pk_add_f32 v[26:27], v[30:31], v[26:27]
	v_cndmask_b32_e64 v25, v29, v25, s[8:9]
	v_cndmask_b32_e64 v24, v28, v24, s[8:9]
	v_cndmask_b32_e64 v27, v27, v45, s[8:9]
	v_cndmask_b32_e64 v26, v26, v44, s[8:9]
	global_store_dwordx2 v[36:37], v[24:25], off
	global_store_dwordx2 v[40:41], v[26:27], off
	v_mul_f32_e32 v43, v22, v34
	v_mul_f32_e32 v40, v21, v34
	v_cndmask_b32_e64 v21, v20, v43, s[8:9]
	v_cndmask_b32_e64 v22, v40, v23, s[8:9]
	v_lshl_add_u64 v[28:29], v[122:123], 0, v[32:33]
	v_mov_b32_dpp v21, v21 quad_perm:[1,0,3,2] row_mask:0xf bank_mask:0xf bound_ctrl:1
	v_mov_b32_dpp v41, v22 quad_perm:[1,0,3,2] row_mask:0xf bank_mask:0xf bound_ctrl:1
	v_mov_b32_e32 v42, v21
	v_lshl_add_u64 v[28:29], v[28:29], 0, v[128:129]
	v_mov_b32_e32 v22, v41
	v_lshl_add_u64 v[30:31], v[120:121], 0, v[32:33]
	v_add_co_u32_e32 v36, vcc, s75, v28
	v_lshl_add_u64 v[30:31], v[30:31], 0, v[128:129]
	s_nop 0
	v_addc_co_u32_e32 v37, vcc, 0, v29, vcc
	v_add_co_u32_e32 v38, vcc, s75, v30
	s_waitcnt vmcnt(30)
; DI float dppx1(float v) { return __int_as_float(__builtin_amdgcn_update_dpp(0, __float_as_int(v), 0xB1, 0xF, 0xF, true)); }
; DI void rmw_pair_f32(float* xo_even, const float* xi_even, long ld, bool odd, float v0, float v1, float v2, float v3) {
;   const float sx = odd ? v0 : v2, sy = odd ? v1 : v3;
;   const float rx = dppx1(sx), ry = dppx1(sy);
;   const long off = odd ? 2 * ld : 0;
;   const float2 a0 = *(const float2*)(xi_even + off), a1 = *(const float2*)(xi_even + off + ld);
;   float2 o0, o1;
;   if (odd) { o0 = float2{a0.x + rx, a0.y + v2}; o1 = float2{a1.x + ry, a1.y + v3}; }
;   else     { o0 = float2{a0.x + v0, a0.y + rx}; o1 = float2{a1.x + v1, a1.y + ry}; }
;   *(float2*)(xo_even + off) = o0;
;   *(float2*)(xo_even + off + ld) = o1;
; }
; template <class Epi>
; DI void gemm_tile(int ws, char* shmc, const TileDesc& td, Epi& epi, int pm, int pn, bool first, bool has_next, const TileDesc& tdn) {
;     ...
;   asm volatile("s_waitcnt vmcnt(0)" ::: "memory");
;   __syncthreads();
; __global__ void __launch_bounds__(NTHR) fwd_kernel(Params pk) {
;     ...
;                 for (int m = 0; m < 4; ++m) {
;                   const long row0 = (long)pm * 256 + ai * 128 + wr * 64 + m * 16 + fq * 4;
;                   const f32x4 a = acc[ai][bj][m][n];
;                   rmw_pair_f32(xo + row0 * DM + (col & ~1), xin + row0 * DM + (col & ~1), DM, col & 1, gv * a[0], gv * a[1], gv * a[2], gv * a[3]);
	v_mov_b64_e32 v[24:25], v[210:211]
	v_mov_b64_e32 v[26:27], v[212:213]
	v_pk_add_f32 v[20:21], v[20:21], v[24:25]
	v_pk_add_f32 v[24:25], v[24:25], v[42:43]
	v_pk_add_f32 v[40:41], v[40:41], v[26:27]
	v_pk_add_f32 v[22:23], v[26:27], v[22:23]
	v_cndmask_b32_e64 v21, v25, v21, s[8:9]
	v_cndmask_b32_e64 v20, v24, v20, s[8:9]
	v_cndmask_b32_e64 v23, v23, v41, s[8:9]
	v_cndmask_b32_e64 v22, v22, v40, s[8:9]
	global_store_dwordx2 v[28:29], v[20:21], off
	global_store_dwordx2 v[36:37], v[22:23], off
	v_addc_co_u32_e32 v39, vcc, 0, v31, vcc
	v_mul_f32_e32 v39, v18, v34
	v_mul_f32_e32 v36, v17, v34
	v_cndmask_b32_e64 v17, v16, v39, s[8:9]
	v_cndmask_b32_e64 v18, v36, v19, s[8:9]
	v_lshl_add_u64 v[24:25], v[116:117], 0, v[32:33]
	v_mov_b32_dpp v17, v17 quad_perm:[1,0,3,2] row_mask:0xf bank_mask:0xf bound_ctrl:1
	v_mov_b32_dpp v37, v18 quad_perm:[1,0,3,2] row_mask:0xf bank_mask:0xf bound_ctrl:1
	v_mov_b32_e32 v38, v17
	v_lshl_add_u64 v[24:25], v[24:25], 0, v[128:129]
	v_mov_b32_e32 v18, v37
	v_lshl_add_u64 v[26:27], v[118:119], 0, v[32:33]
	v_add_co_u32_e32 v28, vcc, s75, v24
	v_lshl_add_u64 v[26:27], v[26:27], 0, v[128:129]
	s_nop 0
	v_addc_co_u32_e32 v29, vcc, 0, v25, vcc
	v_add_co_u32_e32 v30, vcc, s75, v26
	s_waitcnt vmcnt(30)
	v_mov_b64_e32 v[20:21], v[214:215]
	v_mov_b64_e32 v[22:23], v[216:217]
	v_pk_add_f32 v[16:17], v[16:17], v[20:21]
	v_pk_add_f32 v[20:21], v[20:21], v[38:39]
	v_pk_add_f32 v[36:37], v[36:37], v[22:23]
	v_pk_add_f32 v[18:19], v[22:23], v[18:19]
	v_cndmask_b32_e64 v17, v21, v17, s[8:9]
	v_cndmask_b32_e64 v16, v20, v16, s[8:9]
	v_cndmask_b32_e64 v19, v19, v37, s[8:9]
	v_cndmask_b32_e64 v18, v18, v36, s[8:9]
	global_store_dwordx2 v[24:25], v[16:17], off
	global_store_dwordx2 v[28:29], v[18:19], off
	v_addc_co_u32_e32 v31, vcc, 0, v27, vcc
	v_mul_f32_e32 v31, v14, v34
	v_mul_f32_e32 v28, v13, v34
	v_cndmask_b32_e64 v13, v12, v31, s[8:9]
	v_cndmask_b32_e64 v14, v28, v15, s[8:9]
	v_lshl_add_u64 v[20:21], v[112:113], 0, v[32:33]
	v_mov_b32_dpp v13, v13 quad_perm:[1,0,3,2] row_mask:0xf bank_mask:0xf bound_ctrl:1
	v_mov_b32_dpp v29, v14 quad_perm:[1,0,3,2] row_mask:0xf bank_mask:0xf bound_ctrl:1
	v_mov_b32_e32 v30, v13
	v_lshl_add_u64 v[20:21], v[20:21], 0, v[128:129]
	v_mov_b32_e32 v14, v29
	v_lshl_add_u64 v[22:23], v[114:115], 0, v[32:33]
	v_add_co_u32_e32 v24, vcc, s75, v20
	v_lshl_add_u64 v[22:23], v[22:23], 0, v[128:129]
	s_nop 0
	v_addc_co_u32_e32 v25, vcc, 0, v21, vcc
	v_add_co_u32_e32 v26, vcc, s75, v22
	s_waitcnt vmcnt(30)
	v_mov_b64_e32 v[16:17], v[218:219]
	v_mov_b64_e32 v[18:19], v[220:221]
	v_pk_add_f32 v[12:13], v[12:13], v[16:17]
	v_pk_add_f32 v[16:17], v[16:17], v[30:31]
	v_pk_add_f32 v[28:29], v[28:29], v[18:19]
	v_pk_add_f32 v[14:15], v[18:19], v[14:15]
	v_cndmask_b32_e64 v13, v17, v13, s[8:9]
	v_cndmask_b32_e64 v12, v16, v12, s[8:9]
	v_cndmask_b32_e64 v15, v15, v29, s[8:9]
	v_cndmask_b32_e64 v14, v14, v28, s[8:9]
	global_store_dwordx2 v[20:21], v[12:13], off
	global_store_dwordx2 v[24:25], v[14:15], off
	v_addc_co_u32_e32 v27, vcc, 0, v23, vcc
	v_mul_f32_e32 v27, v10, v34
	v_mul_f32_e32 v24, v9, v34
	v_cndmask_b32_e64 v9, v8, v27, s[8:9]
	v_cndmask_b32_e64 v10, v24, v11, s[8:9]
	v_lshl_add_u64 v[16:17], v[108:109], 0, v[32:33]
	v_mov_b32_dpp v9, v9 quad_perm:[1,0,3,2] row_mask:0xf bank_mask:0xf bound_ctrl:1
	v_mov_b32_dpp v25, v10 quad_perm:[1,0,3,2] row_mask:0xf bank_mask:0xf bound_ctrl:1
	v_mov_b32_e32 v26, v9
	v_lshl_add_u64 v[16:17], v[16:17], 0, v[128:129]
	v_mov_b32_e32 v10, v25
	v_lshl_add_u64 v[18:19], v[110:111], 0, v[32:33]
	v_add_co_u32_e32 v20, vcc, s75, v16
	v_lshl_add_u64 v[18:19], v[18:19], 0, v[128:129]
	s_nop 0
	v_addc_co_u32_e32 v21, vcc, 0, v17, vcc
	v_add_co_u32_e32 v22, vcc, s75, v18
	s_waitcnt vmcnt(30)
	v_mov_b64_e32 v[12:13], v[222:223]
	v_mov_b64_e32 v[14:15], v[224:225]
	v_pk_add_f32 v[8:9], v[8:9], v[12:13]
	v_pk_add_f32 v[12:13], v[12:13], v[26:27]
	v_pk_add_f32 v[24:25], v[24:25], v[14:15]
	v_pk_add_f32 v[10:11], v[14:15], v[10:11]
	v_cndmask_b32_e64 v9, v13, v9, s[8:9]
	v_cndmask_b32_e64 v8, v12, v8, s[8:9]
	v_cndmask_b32_e64 v11, v11, v25, s[8:9]
	v_cndmask_b32_e64 v10, v10, v24, s[8:9]
	global_store_dwordx2 v[16:17], v[8:9], off
	global_store_dwordx2 v[20:21], v[10:11], off
	v_addc_co_u32_e32 v23, vcc, 0, v19, vcc
	v_mul_f32_e32 v23, v6, v34
	v_mul_f32_e32 v20, v5, v34
	v_cndmask_b32_e64 v5, v4, v23, s[8:9]
	v_cndmask_b32_e64 v6, v20, v7, s[8:9]
	v_lshl_add_u64 v[12:13], v[104:105], 0, v[32:33]
	v_mov_b32_dpp v5, v5 quad_perm:[1,0,3,2] row_mask:0xf bank_mask:0xf bound_ctrl:1
	v_mov_b32_dpp v21, v6 quad_perm:[1,0,3,2] row_mask:0xf bank_mask:0xf bound_ctrl:1
	v_mov_b32_e32 v22, v5
	v_lshl_add_u64 v[12:13], v[12:13], 0, v[128:129]
	v_mov_b32_e32 v6, v21
	v_lshl_add_u64 v[14:15], v[106:107], 0, v[32:33]
	v_add_co_u32_e32 v16, vcc, s75, v12
	v_lshl_add_u64 v[14:15], v[14:15], 0, v[128:129]
	s_nop 0
	v_addc_co_u32_e32 v17, vcc, 0, v13, vcc
	v_add_co_u32_e32 v18, vcc, s75, v14
	s_waitcnt vmcnt(30)
	v_mov_b64_e32 v[8:9], v[226:227]
	v_mov_b64_e32 v[10:11], v[228:229]
	v_pk_add_f32 v[4:5], v[4:5], v[8:9]
	v_pk_add_f32 v[8:9], v[8:9], v[22:23]
	v_pk_add_f32 v[20:21], v[20:21], v[10:11]
	v_pk_add_f32 v[6:7], v[10:11], v[6:7]
	v_cndmask_b32_e64 v5, v9, v5, s[8:9]
	v_cndmask_b32_e64 v4, v8, v4, s[8:9]
	v_cndmask_b32_e64 v7, v7, v21, s[8:9]
	v_cndmask_b32_e64 v6, v6, v20, s[8:9]
	global_store_dwordx2 v[12:13], v[4:5], off
	global_store_dwordx2 v[16:17], v[6:7], off
	v_addc_co_u32_e32 v19, vcc, 0, v15, vcc
	v_mul_f32_e32 v15, v2, v34
	v_mul_f32_e32 v12, v1, v34
	v_cndmask_b32_e64 v1, v0, v15, s[8:9]
	v_cndmask_b32_e64 v2, v12, v3, s[8:9]
	v_lshl_add_u64 v[8:9], v[100:101], 0, v[32:33]
	v_mov_b32_dpp v1, v1 quad_perm:[1,0,3,2] row_mask:0xf bank_mask:0xf bound_ctrl:1
	v_mov_b32_dpp v13, v2 quad_perm:[1,0,3,2] row_mask:0xf bank_mask:0xf bound_ctrl:1
	v_mov_b32_e32 v14, v1
	v_lshl_add_u64 v[8:9], v[8:9], 0, v[128:129]
	v_mov_b32_e32 v2, v13
	v_add_co_u32_e32 v10, vcc, 0x1000, v8
	s_waitcnt vmcnt(30)
	v_mov_b64_e32 v[4:5], v[230:231]
	v_mov_b64_e32 v[6:7], v[232:233]
	v_pk_add_f32 v[0:1], v[0:1], v[4:5]
	v_pk_add_f32 v[4:5], v[4:5], v[14:15]
	v_pk_add_f32 v[12:13], v[12:13], v[6:7]
	v_pk_add_f32 v[2:3], v[6:7], v[2:3]
	v_cndmask_b32_e64 v1, v5, v1, s[8:9]
	v_cndmask_b32_e64 v0, v4, v0, s[8:9]
	v_addc_co_u32_e32 v11, vcc, 0, v9, vcc
	v_cndmask_b32_e64 v3, v3, v13, s[8:9]
	v_cndmask_b32_e64 v2, v2, v12, s[8:9]
	global_store_dwordx2 v[8:9], v[0:1], off
	global_store_dwordx2 v[10:11], v[2:3], off
	s_waitcnt vmcnt(0)
	s_andn2_b64 vcc, exec, s[64:65]
	s_mov_b32 s8, s82
	s_waitcnt lgkmcnt(0)
	s_barrier
	s_cbranch_vccz .LBB0_222

; DI float dppx1(float v) { return __int_as_float(__builtin_amdgcn_update_dpp(0, __float_as_int(v), 0xB1, 0xF, 0xF, true)); }
; DI void rmw_pair_f32(float* xo_even, const float* xi_even, long ld, bool odd, float v0, float v1, float v2, float v3) {
;   const float sx = odd ? v0 : v2, sy = odd ? v1 : v3;
;   const float rx = dppx1(sx), ry = dppx1(sy);
;   const long off = odd ? 2 * ld : 0;
;   const float2 a0 = *(const float2*)(xi_even + off), a1 = *(const float2*)(xi_even + off + ld);
;   float2 o0, o1;
;   if (odd) { o0 = float2{a0.x + rx, a0.y + v2}; o1 = float2{a1.x + ry, a1.y + v3}; }
;   else     { o0 = float2{a0.x + v0, a0.y + rx}; o1 = float2{a1.x + v1, a1.y + ry}; }
;   *(float2*)(xo_even + off) = o0;
;   *(float2*)(xo_even + off + ld) = o1;
; }
; __global__ void __launch_bounds__(NTHR) fwd_kernel(Params pk) {
;     ...
;             const int b = (pm * 256) >> 13;
; #pragma unroll
;             for (int bj = 0; bj < 2; ++bj)
; #pragma unroll
;               for (int n = 0; n < 2; ++n) {
;                 const int col = pn * 256 + bj * 128 + wc * 32 + n * 16 + fr;
;                 const float gv = gate[(long)b * 9216 + col];
; #pragma unroll
;                 for (int ai = 0; ai < 2; ++ai)
; #pragma unroll
;                   for (int m = 0; m < 4; ++m) {
;                     const long row0 = (long)pm * 256 + ai * 128 + wr * 64 + m * 16 + fq * 4;
;                     const f32x4 a = acc[ai][bj][m][n];
;                     rmw_pair_f32(xo + row0 * DM + (col & ~1), xo + row0 * DM + (col & ~1), DM, col & 1, gv * a[0], gv * a[1], gv * a[2], gv * a[3]);
.LBB0_857:
	s_ashr_i32 s3, s10, 5
	s_lshl_b32 s4, s80, 8
	s_ashr_i32 s11, s10, 31
	v_lshl_or_b32 v136, v150, 5, s4
	s_mul_hi_i32 s65, s3, 0x9000
	s_mul_i32 s3, s3, 0x9000
	s_lshl_b64 s[4:5], s[10:11], 8
	v_ashrrev_i32_e32 v135, 31, v134
	v_or_b32_e32 v132, v136, v145
	v_lshl_add_u64 v[130:131], s[4:5], 0, v[134:135]
	v_and_b32_e32 v128, 1, v140
	v_bfe_i32 v133, v140, 0, 1
	s_add_u32 s4, s1, s3
	v_lshl_or_b32 v130, v149, 2, v130
	v_cmp_eq_u32_e32 vcc, 0, v128
	v_and_b32_e32 v128, 0x2000, v133
	v_ashrrev_i32_e32 v133, 31, v132
	s_addc_u32 s5, s6, s65
	v_bitop3_b32 v136, v136, s74, v145 bitop3:0xc8
	v_lshl_add_u64 v[134:135], v[132:133], 2, s[4:5]
	v_ashrrev_i32_e32 v137, 31, v136
	v_lshlrev_b64 v[130:131], 12, v[130:131]
	global_load_dword v244, v[134:135], off
	global_load_dword v245, v[134:135], off offset:64
	global_load_dword v246, v[134:135], off offset:512
	global_load_dword v247, v[134:135], off offset:576
	v_lshl_add_u64 v[130:131], s[16:17], 0, v[130:131]
	v_lshlrev_b64 v[136:137], 2, v[136:137]
	v_lshl_add_u64 v[138:139], v[130:131], 0, v[136:137]
	v_lshl_add_u64 v[138:139], v[138:139], 0, v[128:129]
	v_add_co_u32_e64 v146, s[10:11], s8, v138
	v_mov_b64_e32 v[248:249], v[138:139]
	global_load_dwordx2 v[168:169], v[248:249], off
	s_mov_b32 s98, 0x1000
	s_mov_b32 s99, 0
	v_lshl_add_u64 v[250:251], v[248:249], 0, s[98:99]
	global_load_dwordx2 v[170:171], v[250:251], off
	s_mov_b32 s98, 0x10000
	s_mov_b32 s99, 0
	v_lshl_add_u64 v[250:251], v[248:249], 0, s[98:99]
	global_load_dwordx2 v[172:173], v[250:251], off
	s_mov_b32 s98, 0x11000
	s_mov_b32 s99, 0
	v_lshl_add_u64 v[250:251], v[248:249], 0, s[98:99]
	global_load_dwordx2 v[174:175], v[250:251], off
	s_mov_b32 s98, 0x20000
	s_mov_b32 s99, 0
	v_lshl_add_u64 v[250:251], v[248:249], 0, s[98:99]
	global_load_dwordx2 v[176:177], v[250:251], off
	s_mov_b32 s98, 0x21000
	s_mov_b32 s99, 0
	v_lshl_add_u64 v[250:251], v[248:249], 0, s[98:99]
	global_load_dwordx2 v[178:179], v[250:251], off
	s_mov_b32 s98, 0x30000
	s_mov_b32 s99, 0
	v_lshl_add_u64 v[250:251], v[248:249], 0, s[98:99]
	global_load_dwordx2 v[180:181], v[250:251], off
	s_mov_b32 s98, 0x31000
	s_mov_b32 s99, 0
	v_lshl_add_u64 v[250:251], v[248:249], 0, s[98:99]
	global_load_dwordx2 v[182:183], v[250:251], off
	s_mov_b32 s98, 0x80000
	s_mov_b32 s99, 0
	v_lshl_add_u64 v[250:251], v[248:249], 0, s[98:99]
	global_load_dwordx2 v[184:185], v[250:251], off
	s_mov_b32 s98, 0x81000
	s_mov_b32 s99, 0
	v_lshl_add_u64 v[250:251], v[248:249], 0, s[98:99]
	global_load_dwordx2 v[186:187], v[250:251], off
	s_mov_b32 s98, 0x90000
	s_mov_b32 s99, 0
	v_lshl_add_u64 v[250:251], v[248:249], 0, s[98:99]
	global_load_dwordx2 v[188:189], v[250:251], off
	s_mov_b32 s98, 0x91000
	s_mov_b32 s99, 0
	v_lshl_add_u64 v[250:251], v[248:249], 0, s[98:99]
	global_load_dwordx2 v[190:191], v[250:251], off
	s_mov_b32 s98, 0xa0000
	s_mov_b32 s99, 0
	v_lshl_add_u64 v[250:251], v[248:249], 0, s[98:99]
	global_load_dwordx2 v[192:193], v[250:251], off
	s_mov_b32 s98, 0xa1000
	s_mov_b32 s99, 0
	v_lshl_add_u64 v[250:251], v[248:249], 0, s[98:99]
	global_load_dwordx2 v[196:197], v[250:251], off
	s_mov_b32 s98, 0xb0000
	s_mov_b32 s99, 0
	v_lshl_add_u64 v[250:251], v[248:249], 0, s[98:99]
	global_load_dwordx2 v[198:199], v[250:251], off
	s_mov_b32 s98, 0xb1000
	s_mov_b32 s99, 0
	v_lshl_add_u64 v[250:251], v[248:249], 0, s[98:99]
	global_load_dwordx2 v[200:201], v[250:251], off
	s_mov_b32 s98, 0x40
	s_mov_b32 s99, 0
	v_lshl_add_u64 v[250:251], v[248:249], 0, s[98:99]
	global_load_dwordx2 v[202:203], v[250:251], off
	s_mov_b32 s98, 0x1040
	s_mov_b32 s99, 0
	v_lshl_add_u64 v[250:251], v[248:249], 0, s[98:99]
	global_load_dwordx2 v[204:205], v[250:251], off
	s_mov_b32 s98, 0x10040
	s_mov_b32 s99, 0
	v_lshl_add_u64 v[250:251], v[248:249], 0, s[98:99]
	global_load_dwordx2 v[206:207], v[250:251], off
	s_mov_b32 s98, 0x11040
	s_mov_b32 s99, 0
	v_lshl_add_u64 v[250:251], v[248:249], 0, s[98:99]
	global_load_dwordx2 v[208:209], v[250:251], off
	s_mov_b32 s98, 0x20040
	s_mov_b32 s99, 0
	v_lshl_add_u64 v[250:251], v[248:249], 0, s[98:99]
	global_load_dwordx2 v[210:211], v[250:251], off
	s_mov_b32 s98, 0x21040
	s_mov_b32 s99, 0
	v_lshl_add_u64 v[250:251], v[248:249], 0, s[98:99]
	global_load_dwordx2 v[212:213], v[250:251], off
	s_mov_b32 s98, 0x30040
	s_mov_b32 s99, 0
	v_lshl_add_u64 v[250:251], v[248:249], 0, s[98:99]
	global_load_dwordx2 v[214:215], v[250:251], off
	s_mov_b32 s98, 0x31040
	s_mov_b32 s99, 0
	v_lshl_add_u64 v[250:251], v[248:249], 0, s[98:99]
	global_load_dwordx2 v[216:217], v[250:251], off
	s_mov_b32 s98, 0x80040
	s_mov_b32 s99, 0
	v_lshl_add_u64 v[250:251], v[248:249], 0, s[98:99]
	global_load_dwordx2 v[218:219], v[250:251], off
	s_mov_b32 s98, 0x81040
	s_mov_b32 s99, 0
	v_lshl_add_u64 v[250:251], v[248:249], 0, s[98:99]
	global_load_dwordx2 v[220:221], v[250:251], off
	s_mov_b32 s98, 0x90040
	s_mov_b32 s99, 0
	v_lshl_add_u64 v[250:251], v[248:249], 0, s[98:99]
	global_load_dwordx2 v[222:223], v[250:251], off
	s_mov_b32 s98, 0x91040
	s_mov_b32 s99, 0
	v_lshl_add_u64 v[250:251], v[248:249], 0, s[98:99]
	global_load_dwordx2 v[224:225], v[250:251], off
	s_mov_b32 s98, 0xa0040
	s_mov_b32 s99, 0
	v_lshl_add_u64 v[250:251], v[248:249], 0, s[98:99]
	global_load_dwordx2 v[226:227], v[250:251], off
	s_mov_b32 s98, 0xa1040
	s_mov_b32 s99, 0
	v_lshl_add_u64 v[250:251], v[248:249], 0, s[98:99]
	global_load_dwordx2 v[228:229], v[250:251], off
	s_mov_b32 s98, 0xb0040
	s_mov_b32 s99, 0
	v_lshl_add_u64 v[250:251], v[248:249], 0, s[98:99]
	global_load_dwordx2 v[230:231], v[250:251], off
	s_mov_b32 s98, 0xb1040
	s_mov_b32 s99, 0
	v_lshl_add_u64 v[250:251], v[248:249], 0, s[98:99]
	global_load_dwordx2 v[232:233], v[250:251], off
	s_nop 0
	v_addc_co_u32_e64 v147, s[10:11], 0, v139, s[10:11]
	s_mov_b64 s[84:85], 0
	s_mov_b32 s80, s66
	s_waitcnt vmcnt(30)
; DI float dppx1(float v) { return __int_as_float(__builtin_amdgcn_update_dpp(0, __float_as_int(v), 0xB1, 0xF, 0xF, true)); }
; DI void rmw_pair_f32(float* xo_even, const float* xi_even, long ld, bool odd, float v0, float v1, float v2, float v3) {
;   const float sx = odd ? v0 : v2, sy = odd ? v1 : v3;
;   const float rx = dppx1(sx), ry = dppx1(sy);
;   const long off = odd ? 2 * ld : 0;
;   const float2 a0 = *(const float2*)(xi_even + off), a1 = *(const float2*)(xi_even + off + ld);
;   float2 o0, o1;
;   if (odd) { o0 = float2{a0.x + rx, a0.y + v2}; o1 = float2{a1.x + ry, a1.y + v3}; }
;   else     { o0 = float2{a0.x + v0, a0.y + rx}; o1 = float2{a1.x + v1, a1.y + ry}; }
;   *(float2*)(xo_even + off) = o0;
;   *(float2*)(xo_even + off + ld) = o1;
; }
; __global__ void __launch_bounds__(NTHR) fwd_kernel(Params pk) {
;     ...
;             const int b = (pm * 256) >> 13;
; #pragma unroll
;             for (int bj = 0; bj < 2; ++bj)
; #pragma unroll
;               for (int n = 0; n < 2; ++n) {
;                 const int col = pn * 256 + bj * 128 + wc * 32 + n * 16 + fr;
;                 const float gv = gate[(long)b * 9216 + col];
; #pragma unroll
;                 for (int ai = 0; ai < 2; ++ai)
; #pragma unroll
;                   for (int m = 0; m < 4; ++m) {
;                     const long row0 = (long)pm * 256 + ai * 128 + wr * 64 + m * 16 + fq * 4;
;                     const f32x4 a = acc[ai][bj][m][n];
;                     rmw_pair_f32(xo + row0 * DM + (col & ~1), xo + row0 * DM + (col & ~1), DM, col & 1, gv * a[0], gv * a[1], gv * a[2], gv * a[3]);
	v_mov_b64_e32 v[144:145], v[168:169]
	v_mov_b64_e32 v[148:149], v[170:171]
	v_mov_b32_e32 v133, v244
	v_mul_f32_e32 v124, v124, v133
	v_mul_f32_e32 v143, v126, v133
	v_mul_f32_e32 v140, v125, v133
	v_mul_f32_e32 v127, v127, v133
	v_cndmask_b32_e32 v125, v124, v143, vcc
	v_cndmask_b32_e32 v126, v140, v127, vcc
	v_mul_f32_e32 v120, v120, v133
	v_mov_b32_dpp v125, v125 quad_perm:[1,0,3,2] row_mask:0xf bank_mask:0xf bound_ctrl:1
	v_mov_b32_dpp v141, v126 quad_perm:[1,0,3,2] row_mask:0xf bank_mask:0xf bound_ctrl:1
	v_mov_b32_e32 v142, v125
	v_pk_add_f32 v[150:151], v[124:125], v[144:145]
	v_pk_add_f32 v[124:125], v[144:145], v[142:143]
	v_mov_b32_e32 v126, v141
	v_pk_add_f32 v[152:153], v[140:141], v[148:149]
	v_pk_add_f32 v[126:127], v[148:149], v[126:127]
	v_cndmask_b32_e32 v125, v125, v151, vcc
	v_cndmask_b32_e32 v124, v124, v150, vcc
	v_cndmask_b32_e32 v127, v127, v153, vcc
	v_cndmask_b32_e32 v126, v126, v152, vcc
	global_store_dwordx2 v[138:139], v[124:125], off
	global_store_dwordx2 v[146:147], v[126:127], off
	v_lshl_add_u64 v[124:125], v[130:131], 0, s[52:53]
	v_lshl_add_u64 v[126:127], v[124:125], 0, v[136:137]
	v_lshl_add_u64 v[126:127], v[126:127], 0, v[128:129]
	v_add_co_u32_e64 v144, s[10:11], s8, v126
	s_nop 0
	v_addc_co_u32_e64 v145, s[10:11], 0, v127, s[10:11]
	v_mul_f32_e32 v141, v122, v133
	v_mul_f32_e32 v138, v121, v133
	v_mul_f32_e32 v123, v123, v133
	v_cndmask_b32_e32 v121, v120, v141, vcc
	v_cndmask_b32_e32 v122, v138, v123, vcc
	v_mul_f32_e32 v116, v116, v133
	v_mov_b32_dpp v121, v121 quad_perm:[1,0,3,2] row_mask:0xf bank_mask:0xf bound_ctrl:1
	v_mov_b32_dpp v139, v122 quad_perm:[1,0,3,2] row_mask:0xf bank_mask:0xf bound_ctrl:1
	v_mov_b32_e32 v140, v121
	v_mov_b32_e32 v122, v139
	v_mul_f32_e32 v119, v119, v133
	v_mul_f32_e32 v112, v112, v133
	v_mul_f32_e32 v115, v115, v133
	v_mul_f32_e32 v108, v108, v133
	v_mul_f32_e32 v111, v111, v133
	v_mul_f32_e32 v104, v104, v133
	v_mul_f32_e32 v107, v107, v133
	v_mul_f32_e32 v100, v100, v133
	v_mul_f32_e32 v103, v103, v133
	v_mul_f32_e32 v96, v96, v133
	v_mul_f32_e32 v99, v99, v133
	s_waitcnt vmcnt(30)
	v_mov_b64_e32 v[142:143], v[172:173]
	v_mov_b64_e32 v[146:147], v[174:175]
	v_pk_add_f32 v[148:149], v[120:121], v[142:143]
	v_pk_add_f32 v[120:121], v[142:143], v[140:141]
	v_pk_add_f32 v[150:151], v[138:139], v[146:147]
	v_pk_add_f32 v[122:123], v[146:147], v[122:123]
	v_cndmask_b32_e32 v121, v121, v149, vcc
	v_cndmask_b32_e32 v120, v120, v148, vcc
	v_cndmask_b32_e32 v123, v123, v151, vcc
	v_cndmask_b32_e32 v122, v122, v150, vcc
	global_store_dwordx2 v[126:127], v[120:121], off
	global_store_dwordx2 v[144:145], v[122:123], off
	v_lshl_add_u64 v[120:121], v[130:131], 0, s[18:19]
	v_lshl_add_u64 v[122:123], v[120:121], 0, v[136:137]
	v_lshl_add_u64 v[122:123], v[122:123], 0, v[128:129]
	v_add_co_u32_e64 v142, s[10:11], s8, v122
	s_nop 0
	v_addc_co_u32_e64 v143, s[10:11], 0, v123, s[10:11]
	v_mul_f32_e32 v139, v118, v133
	v_mul_f32_e32 v126, v117, v133
	v_cndmask_b32_e32 v117, v116, v139, vcc
	v_cndmask_b32_e32 v118, v126, v119, vcc
	s_nop 0
	v_mov_b32_dpp v117, v117 quad_perm:[1,0,3,2] row_mask:0xf bank_mask:0xf bound_ctrl:1
	v_mov_b32_dpp v127, v118 quad_perm:[1,0,3,2] row_mask:0xf bank_mask:0xf bound_ctrl:1
	v_mov_b32_e32 v138, v117
	v_mov_b32_e32 v118, v127
	s_waitcnt vmcnt(30)
	v_mov_b64_e32 v[140:141], v[176:177]
	v_mov_b64_e32 v[144:145], v[178:179]
	v_pk_add_f32 v[146:147], v[116:117], v[140:141]
	v_pk_add_f32 v[116:117], v[140:141], v[138:139]
	v_pk_add_f32 v[148:149], v[126:127], v[144:145]
	v_pk_add_f32 v[118:119], v[144:145], v[118:119]
	v_cndmask_b32_e32 v117, v117, v147, vcc
	v_cndmask_b32_e32 v116, v116, v146, vcc
	v_cndmask_b32_e32 v119, v119, v149, vcc
	v_cndmask_b32_e32 v118, v118, v148, vcc
	global_store_dwordx2 v[122:123], v[116:117], off
	global_store_dwordx2 v[142:143], v[118:119], off
	v_lshl_add_u64 v[116:117], v[130:131], 0, s[54:55]
	v_lshl_add_u64 v[118:119], v[116:117], 0, v[136:137]
	v_lshl_add_u64 v[118:119], v[118:119], 0, v[128:129]
	v_add_co_u32_e64 v140, s[10:11], s8, v118
	s_nop 0
	v_addc_co_u32_e64 v141, s[10:11], 0, v119, s[10:11]
	v_mul_f32_e32 v127, v114, v133
	v_mul_f32_e32 v122, v113, v133
	v_cndmask_b32_e32 v113, v112, v127, vcc
	v_cndmask_b32_e32 v114, v122, v115, vcc
	s_nop 0
	v_mov_b32_dpp v113, v113 quad_perm:[1,0,3,2] row_mask:0xf bank_mask:0xf bound_ctrl:1
	v_mov_b32_dpp v123, v114 quad_perm:[1,0,3,2] row_mask:0xf bank_mask:0xf bound_ctrl:1
	v_mov_b32_e32 v126, v113
	v_mov_b32_e32 v114, v123
	s_waitcnt vmcnt(30)
	v_mov_b64_e32 v[138:139], v[180:181]
	v_mov_b64_e32 v[142:143], v[182:183]
	v_pk_add_f32 v[144:145], v[112:113], v[138:139]
	v_pk_add_f32 v[112:113], v[138:139], v[126:127]
	v_pk_add_f32 v[146:147], v[122:123], v[142:143]
	v_pk_add_f32 v[114:115], v[142:143], v[114:115]
	v_cndmask_b32_e32 v113, v113, v145, vcc
	v_cndmask_b32_e32 v112, v112, v144, vcc
	v_cndmask_b32_e32 v115, v115, v147, vcc
	v_cndmask_b32_e32 v114, v114, v146, vcc
	global_store_dwordx2 v[118:119], v[112:113], off
	global_store_dwordx2 v[140:141], v[114:115], off
	v_lshl_add_u64 v[112:113], v[130:131], 0, s[56:57]
	v_lshl_add_u64 v[114:115], v[112:113], 0, v[136:137]
	v_lshl_add_u64 v[114:115], v[114:115], 0, v[128:129]
	v_add_co_u32_e64 v138, s[10:11], s8, v114
	s_nop 0
	v_addc_co_u32_e64 v139, s[10:11], 0, v115, s[10:11]
	v_mul_f32_e32 v123, v110, v133
	v_mul_f32_e32 v118, v109, v133
	v_cndmask_b32_e32 v109, v108, v123, vcc
	v_cndmask_b32_e32 v110, v118, v111, vcc
	s_nop 0
	v_mov_b32_dpp v109, v109 quad_perm:[1,0,3,2] row_mask:0xf bank_mask:0xf bound_ctrl:1
	v_mov_b32_dpp v119, v110 quad_perm:[1,0,3,2] row_mask:0xf bank_mask:0xf bound_ctrl:1
	v_mov_b32_e32 v122, v109
	v_mov_b32_e32 v110, v119
	s_waitcnt vmcnt(30)
; DI float dppx1(float v) { return __int_as_float(__builtin_amdgcn_update_dpp(0, __float_as_int(v), 0xB1, 0xF, 0xF, true)); }
; DI void rmw_pair_f32(float* xo_even, const float* xi_even, long ld, bool odd, float v0, float v1, float v2, float v3) {
;   const float sx = odd ? v0 : v2, sy = odd ? v1 : v3;
;   const float rx = dppx1(sx), ry = dppx1(sy);
;   const long off = odd ? 2 * ld : 0;
;   const float2 a0 = *(const float2*)(xi_even + off), a1 = *(const float2*)(xi_even + off + ld);
;   float2 o0, o1;
;   if (odd) { o0 = float2{a0.x + rx, a0.y + v2}; o1 = float2{a1.x + ry, a1.y + v3}; }
;   else     { o0 = float2{a0.x + v0, a0.y + rx}; o1 = float2{a1.x + v1, a1.y + ry}; }
;   *(float2*)(xo_even + off) = o0;
;   *(float2*)(xo_even + off + ld) = o1;
; }
; __global__ void __launch_bounds__(NTHR) fwd_kernel(Params pk) {
;     ...
;             const int b = (pm * 256) >> 13;
; #pragma unroll
;             for (int bj = 0; bj < 2; ++bj)
; #pragma unroll
;               for (int n = 0; n < 2; ++n) {
;                 const int col = pn * 256 + bj * 128 + wc * 32 + n * 16 + fr;
;                 const float gv = gate[(long)b * 9216 + col];
; #pragma unroll
;                 for (int ai = 0; ai < 2; ++ai)
; #pragma unroll
;                   for (int m = 0; m < 4; ++m) {
;                     const long row0 = (long)pm * 256 + ai * 128 + wr * 64 + m * 16 + fq * 4;
;                     const f32x4 a = acc[ai][bj][m][n];
;                     rmw_pair_f32(xo + row0 * DM + (col & ~1), xo + row0 * DM + (col & ~1), DM, col & 1, gv * a[0], gv * a[1], gv * a[2], gv * a[3]);
	v_mov_b64_e32 v[126:127], v[184:185]
	v_mov_b64_e32 v[140:141], v[186:187]
	v_pk_add_f32 v[142:143], v[108:109], v[126:127]
	v_pk_add_f32 v[108:109], v[126:127], v[122:123]
	v_pk_add_f32 v[144:145], v[118:119], v[140:141]
	v_pk_add_f32 v[110:111], v[140:141], v[110:111]
	v_cndmask_b32_e32 v109, v109, v143, vcc
	v_cndmask_b32_e32 v108, v108, v142, vcc
	v_cndmask_b32_e32 v111, v111, v145, vcc
	v_cndmask_b32_e32 v110, v110, v144, vcc
	global_store_dwordx2 v[114:115], v[108:109], off
	global_store_dwordx2 v[138:139], v[110:111], off
	v_lshl_add_u64 v[108:109], v[130:131], 0, s[58:59]
	v_lshl_add_u64 v[110:111], v[108:109], 0, v[136:137]
	v_lshl_add_u64 v[110:111], v[110:111], 0, v[128:129]
	v_add_co_u32_e64 v126, s[10:11], s8, v110
	s_nop 0
	v_addc_co_u32_e64 v127, s[10:11], 0, v111, s[10:11]
	v_mul_f32_e32 v119, v106, v133
	v_mul_f32_e32 v114, v105, v133
	v_cndmask_b32_e32 v105, v104, v119, vcc
	v_cndmask_b32_e32 v106, v114, v107, vcc
	s_nop 0
	v_mov_b32_dpp v105, v105 quad_perm:[1,0,3,2] row_mask:0xf bank_mask:0xf bound_ctrl:1
	v_mov_b32_dpp v115, v106 quad_perm:[1,0,3,2] row_mask:0xf bank_mask:0xf bound_ctrl:1
	v_mov_b32_e32 v118, v105
	v_mov_b32_e32 v106, v115
	s_waitcnt vmcnt(30)
	v_mov_b64_e32 v[122:123], v[188:189]
	v_mov_b64_e32 v[138:139], v[190:191]
	v_pk_add_f32 v[140:141], v[104:105], v[122:123]
	v_pk_add_f32 v[104:105], v[122:123], v[118:119]
	v_pk_add_f32 v[142:143], v[114:115], v[138:139]
	v_pk_add_f32 v[106:107], v[138:139], v[106:107]
	v_cndmask_b32_e32 v105, v105, v141, vcc
	v_cndmask_b32_e32 v104, v104, v140, vcc
	v_cndmask_b32_e32 v107, v107, v143, vcc
	v_cndmask_b32_e32 v106, v106, v142, vcc
	global_store_dwordx2 v[110:111], v[104:105], off
	global_store_dwordx2 v[126:127], v[106:107], off
	v_lshl_add_u64 v[104:105], v[130:131], 0, s[60:61]
	v_lshl_add_u64 v[106:107], v[104:105], 0, v[136:137]
	v_lshl_add_u64 v[106:107], v[106:107], 0, v[128:129]
	v_add_co_u32_e64 v122, s[10:11], s8, v106
	s_nop 0
	v_addc_co_u32_e64 v123, s[10:11], 0, v107, s[10:11]
	v_mul_f32_e32 v115, v102, v133
	v_mul_f32_e32 v110, v101, v133
	v_cndmask_b32_e32 v101, v100, v115, vcc
	v_cndmask_b32_e32 v102, v110, v103, vcc
	s_nop 0
	v_mov_b32_dpp v101, v101 quad_perm:[1,0,3,2] row_mask:0xf bank_mask:0xf bound_ctrl:1
	v_mov_b32_dpp v111, v102 quad_perm:[1,0,3,2] row_mask:0xf bank_mask:0xf bound_ctrl:1
	v_mov_b32_e32 v114, v101
	v_mov_b32_e32 v102, v111
	s_waitcnt vmcnt(30)
	v_mov_b64_e32 v[118:119], v[192:193]
	v_mov_b64_e32 v[126:127], v[196:197]
	v_pk_add_f32 v[138:139], v[100:101], v[118:119]
	v_pk_add_f32 v[100:101], v[118:119], v[114:115]
	v_pk_add_f32 v[140:141], v[110:111], v[126:127]
	v_pk_add_f32 v[102:103], v[126:127], v[102:103]
	v_cndmask_b32_e32 v101, v101, v139, vcc
	v_cndmask_b32_e32 v100, v100, v138, vcc
	v_cndmask_b32_e32 v103, v103, v141, vcc
	v_cndmask_b32_e32 v102, v102, v140, vcc
	global_store_dwordx2 v[106:107], v[100:101], off
	global_store_dwordx2 v[122:123], v[102:103], off
	v_lshl_add_u64 v[100:101], v[130:131], 0, s[62:63]
	v_lshl_add_u64 v[102:103], v[100:101], 0, v[136:137]
	v_lshl_add_u64 v[102:103], v[102:103], 0, v[128:129]
	v_add_co_u32_e64 v118, s[10:11], s8, v102
	s_nop 0
	v_addc_co_u32_e64 v119, s[10:11], 0, v103, s[10:11]
	v_mul_f32_e32 v111, v98, v133
	v_mul_f32_e32 v106, v97, v133
	v_cndmask_b32_e32 v97, v96, v111, vcc
	v_cndmask_b32_e32 v98, v106, v99, vcc
	s_nop 0
	v_mov_b32_dpp v97, v97 quad_perm:[1,0,3,2] row_mask:0xf bank_mask:0xf bound_ctrl:1
	v_mov_b32_dpp v107, v98 quad_perm:[1,0,3,2] row_mask:0xf bank_mask:0xf bound_ctrl:1
	v_mov_b32_e32 v110, v97
	v_mov_b32_e32 v98, v107
	s_waitcnt vmcnt(30)
	v_mov_b64_e32 v[114:115], v[198:199]
	v_mov_b64_e32 v[122:123], v[200:201]
	v_pk_add_f32 v[126:127], v[96:97], v[114:115]
	v_pk_add_f32 v[96:97], v[114:115], v[110:111]
	v_pk_add_f32 v[136:137], v[106:107], v[122:123]
	v_pk_add_f32 v[98:99], v[122:123], v[98:99]
	v_cndmask_b32_e32 v97, v97, v127, vcc
	v_cndmask_b32_e32 v96, v96, v126, vcc
	v_cndmask_b32_e32 v99, v99, v137, vcc
	v_cndmask_b32_e32 v98, v98, v136, vcc
	global_store_dwordx2 v[102:103], v[96:97], off
	global_store_dwordx2 v[118:119], v[98:99], off
	v_bitop3_b32 v96, v132, s75, 16 bitop3:0xc8
	v_ashrrev_i32_e32 v97, 31, v96
	v_lshlrev_b64 v[96:97], 2, v[96:97]
	v_lshl_add_u64 v[102:103], v[130:131], 0, v[96:97]
	v_lshl_add_u64 v[102:103], v[102:103], 0, v[128:129]
	v_add_co_u32_e64 v118, s[10:11], s8, v102
	s_mov_b32 s98, 0x200
	s_mov_b32 s99, 0
	v_lshl_add_u64 v[250:251], v[248:249], 0, s[98:99]
	global_load_dwordx2 v[168:169], v[250:251], off
	s_mov_b32 s98, 0x1200
	s_mov_b32 s99, 0
	v_lshl_add_u64 v[250:251], v[248:249], 0, s[98:99]
	global_load_dwordx2 v[170:171], v[250:251], off
	s_mov_b32 s98, 0x10200
	s_mov_b32 s99, 0
	v_lshl_add_u64 v[250:251], v[248:249], 0, s[98:99]
	global_load_dwordx2 v[172:173], v[250:251], off
	s_mov_b32 s98, 0x11200
	s_mov_b32 s99, 0
	v_lshl_add_u64 v[250:251], v[248:249], 0, s[98:99]
	global_load_dwordx2 v[174:175], v[250:251], off
	s_mov_b32 s98, 0x20200
	s_mov_b32 s99, 0
	v_lshl_add_u64 v[250:251], v[248:249], 0, s[98:99]
	global_load_dwordx2 v[176:177], v[250:251], off
	s_mov_b32 s98, 0x21200
	s_mov_b32 s99, 0
	v_lshl_add_u64 v[250:251], v[248:249], 0, s[98:99]
	global_load_dwordx2 v[178:179], v[250:251], off
	s_mov_b32 s98, 0x30200
	s_mov_b32 s99, 0
	v_lshl_add_u64 v[250:251], v[248:249], 0, s[98:99]
	global_load_dwordx2 v[180:181], v[250:251], off
	s_mov_b32 s98, 0x31200
	s_mov_b32 s99, 0
	v_lshl_add_u64 v[250:251], v[248:249], 0, s[98:99]
	global_load_dwordx2 v[182:183], v[250:251], off
	s_mov_b32 s98, 0x80200
	s_mov_b32 s99, 0
	v_lshl_add_u64 v[250:251], v[248:249], 0, s[98:99]
	global_load_dwordx2 v[184:185], v[250:251], off
	s_mov_b32 s98, 0x81200
	s_mov_b32 s99, 0
	v_lshl_add_u64 v[250:251], v[248:249], 0, s[98:99]
	global_load_dwordx2 v[186:187], v[250:251], off
	s_mov_b32 s98, 0x90200
	s_mov_b32 s99, 0
	v_lshl_add_u64 v[250:251], v[248:249], 0, s[98:99]
	global_load_dwordx2 v[188:189], v[250:251], off
	s_mov_b32 s98, 0x91200
	s_mov_b32 s99, 0
	v_lshl_add_u64 v[250:251], v[248:249], 0, s[98:99]
	global_load_dwordx2 v[190:191], v[250:251], off
	s_mov_b32 s98, 0xa0200
	s_mov_b32 s99, 0
	v_lshl_add_u64 v[250:251], v[248:249], 0, s[98:99]
	global_load_dwordx2 v[192:193], v[250:251], off
	s_mov_b32 s98, 0xa1200
	s_mov_b32 s99, 0
	v_lshl_add_u64 v[250:251], v[248:249], 0, s[98:99]
	global_load_dwordx2 v[196:197], v[250:251], off
	s_mov_b32 s98, 0xb0200
	s_mov_b32 s99, 0
	v_lshl_add_u64 v[250:251], v[248:249], 0, s[98:99]
	global_load_dwordx2 v[198:199], v[250:251], off
	s_mov_b32 s98, 0xb1200
	s_mov_b32 s99, 0
	v_lshl_add_u64 v[250:251], v[248:249], 0, s[98:99]
	global_load_dwordx2 v[200:201], v[250:251], off
	s_nop 0
	v_addc_co_u32_e64 v119, s[10:11], 0, v103, s[10:11]
	s_waitcnt vmcnt(46)
; DI float dppx1(float v) { return __int_as_float(__builtin_amdgcn_update_dpp(0, __float_as_int(v), 0xB1, 0xF, 0xF, true)); }
; DI void rmw_pair_f32(float* xo_even, const float* xi_even, long ld, bool odd, float v0, float v1, float v2, float v3) {
;   const float sx = odd ? v0 : v2, sy = odd ? v1 : v3;
;   const float rx = dppx1(sx), ry = dppx1(sy);
;   const long off = odd ? 2 * ld : 0;
;   const float2 a0 = *(const float2*)(xi_even + off), a1 = *(const float2*)(xi_even + off + ld);
;   float2 o0, o1;
;   if (odd) { o0 = float2{a0.x + rx, a0.y + v2}; o1 = float2{a1.x + ry, a1.y + v3}; }
;   else     { o0 = float2{a0.x + v0, a0.y + rx}; o1 = float2{a1.x + v1, a1.y + ry}; }
;   *(float2*)(xo_even + off) = o0;
;   *(float2*)(xo_even + off + ld) = o1;
; }
; __global__ void __launch_bounds__(NTHR) fwd_kernel(Params pk) {
;     ...
;             const int b = (pm * 256) >> 13;
; #pragma unroll
;             for (int bj = 0; bj < 2; ++bj)
; #pragma unroll
;               for (int n = 0; n < 2; ++n) {
;                 const int col = pn * 256 + bj * 128 + wc * 32 + n * 16 + fr;
;                 const float gv = gate[(long)b * 9216 + col];
; #pragma unroll
;                 for (int ai = 0; ai < 2; ++ai)
; #pragma unroll
;                   for (int m = 0; m < 4; ++m) {
;                     const long row0 = (long)pm * 256 + ai * 128 + wr * 64 + m * 16 + fq * 4;
;                     const f32x4 a = acc[ai][bj][m][n];
;                     rmw_pair_f32(xo + row0 * DM + (col & ~1), xo + row0 * DM + (col & ~1), DM, col & 1, gv * a[0], gv * a[1], gv * a[2], gv * a[3]);
	v_mov_b64_e32 v[114:115], v[202:203]
	v_mov_b64_e32 v[122:123], v[204:205]
	v_mov_b32_e32 v98, v245
	v_mul_f32_e32 v92, v92, v98
	v_mul_f32_e32 v111, v94, v98
	v_mul_f32_e32 v106, v93, v98
	v_mul_f32_e32 v95, v95, v98
	v_cndmask_b32_e32 v93, v92, v111, vcc
	v_cndmask_b32_e32 v94, v106, v95, vcc
	v_mul_f32_e32 v88, v88, v98
	v_mov_b32_dpp v93, v93 quad_perm:[1,0,3,2] row_mask:0xf bank_mask:0xf bound_ctrl:1
	v_mov_b32_dpp v107, v94 quad_perm:[1,0,3,2] row_mask:0xf bank_mask:0xf bound_ctrl:1
	v_mov_b32_e32 v110, v93
	v_pk_add_f32 v[126:127], v[92:93], v[114:115]
	v_pk_add_f32 v[92:93], v[114:115], v[110:111]
	v_mov_b32_e32 v94, v107
	v_pk_add_f32 v[136:137], v[106:107], v[122:123]
	v_pk_add_f32 v[94:95], v[122:123], v[94:95]
	v_cndmask_b32_e32 v93, v93, v127, vcc
	v_cndmask_b32_e32 v92, v92, v126, vcc
	v_cndmask_b32_e32 v95, v95, v137, vcc
	v_cndmask_b32_e32 v94, v94, v136, vcc
	global_store_dwordx2 v[102:103], v[92:93], off
	global_store_dwordx2 v[118:119], v[94:95], off
	v_lshl_add_u64 v[92:93], v[124:125], 0, v[96:97]
	v_lshl_add_u64 v[92:93], v[92:93], 0, v[128:129]
	v_add_co_u32_e64 v110, s[10:11], s8, v92
	s_nop 0
	v_addc_co_u32_e64 v111, s[10:11], 0, v93, s[10:11]
	v_mul_f32_e32 v103, v90, v98
	v_mul_f32_e32 v94, v89, v98
	v_mul_f32_e32 v91, v91, v98
	v_cndmask_b32_e32 v89, v88, v103, vcc
	v_cndmask_b32_e32 v90, v94, v91, vcc
	v_mul_f32_e32 v84, v84, v98
	v_mov_b32_dpp v89, v89 quad_perm:[1,0,3,2] row_mask:0xf bank_mask:0xf bound_ctrl:1
	v_mov_b32_dpp v95, v90 quad_perm:[1,0,3,2] row_mask:0xf bank_mask:0xf bound_ctrl:1
	v_mov_b32_e32 v102, v89
	v_mov_b32_e32 v90, v95
	v_mul_f32_e32 v87, v87, v98
	v_mul_f32_e32 v80, v80, v98
	v_mul_f32_e32 v83, v83, v98
	v_mul_f32_e32 v76, v76, v98
	v_mul_f32_e32 v79, v79, v98
	v_mul_f32_e32 v72, v72, v98
	v_mul_f32_e32 v75, v75, v98
	v_mul_f32_e32 v68, v68, v98
	v_mul_f32_e32 v71, v71, v98
	v_mul_f32_e32 v64, v64, v98
	v_mul_f32_e32 v67, v67, v98
	s_waitcnt vmcnt(46)
	v_mov_b64_e32 v[106:107], v[206:207]
	v_mov_b64_e32 v[114:115], v[208:209]
	v_pk_add_f32 v[118:119], v[88:89], v[106:107]
	v_pk_add_f32 v[88:89], v[106:107], v[102:103]
	v_pk_add_f32 v[122:123], v[94:95], v[114:115]
	v_pk_add_f32 v[90:91], v[114:115], v[90:91]
	v_cndmask_b32_e32 v89, v89, v119, vcc
	v_cndmask_b32_e32 v88, v88, v118, vcc
	v_cndmask_b32_e32 v91, v91, v123, vcc
	v_cndmask_b32_e32 v90, v90, v122, vcc
	global_store_dwordx2 v[92:93], v[88:89], off
	global_store_dwordx2 v[110:111], v[90:91], off
	v_lshl_add_u64 v[88:89], v[120:121], 0, v[96:97]
	v_lshl_add_u64 v[88:89], v[88:89], 0, v[128:129]
	v_add_co_u32_e64 v102, s[10:11], s8, v88
	s_nop 0
	v_addc_co_u32_e64 v103, s[10:11], 0, v89, s[10:11]
	v_mul_f32_e32 v93, v86, v98
	v_mul_f32_e32 v90, v85, v98
	v_cndmask_b32_e32 v85, v84, v93, vcc
	v_cndmask_b32_e32 v86, v90, v87, vcc
	s_nop 0
	v_mov_b32_dpp v85, v85 quad_perm:[1,0,3,2] row_mask:0xf bank_mask:0xf bound_ctrl:1
	v_mov_b32_dpp v91, v86 quad_perm:[1,0,3,2] row_mask:0xf bank_mask:0xf bound_ctrl:1
	v_mov_b32_e32 v92, v85
	v_mov_b32_e32 v86, v91
	s_waitcnt vmcnt(46)
	v_mov_b64_e32 v[94:95], v[210:211]
	v_mov_b64_e32 v[106:107], v[212:213]
	v_pk_add_f32 v[110:111], v[84:85], v[94:95]
	v_pk_add_f32 v[84:85], v[94:95], v[92:93]
	v_pk_add_f32 v[114:115], v[90:91], v[106:107]
	v_pk_add_f32 v[86:87], v[106:107], v[86:87]
	v_cndmask_b32_e32 v85, v85, v111, vcc
	v_cndmask_b32_e32 v84, v84, v110, vcc
	v_cndmask_b32_e32 v87, v87, v115, vcc
	v_cndmask_b32_e32 v86, v86, v114, vcc
	global_store_dwordx2 v[88:89], v[84:85], off
	global_store_dwordx2 v[102:103], v[86:87], off
	v_lshl_add_u64 v[84:85], v[116:117], 0, v[96:97]
	v_lshl_add_u64 v[84:85], v[84:85], 0, v[128:129]
	v_add_co_u32_e64 v92, s[10:11], s8, v84
	s_nop 0
	v_addc_co_u32_e64 v93, s[10:11], 0, v85, s[10:11]
	v_mul_f32_e32 v89, v82, v98
	v_mul_f32_e32 v86, v81, v98
	v_cndmask_b32_e32 v81, v80, v89, vcc
	v_cndmask_b32_e32 v82, v86, v83, vcc
	s_nop 0
	v_mov_b32_dpp v81, v81 quad_perm:[1,0,3,2] row_mask:0xf bank_mask:0xf bound_ctrl:1
	v_mov_b32_dpp v87, v82 quad_perm:[1,0,3,2] row_mask:0xf bank_mask:0xf bound_ctrl:1
	v_mov_b32_e32 v88, v81
	v_mov_b32_e32 v82, v87
	s_waitcnt vmcnt(46)
	v_mov_b64_e32 v[90:91], v[214:215]
	v_mov_b64_e32 v[94:95], v[216:217]
	v_pk_add_f32 v[102:103], v[80:81], v[90:91]
	v_pk_add_f32 v[80:81], v[90:91], v[88:89]
	v_pk_add_f32 v[106:107], v[86:87], v[94:95]
	v_pk_add_f32 v[82:83], v[94:95], v[82:83]
	v_cndmask_b32_e32 v81, v81, v103, vcc
	v_cndmask_b32_e32 v80, v80, v102, vcc
	v_cndmask_b32_e32 v83, v83, v107, vcc
	v_cndmask_b32_e32 v82, v82, v106, vcc
	global_store_dwordx2 v[84:85], v[80:81], off
	global_store_dwordx2 v[92:93], v[82:83], off
	v_lshl_add_u64 v[80:81], v[112:113], 0, v[96:97]
	v_lshl_add_u64 v[80:81], v[80:81], 0, v[128:129]
	v_add_co_u32_e64 v88, s[10:11], s8, v80
	s_nop 0
	v_addc_co_u32_e64 v89, s[10:11], 0, v81, s[10:11]
	v_mul_f32_e32 v85, v78, v98
	v_mul_f32_e32 v82, v77, v98
	v_cndmask_b32_e32 v77, v76, v85, vcc
	v_cndmask_b32_e32 v78, v82, v79, vcc
	s_nop 0
	v_mov_b32_dpp v77, v77 quad_perm:[1,0,3,2] row_mask:0xf bank_mask:0xf bound_ctrl:1
	v_mov_b32_dpp v83, v78 quad_perm:[1,0,3,2] row_mask:0xf bank_mask:0xf bound_ctrl:1
	v_mov_b32_e32 v84, v77
	v_mov_b32_e32 v78, v83
	s_waitcnt vmcnt(46)
; DI float dppx1(float v) { return __int_as_float(__builtin_amdgcn_update_dpp(0, __float_as_int(v), 0xB1, 0xF, 0xF, true)); }
; DI void rmw_pair_f32(float* xo_even, const float* xi_even, long ld, bool odd, float v0, float v1, float v2, float v3) {
;   const float sx = odd ? v0 : v2, sy = odd ? v1 : v3;
;   const float rx = dppx1(sx), ry = dppx1(sy);
;   const long off = odd ? 2 * ld : 0;
;   const float2 a0 = *(const float2*)(xi_even + off), a1 = *(const float2*)(xi_even + off + ld);
;   float2 o0, o1;
;   if (odd) { o0 = float2{a0.x + rx, a0.y + v2}; o1 = float2{a1.x + ry, a1.y + v3}; }
;   else     { o0 = float2{a0.x + v0, a0.y + rx}; o1 = float2{a1.x + v1, a1.y + ry}; }
;   *(float2*)(xo_even + off) = o0;
;   *(float2*)(xo_even + off + ld) = o1;
; }
; __global__ void __launch_bounds__(NTHR) fwd_kernel(Params pk) {
;     ...
;             const int b = (pm * 256) >> 13;
; #pragma unroll
;             for (int bj = 0; bj < 2; ++bj)
; #pragma unroll
;               for (int n = 0; n < 2; ++n) {
;                 const int col = pn * 256 + bj * 128 + wc * 32 + n * 16 + fr;
;                 const float gv = gate[(long)b * 9216 + col];
; #pragma unroll
;                 for (int ai = 0; ai < 2; ++ai)
; #pragma unroll
;                   for (int m = 0; m < 4; ++m) {
;                     const long row0 = (long)pm * 256 + ai * 128 + wr * 64 + m * 16 + fq * 4;
;                     const f32x4 a = acc[ai][bj][m][n];
;                     rmw_pair_f32(xo + row0 * DM + (col & ~1), xo + row0 * DM + (col & ~1), DM, col & 1, gv * a[0], gv * a[1], gv * a[2], gv * a[3]);
	v_mov_b64_e32 v[86:87], v[218:219]
	v_mov_b64_e32 v[90:91], v[220:221]
	v_pk_add_f32 v[92:93], v[76:77], v[86:87]
	v_pk_add_f32 v[76:77], v[86:87], v[84:85]
	v_pk_add_f32 v[94:95], v[82:83], v[90:91]
	v_pk_add_f32 v[78:79], v[90:91], v[78:79]
	v_cndmask_b32_e32 v77, v77, v93, vcc
	v_cndmask_b32_e32 v76, v76, v92, vcc
	v_cndmask_b32_e32 v79, v79, v95, vcc
	v_cndmask_b32_e32 v78, v78, v94, vcc
	global_store_dwordx2 v[80:81], v[76:77], off
	global_store_dwordx2 v[88:89], v[78:79], off
	v_lshl_add_u64 v[76:77], v[108:109], 0, v[96:97]
	v_lshl_add_u64 v[76:77], v[76:77], 0, v[128:129]
	v_add_co_u32_e64 v84, s[10:11], s8, v76
	s_nop 0
	v_addc_co_u32_e64 v85, s[10:11], 0, v77, s[10:11]
	v_mul_f32_e32 v81, v74, v98
	v_mul_f32_e32 v78, v73, v98
	v_cndmask_b32_e32 v73, v72, v81, vcc
	v_cndmask_b32_e32 v74, v78, v75, vcc
	s_nop 0
	v_mov_b32_dpp v73, v73 quad_perm:[1,0,3,2] row_mask:0xf bank_mask:0xf bound_ctrl:1
	v_mov_b32_dpp v79, v74 quad_perm:[1,0,3,2] row_mask:0xf bank_mask:0xf bound_ctrl:1
	v_mov_b32_e32 v80, v73
	v_mov_b32_e32 v74, v79
	s_waitcnt vmcnt(46)
	v_mov_b64_e32 v[82:83], v[222:223]
	v_mov_b64_e32 v[86:87], v[224:225]
	v_pk_add_f32 v[88:89], v[72:73], v[82:83]
	v_pk_add_f32 v[72:73], v[82:83], v[80:81]
	v_pk_add_f32 v[90:91], v[78:79], v[86:87]
	v_pk_add_f32 v[74:75], v[86:87], v[74:75]
	v_cndmask_b32_e32 v73, v73, v89, vcc
	v_cndmask_b32_e32 v72, v72, v88, vcc
	v_cndmask_b32_e32 v75, v75, v91, vcc
	v_cndmask_b32_e32 v74, v74, v90, vcc
	global_store_dwordx2 v[76:77], v[72:73], off
	global_store_dwordx2 v[84:85], v[74:75], off
	v_lshl_add_u64 v[72:73], v[104:105], 0, v[96:97]
	v_lshl_add_u64 v[72:73], v[72:73], 0, v[128:129]
	v_add_co_u32_e64 v80, s[10:11], s8, v72
	s_nop 0
	v_addc_co_u32_e64 v81, s[10:11], 0, v73, s[10:11]
	v_mul_f32_e32 v77, v70, v98
	v_mul_f32_e32 v74, v69, v98
	v_cndmask_b32_e32 v69, v68, v77, vcc
	v_cndmask_b32_e32 v70, v74, v71, vcc
	s_nop 0
	v_mov_b32_dpp v69, v69 quad_perm:[1,0,3,2] row_mask:0xf bank_mask:0xf bound_ctrl:1
	v_mov_b32_dpp v75, v70 quad_perm:[1,0,3,2] row_mask:0xf bank_mask:0xf bound_ctrl:1
	v_mov_b32_e32 v76, v69
	v_mov_b32_e32 v70, v75
	s_waitcnt vmcnt(46)
	v_mov_b64_e32 v[78:79], v[226:227]
	v_mov_b64_e32 v[82:83], v[228:229]
	v_pk_add_f32 v[84:85], v[68:69], v[78:79]
	v_pk_add_f32 v[68:69], v[78:79], v[76:77]
	v_pk_add_f32 v[86:87], v[74:75], v[82:83]
	v_pk_add_f32 v[70:71], v[82:83], v[70:71]
	v_cndmask_b32_e32 v69, v69, v85, vcc
	v_cndmask_b32_e32 v68, v68, v84, vcc
	v_cndmask_b32_e32 v71, v71, v87, vcc
	v_cndmask_b32_e32 v70, v70, v86, vcc
	global_store_dwordx2 v[72:73], v[68:69], off
	global_store_dwordx2 v[80:81], v[70:71], off
	v_lshl_add_u64 v[68:69], v[100:101], 0, v[96:97]
	v_lshl_add_u64 v[68:69], v[68:69], 0, v[128:129]
	v_add_co_u32_e64 v76, s[10:11], s8, v68
	s_nop 0
	v_addc_co_u32_e64 v77, s[10:11], 0, v69, s[10:11]
	v_mul_f32_e32 v73, v66, v98
	v_mul_f32_e32 v70, v65, v98
	v_cndmask_b32_e32 v65, v64, v73, vcc
	v_cndmask_b32_e32 v66, v70, v67, vcc
	s_nop 0
	v_mov_b32_dpp v65, v65 quad_perm:[1,0,3,2] row_mask:0xf bank_mask:0xf bound_ctrl:1
	v_mov_b32_dpp v71, v66 quad_perm:[1,0,3,2] row_mask:0xf bank_mask:0xf bound_ctrl:1
	v_mov_b32_e32 v72, v65
	v_mov_b32_e32 v66, v71
	s_waitcnt vmcnt(46)
	v_mov_b64_e32 v[74:75], v[230:231]
	v_mov_b64_e32 v[78:79], v[232:233]
	v_pk_add_f32 v[80:81], v[64:65], v[74:75]
	v_pk_add_f32 v[64:65], v[74:75], v[72:73]
	v_pk_add_f32 v[82:83], v[70:71], v[78:79]
	v_pk_add_f32 v[66:67], v[78:79], v[66:67]
	v_cndmask_b32_e32 v65, v65, v81, vcc
	v_cndmask_b32_e32 v64, v64, v80, vcc
	v_cndmask_b32_e32 v67, v67, v83, vcc
	v_cndmask_b32_e32 v66, v66, v82, vcc
	global_store_dwordx2 v[68:69], v[64:65], off
	global_store_dwordx2 v[76:77], v[66:67], off
	v_bitop3_b32 v64, v132, s76, v194 bitop3:0xc8
	v_ashrrev_i32_e32 v65, 31, v64
	v_lshlrev_b64 v[64:65], 2, v[64:65]
	v_lshl_add_u64 v[68:69], v[130:131], 0, v[64:65]
	v_lshl_add_u64 v[68:69], v[68:69], 0, v[128:129]
	v_add_co_u32_e64 v76, s[10:11], s8, v68
	s_mov_b32 s98, 0x240
	s_mov_b32 s99, 0
	v_lshl_add_u64 v[250:251], v[248:249], 0, s[98:99]
	global_load_dwordx2 v[202:203], v[250:251], off
	s_mov_b32 s98, 0x1240
	s_mov_b32 s99, 0
	v_lshl_add_u64 v[250:251], v[248:249], 0, s[98:99]
	global_load_dwordx2 v[204:205], v[250:251], off
	s_mov_b32 s98, 0x10240
	s_mov_b32 s99, 0
	v_lshl_add_u64 v[250:251], v[248:249], 0, s[98:99]
	global_load_dwordx2 v[206:207], v[250:251], off
	s_mov_b32 s98, 0x11240
	s_mov_b32 s99, 0
	v_lshl_add_u64 v[250:251], v[248:249], 0, s[98:99]
	global_load_dwordx2 v[208:209], v[250:251], off
	s_mov_b32 s98, 0x20240
	s_mov_b32 s99, 0
	v_lshl_add_u64 v[250:251], v[248:249], 0, s[98:99]
	global_load_dwordx2 v[210:211], v[250:251], off
	s_mov_b32 s98, 0x21240
	s_mov_b32 s99, 0
	v_lshl_add_u64 v[250:251], v[248:249], 0, s[98:99]
	global_load_dwordx2 v[212:213], v[250:251], off
	s_mov_b32 s98, 0x30240
	s_mov_b32 s99, 0
	v_lshl_add_u64 v[250:251], v[248:249], 0, s[98:99]
	global_load_dwordx2 v[214:215], v[250:251], off
	s_mov_b32 s98, 0x31240
	s_mov_b32 s99, 0
	v_lshl_add_u64 v[250:251], v[248:249], 0, s[98:99]
	global_load_dwordx2 v[216:217], v[250:251], off
	s_mov_b32 s98, 0x80240
	s_mov_b32 s99, 0
	v_lshl_add_u64 v[250:251], v[248:249], 0, s[98:99]
	global_load_dwordx2 v[218:219], v[250:251], off
	s_mov_b32 s98, 0x81240
	s_mov_b32 s99, 0
	v_lshl_add_u64 v[250:251], v[248:249], 0, s[98:99]
	global_load_dwordx2 v[220:221], v[250:251], off
	s_mov_b32 s98, 0x90240
	s_mov_b32 s99, 0
	v_lshl_add_u64 v[250:251], v[248:249], 0, s[98:99]
	global_load_dwordx2 v[222:223], v[250:251], off
	s_mov_b32 s98, 0x91240
	s_mov_b32 s99, 0
	v_lshl_add_u64 v[250:251], v[248:249], 0, s[98:99]
	global_load_dwordx2 v[224:225], v[250:251], off
	s_mov_b32 s98, 0xa0240
	s_mov_b32 s99, 0
	v_lshl_add_u64 v[250:251], v[248:249], 0, s[98:99]
	global_load_dwordx2 v[226:227], v[250:251], off
	s_mov_b32 s98, 0xa1240
	s_mov_b32 s99, 0
	v_lshl_add_u64 v[250:251], v[248:249], 0, s[98:99]
	global_load_dwordx2 v[228:229], v[250:251], off
	s_mov_b32 s98, 0xb0240
	s_mov_b32 s99, 0
	v_lshl_add_u64 v[250:251], v[248:249], 0, s[98:99]
	global_load_dwordx2 v[230:231], v[250:251], off
	s_mov_b32 s98, 0xb1240
	s_mov_b32 s99, 0
	v_lshl_add_u64 v[250:251], v[248:249], 0, s[98:99]
	global_load_dwordx2 v[232:233], v[250:251], off
	s_nop 0
	v_addc_co_u32_e64 v77, s[10:11], 0, v69, s[10:11]
	s_waitcnt vmcnt(46)
; DI float dppx1(float v) { return __int_as_float(__builtin_amdgcn_update_dpp(0, __float_as_int(v), 0xB1, 0xF, 0xF, true)); }
; DI void rmw_pair_f32(float* xo_even, const float* xi_even, long ld, bool odd, float v0, float v1, float v2, float v3) {
;   const float sx = odd ? v0 : v2, sy = odd ? v1 : v3;
;   const float rx = dppx1(sx), ry = dppx1(sy);
;   const long off = odd ? 2 * ld : 0;
;   const float2 a0 = *(const float2*)(xi_even + off), a1 = *(const float2*)(xi_even + off + ld);
;   float2 o0, o1;
;   if (odd) { o0 = float2{a0.x + rx, a0.y + v2}; o1 = float2{a1.x + ry, a1.y + v3}; }
;   else     { o0 = float2{a0.x + v0, a0.y + rx}; o1 = float2{a1.x + v1, a1.y + ry}; }
;   *(float2*)(xo_even + off) = o0;
;   *(float2*)(xo_even + off + ld) = o1;
; }
; __global__ void __launch_bounds__(NTHR) fwd_kernel(Params pk) {
;     ...
;             const int b = (pm * 256) >> 13;
; #pragma unroll
;             for (int bj = 0; bj < 2; ++bj)
; #pragma unroll
;               for (int n = 0; n < 2; ++n) {
;                 const int col = pn * 256 + bj * 128 + wc * 32 + n * 16 + fr;
;                 const float gv = gate[(long)b * 9216 + col];
; #pragma unroll
;                 for (int ai = 0; ai < 2; ++ai)
; #pragma unroll
;                   for (int m = 0; m < 4; ++m) {
;                     const long row0 = (long)pm * 256 + ai * 128 + wr * 64 + m * 16 + fq * 4;
;                     const f32x4 a = acc[ai][bj][m][n];
;                     rmw_pair_f32(xo + row0 * DM + (col & ~1), xo + row0 * DM + (col & ~1), DM, col & 1, gv * a[0], gv * a[1], gv * a[2], gv * a[3]);
	v_mov_b64_e32 v[74:75], v[168:169]
	v_mov_b64_e32 v[78:79], v[170:171]
	v_mov_b32_e32 v66, v246
	v_mul_f32_e32 v60, v60, v66
	v_mul_f32_e32 v73, v62, v66
	v_mul_f32_e32 v70, v61, v66
	v_mul_f32_e32 v63, v63, v66
	v_cndmask_b32_e32 v61, v60, v73, vcc
	v_cndmask_b32_e32 v62, v70, v63, vcc
	v_mul_f32_e32 v56, v56, v66
	v_mov_b32_dpp v61, v61 quad_perm:[1,0,3,2] row_mask:0xf bank_mask:0xf bound_ctrl:1
	v_mov_b32_dpp v71, v62 quad_perm:[1,0,3,2] row_mask:0xf bank_mask:0xf bound_ctrl:1
	v_mov_b32_e32 v72, v61
	v_pk_add_f32 v[80:81], v[60:61], v[74:75]
	v_pk_add_f32 v[60:61], v[74:75], v[72:73]
	v_mov_b32_e32 v62, v71
	v_pk_add_f32 v[82:83], v[70:71], v[78:79]
	v_pk_add_f32 v[62:63], v[78:79], v[62:63]
	v_cndmask_b32_e32 v61, v61, v81, vcc
	v_cndmask_b32_e32 v60, v60, v80, vcc
	v_cndmask_b32_e32 v63, v63, v83, vcc
	v_cndmask_b32_e32 v62, v62, v82, vcc
	global_store_dwordx2 v[68:69], v[60:61], off
	global_store_dwordx2 v[76:77], v[62:63], off
	v_lshl_add_u64 v[60:61], v[124:125], 0, v[64:65]
	v_lshl_add_u64 v[60:61], v[60:61], 0, v[128:129]
	v_add_co_u32_e64 v72, s[10:11], s8, v60
	s_nop 0
	v_addc_co_u32_e64 v73, s[10:11], 0, v61, s[10:11]
	v_mul_f32_e32 v69, v58, v66
	v_mul_f32_e32 v62, v57, v66
	v_mul_f32_e32 v59, v59, v66
	v_cndmask_b32_e32 v57, v56, v69, vcc
	v_cndmask_b32_e32 v58, v62, v59, vcc
	v_mul_f32_e32 v52, v52, v66
	v_mov_b32_dpp v57, v57 quad_perm:[1,0,3,2] row_mask:0xf bank_mask:0xf bound_ctrl:1
	v_mov_b32_dpp v63, v58 quad_perm:[1,0,3,2] row_mask:0xf bank_mask:0xf bound_ctrl:1
	v_mov_b32_e32 v68, v57
	v_mov_b32_e32 v58, v63
	v_mul_f32_e32 v55, v55, v66
	v_mul_f32_e32 v48, v48, v66
	v_mul_f32_e32 v51, v51, v66
	v_mul_f32_e32 v44, v44, v66
	v_mul_f32_e32 v47, v47, v66
	v_mul_f32_e32 v40, v40, v66
	v_mul_f32_e32 v43, v43, v66
	v_mul_f32_e32 v36, v36, v66
	v_mul_f32_e32 v39, v39, v66
	v_mul_f32_e32 v32, v32, v66
	v_mul_f32_e32 v35, v35, v66
	s_waitcnt vmcnt(46)
	v_mov_b64_e32 v[70:71], v[172:173]
	v_mov_b64_e32 v[74:75], v[174:175]
	v_pk_add_f32 v[76:77], v[56:57], v[70:71]
	v_pk_add_f32 v[56:57], v[70:71], v[68:69]
	v_pk_add_f32 v[78:79], v[62:63], v[74:75]
	v_pk_add_f32 v[58:59], v[74:75], v[58:59]
	v_cndmask_b32_e32 v57, v57, v77, vcc
	v_cndmask_b32_e32 v56, v56, v76, vcc
	v_cndmask_b32_e32 v59, v59, v79, vcc
	v_cndmask_b32_e32 v58, v58, v78, vcc
	global_store_dwordx2 v[60:61], v[56:57], off
	global_store_dwordx2 v[72:73], v[58:59], off
	v_lshl_add_u64 v[56:57], v[120:121], 0, v[64:65]
	v_lshl_add_u64 v[56:57], v[56:57], 0, v[128:129]
	v_add_co_u32_e64 v68, s[10:11], s8, v56
	s_nop 0
	v_addc_co_u32_e64 v69, s[10:11], 0, v57, s[10:11]
	v_mul_f32_e32 v61, v54, v66
	v_mul_f32_e32 v58, v53, v66
	v_cndmask_b32_e32 v53, v52, v61, vcc
	v_cndmask_b32_e32 v54, v58, v55, vcc
	s_nop 0
	v_mov_b32_dpp v53, v53 quad_perm:[1,0,3,2] row_mask:0xf bank_mask:0xf bound_ctrl:1
	v_mov_b32_dpp v59, v54 quad_perm:[1,0,3,2] row_mask:0xf bank_mask:0xf bound_ctrl:1
	v_mov_b32_e32 v60, v53
	v_mov_b32_e32 v54, v59
	s_waitcnt vmcnt(46)
	v_mov_b64_e32 v[62:63], v[176:177]
	v_mov_b64_e32 v[70:71], v[178:179]
	v_pk_add_f32 v[72:73], v[52:53], v[62:63]
	v_pk_add_f32 v[52:53], v[62:63], v[60:61]
	v_pk_add_f32 v[74:75], v[58:59], v[70:71]
	v_pk_add_f32 v[54:55], v[70:71], v[54:55]
	v_cndmask_b32_e32 v53, v53, v73, vcc
	v_cndmask_b32_e32 v52, v52, v72, vcc
	v_cndmask_b32_e32 v55, v55, v75, vcc
	v_cndmask_b32_e32 v54, v54, v74, vcc
	global_store_dwordx2 v[56:57], v[52:53], off
	global_store_dwordx2 v[68:69], v[54:55], off
	v_lshl_add_u64 v[52:53], v[116:117], 0, v[64:65]
	v_lshl_add_u64 v[52:53], v[52:53], 0, v[128:129]
	v_add_co_u32_e64 v60, s[10:11], s8, v52
	s_nop 0
	v_addc_co_u32_e64 v61, s[10:11], 0, v53, s[10:11]
	v_mul_f32_e32 v57, v50, v66
	v_mul_f32_e32 v54, v49, v66
	v_cndmask_b32_e32 v49, v48, v57, vcc
	v_cndmask_b32_e32 v50, v54, v51, vcc
	s_nop 0
	v_mov_b32_dpp v49, v49 quad_perm:[1,0,3,2] row_mask:0xf bank_mask:0xf bound_ctrl:1
	v_mov_b32_dpp v55, v50 quad_perm:[1,0,3,2] row_mask:0xf bank_mask:0xf bound_ctrl:1
	v_mov_b32_e32 v56, v49
	v_mov_b32_e32 v50, v55
	s_waitcnt vmcnt(46)
	v_mov_b64_e32 v[58:59], v[180:181]
	v_mov_b64_e32 v[62:63], v[182:183]
	v_pk_add_f32 v[68:69], v[48:49], v[58:59]
	v_pk_add_f32 v[48:49], v[58:59], v[56:57]
	v_pk_add_f32 v[70:71], v[54:55], v[62:63]
	v_pk_add_f32 v[50:51], v[62:63], v[50:51]
	v_cndmask_b32_e32 v49, v49, v69, vcc
	v_cndmask_b32_e32 v48, v48, v68, vcc
	v_cndmask_b32_e32 v51, v51, v71, vcc
	v_cndmask_b32_e32 v50, v50, v70, vcc
	global_store_dwordx2 v[52:53], v[48:49], off
	global_store_dwordx2 v[60:61], v[50:51], off
	v_lshl_add_u64 v[48:49], v[112:113], 0, v[64:65]
	v_lshl_add_u64 v[48:49], v[48:49], 0, v[128:129]
	v_add_co_u32_e64 v56, s[10:11], s8, v48
	s_nop 0
	v_addc_co_u32_e64 v57, s[10:11], 0, v49, s[10:11]
	v_mul_f32_e32 v53, v46, v66
	v_mul_f32_e32 v50, v45, v66
	v_cndmask_b32_e32 v45, v44, v53, vcc
	v_cndmask_b32_e32 v46, v50, v47, vcc
	s_nop 0
	v_mov_b32_dpp v45, v45 quad_perm:[1,0,3,2] row_mask:0xf bank_mask:0xf bound_ctrl:1
	v_mov_b32_dpp v51, v46 quad_perm:[1,0,3,2] row_mask:0xf bank_mask:0xf bound_ctrl:1
	v_mov_b32_e32 v52, v45
	v_mov_b32_e32 v46, v51
	s_waitcnt vmcnt(46)
; DI float dppx1(float v) { return __int_as_float(__builtin_amdgcn_update_dpp(0, __float_as_int(v), 0xB1, 0xF, 0xF, true)); }
; DI void rmw_pair_f32(float* xo_even, const float* xi_even, long ld, bool odd, float v0, float v1, float v2, float v3) {
;   const float sx = odd ? v0 : v2, sy = odd ? v1 : v3;
;   const float rx = dppx1(sx), ry = dppx1(sy);
;   const long off = odd ? 2 * ld : 0;
;   const float2 a0 = *(const float2*)(xi_even + off), a1 = *(const float2*)(xi_even + off + ld);
;   float2 o0, o1;
;   if (odd) { o0 = float2{a0.x + rx, a0.y + v2}; o1 = float2{a1.x + ry, a1.y + v3}; }
;   else     { o0 = float2{a0.x + v0, a0.y + rx}; o1 = float2{a1.x + v1, a1.y + ry}; }
;   *(float2*)(xo_even + off) = o0;
;   *(float2*)(xo_even + off + ld) = o1;
; }
; __global__ void __launch_bounds__(NTHR) fwd_kernel(Params pk) {
;     ...
;             const int b = (pm * 256) >> 13;
; #pragma unroll
;             for (int bj = 0; bj < 2; ++bj)
; #pragma unroll
;               for (int n = 0; n < 2; ++n) {
;                 const int col = pn * 256 + bj * 128 + wc * 32 + n * 16 + fr;
;                 const float gv = gate[(long)b * 9216 + col];
; #pragma unroll
;                 for (int ai = 0; ai < 2; ++ai)
; #pragma unroll
;                   for (int m = 0; m < 4; ++m) {
;                     const long row0 = (long)pm * 256 + ai * 128 + wr * 64 + m * 16 + fq * 4;
;                     const f32x4 a = acc[ai][bj][m][n];
;                     rmw_pair_f32(xo + row0 * DM + (col & ~1), xo + row0 * DM + (col & ~1), DM, col & 1, gv * a[0], gv * a[1], gv * a[2], gv * a[3]);
	v_mov_b64_e32 v[54:55], v[184:185]
	v_mov_b64_e32 v[58:59], v[186:187]
	v_pk_add_f32 v[60:61], v[44:45], v[54:55]
	v_pk_add_f32 v[44:45], v[54:55], v[52:53]
	v_pk_add_f32 v[62:63], v[50:51], v[58:59]
	v_pk_add_f32 v[46:47], v[58:59], v[46:47]
	v_cndmask_b32_e32 v45, v45, v61, vcc
	v_cndmask_b32_e32 v44, v44, v60, vcc
	v_cndmask_b32_e32 v47, v47, v63, vcc
	v_cndmask_b32_e32 v46, v46, v62, vcc
	global_store_dwordx2 v[48:49], v[44:45], off
	global_store_dwordx2 v[56:57], v[46:47], off
	v_lshl_add_u64 v[44:45], v[108:109], 0, v[64:65]
	v_lshl_add_u64 v[44:45], v[44:45], 0, v[128:129]
	v_add_co_u32_e64 v52, s[10:11], s8, v44
	s_nop 0
	v_addc_co_u32_e64 v53, s[10:11], 0, v45, s[10:11]
	v_mul_f32_e32 v49, v42, v66
	v_mul_f32_e32 v46, v41, v66
	v_cndmask_b32_e32 v41, v40, v49, vcc
	v_cndmask_b32_e32 v42, v46, v43, vcc
	s_nop 0
	v_mov_b32_dpp v41, v41 quad_perm:[1,0,3,2] row_mask:0xf bank_mask:0xf bound_ctrl:1
	v_mov_b32_dpp v47, v42 quad_perm:[1,0,3,2] row_mask:0xf bank_mask:0xf bound_ctrl:1
	v_mov_b32_e32 v48, v41
	v_mov_b32_e32 v42, v47
	s_waitcnt vmcnt(46)
	v_mov_b64_e32 v[50:51], v[188:189]
	v_mov_b64_e32 v[54:55], v[190:191]
	v_pk_add_f32 v[56:57], v[40:41], v[50:51]
	v_pk_add_f32 v[40:41], v[50:51], v[48:49]
	v_pk_add_f32 v[58:59], v[46:47], v[54:55]
	v_pk_add_f32 v[42:43], v[54:55], v[42:43]
	v_cndmask_b32_e32 v41, v41, v57, vcc
	v_cndmask_b32_e32 v40, v40, v56, vcc
	v_cndmask_b32_e32 v43, v43, v59, vcc
	v_cndmask_b32_e32 v42, v42, v58, vcc
	global_store_dwordx2 v[44:45], v[40:41], off
	global_store_dwordx2 v[52:53], v[42:43], off
	v_lshl_add_u64 v[40:41], v[104:105], 0, v[64:65]
	v_lshl_add_u64 v[40:41], v[40:41], 0, v[128:129]
	v_add_co_u32_e64 v48, s[10:11], s8, v40
	s_nop 0
	v_addc_co_u32_e64 v49, s[10:11], 0, v41, s[10:11]
	v_mul_f32_e32 v45, v38, v66
	v_mul_f32_e32 v42, v37, v66
	v_cndmask_b32_e32 v37, v36, v45, vcc
	v_cndmask_b32_e32 v38, v42, v39, vcc
	s_nop 0
	v_mov_b32_dpp v37, v37 quad_perm:[1,0,3,2] row_mask:0xf bank_mask:0xf bound_ctrl:1
	v_mov_b32_dpp v43, v38 quad_perm:[1,0,3,2] row_mask:0xf bank_mask:0xf bound_ctrl:1
	v_mov_b32_e32 v44, v37
	v_mov_b32_e32 v38, v43
	s_waitcnt vmcnt(46)
	v_mov_b64_e32 v[46:47], v[192:193]
	v_mov_b64_e32 v[50:51], v[196:197]
	v_pk_add_f32 v[52:53], v[36:37], v[46:47]
	v_pk_add_f32 v[36:37], v[46:47], v[44:45]
	v_pk_add_f32 v[54:55], v[42:43], v[50:51]
	v_pk_add_f32 v[38:39], v[50:51], v[38:39]
	v_cndmask_b32_e32 v37, v37, v53, vcc
	v_cndmask_b32_e32 v36, v36, v52, vcc
	v_cndmask_b32_e32 v39, v39, v55, vcc
	v_cndmask_b32_e32 v38, v38, v54, vcc
	global_store_dwordx2 v[40:41], v[36:37], off
	global_store_dwordx2 v[48:49], v[38:39], off
	v_lshl_add_u64 v[36:37], v[100:101], 0, v[64:65]
	v_lshl_add_u64 v[36:37], v[36:37], 0, v[128:129]
	v_add_co_u32_e64 v44, s[10:11], s8, v36
	s_nop 0
	v_addc_co_u32_e64 v45, s[10:11], 0, v37, s[10:11]
	v_mul_f32_e32 v41, v34, v66
	v_mul_f32_e32 v38, v33, v66
	v_cndmask_b32_e32 v33, v32, v41, vcc
	v_cndmask_b32_e32 v34, v38, v35, vcc
	s_nop 0
	v_mov_b32_dpp v33, v33 quad_perm:[1,0,3,2] row_mask:0xf bank_mask:0xf bound_ctrl:1
	v_mov_b32_dpp v39, v34 quad_perm:[1,0,3,2] row_mask:0xf bank_mask:0xf bound_ctrl:1
	v_mov_b32_e32 v40, v33
	v_mov_b32_e32 v34, v39
	s_waitcnt vmcnt(46)
	v_mov_b64_e32 v[42:43], v[198:199]
	v_mov_b64_e32 v[46:47], v[200:201]
	v_pk_add_f32 v[48:49], v[32:33], v[42:43]
	v_pk_add_f32 v[32:33], v[42:43], v[40:41]
	v_pk_add_f32 v[50:51], v[38:39], v[46:47]
	v_pk_add_f32 v[34:35], v[46:47], v[34:35]
	v_cndmask_b32_e32 v33, v33, v49, vcc
	v_cndmask_b32_e32 v32, v32, v48, vcc
	v_cndmask_b32_e32 v35, v35, v51, vcc
	v_cndmask_b32_e32 v34, v34, v50, vcc
	global_store_dwordx2 v[36:37], v[32:33], off
	global_store_dwordx2 v[44:45], v[34:35], off
	v_bitop3_b32 v32, v132, -2, v252 bitop3:0xc8
	v_ashrrev_i32_e32 v33, 31, v32
	v_lshlrev_b64 v[32:33], 2, v[32:33]
	v_lshl_add_u64 v[36:37], v[130:131], 0, v[32:33]
	v_lshl_add_u64 v[36:37], v[36:37], 0, v[128:129]
	v_add_co_u32_e64 v44, s[10:11], s8, v36
	s_nop 0
	v_addc_co_u32_e64 v45, s[10:11], 0, v37, s[10:11]
	s_waitcnt vmcnt(30)
	v_mov_b64_e32 v[42:43], v[202:203]
	v_mov_b64_e32 v[46:47], v[204:205]
	v_mov_b32_e32 v34, v247
	v_mul_f32_e32 v28, v28, v34
	v_mul_f32_e32 v41, v30, v34
	v_mul_f32_e32 v38, v29, v34
	v_mul_f32_e32 v31, v31, v34
	v_cndmask_b32_e32 v29, v28, v41, vcc
	v_cndmask_b32_e32 v30, v38, v31, vcc
	v_mul_f32_e32 v24, v24, v34
	v_mov_b32_dpp v29, v29 quad_perm:[1,0,3,2] row_mask:0xf bank_mask:0xf bound_ctrl:1
	v_mov_b32_dpp v39, v30 quad_perm:[1,0,3,2] row_mask:0xf bank_mask:0xf bound_ctrl:1
	v_mov_b32_e32 v40, v29
	v_pk_add_f32 v[48:49], v[28:29], v[42:43]
	v_pk_add_f32 v[28:29], v[42:43], v[40:41]
	v_mov_b32_e32 v30, v39
	v_pk_add_f32 v[50:51], v[38:39], v[46:47]
	v_pk_add_f32 v[30:31], v[46:47], v[30:31]
	v_cndmask_b32_e32 v29, v29, v49, vcc
	v_cndmask_b32_e32 v28, v28, v48, vcc
	v_cndmask_b32_e32 v31, v31, v51, vcc
	v_cndmask_b32_e32 v30, v30, v50, vcc
	global_store_dwordx2 v[36:37], v[28:29], off
	global_store_dwordx2 v[44:45], v[30:31], off
	v_lshl_add_u64 v[28:29], v[124:125], 0, v[32:33]
	v_lshl_add_u64 v[28:29], v[28:29], 0, v[128:129]
	v_add_co_u32_e64 v40, s[10:11], s8, v28
	s_nop 0
	v_addc_co_u32_e64 v41, s[10:11], 0, v29, s[10:11]
	v_mul_f32_e32 v37, v26, v34
	v_mul_f32_e32 v30, v25, v34
	v_mul_f32_e32 v27, v27, v34
	v_cndmask_b32_e32 v25, v24, v37, vcc
	v_cndmask_b32_e32 v26, v30, v27, vcc
	v_mul_f32_e32 v20, v20, v34
	v_mov_b32_dpp v25, v25 quad_perm:[1,0,3,2] row_mask:0xf bank_mask:0xf bound_ctrl:1
	v_mov_b32_dpp v31, v26 quad_perm:[1,0,3,2] row_mask:0xf bank_mask:0xf bound_ctrl:1
	v_mov_b32_e32 v36, v25
	v_mov_b32_e32 v26, v31
	v_mul_f32_e32 v23, v23, v34
	v_mul_f32_e32 v16, v16, v34
	v_mul_f32_e32 v19, v19, v34
	v_mul_f32_e32 v12, v12, v34
	v_mul_f32_e32 v15, v15, v34
	v_mul_f32_e32 v8, v8, v34
	v_mul_f32_e32 v11, v11, v34
	v_mul_f32_e32 v4, v4, v34
	v_mul_f32_e32 v7, v7, v34
	v_mul_f32_e32 v0, v0, v34
	v_mul_f32_e32 v3, v3, v34
	s_waitcnt vmcnt(30)
; DI float dppx1(float v) { return __int_as_float(__builtin_amdgcn_update_dpp(0, __float_as_int(v), 0xB1, 0xF, 0xF, true)); }
; DI void rmw_pair_f32(float* xo_even, const float* xi_even, long ld, bool odd, float v0, float v1, float v2, float v3) {
;   const float sx = odd ? v0 : v2, sy = odd ? v1 : v3;
;   const float rx = dppx1(sx), ry = dppx1(sy);
;   const long off = odd ? 2 * ld : 0;
;   const float2 a0 = *(const float2*)(xi_even + off), a1 = *(const float2*)(xi_even + off + ld);
;   float2 o0, o1;
;   if (odd) { o0 = float2{a0.x + rx, a0.y + v2}; o1 = float2{a1.x + ry, a1.y + v3}; }
;   else     { o0 = float2{a0.x + v0, a0.y + rx}; o1 = float2{a1.x + v1, a1.y + ry}; }
;   *(float2*)(xo_even + off) = o0;
;   *(float2*)(xo_even + off + ld) = o1;
; }
; template <class Epi>
; DI void gemm_tile(int ws, char* shmc, const TileDesc& td, Epi& epi, int pm, int pn, bool first, bool has_next, const TileDesc& tdn) {
;     ...
;   asm volatile("s_waitcnt vmcnt(0)" ::: "memory");
;   __syncthreads();
; __global__ void __launch_bounds__(NTHR) fwd_kernel(Params pk) {
;     ...
;             const int b = (pm * 256) >> 13;
; #pragma unroll
;             for (int bj = 0; bj < 2; ++bj)
; #pragma unroll
;               for (int n = 0; n < 2; ++n) {
;                 const int col = pn * 256 + bj * 128 + wc * 32 + n * 16 + fr;
;                 const float gv = gate[(long)b * 9216 + col];
; #pragma unroll
;                 for (int ai = 0; ai < 2; ++ai)
; #pragma unroll
;                   for (int m = 0; m < 4; ++m) {
;                     const long row0 = (long)pm * 256 + ai * 128 + wr * 64 + m * 16 + fq * 4;
;                     const f32x4 a = acc[ai][bj][m][n];
;                     rmw_pair_f32(xo + row0 * DM + (col & ~1), xo + row0 * DM + (col & ~1), DM, col & 1, gv * a[0], gv * a[1], gv * a[2], gv * a[3]);
	v_mov_b64_e32 v[38:39], v[206:207]
	v_mov_b64_e32 v[42:43], v[208:209]
	v_pk_add_f32 v[44:45], v[24:25], v[38:39]
	v_pk_add_f32 v[24:25], v[38:39], v[36:37]
	v_pk_add_f32 v[46:47], v[30:31], v[42:43]
	v_pk_add_f32 v[26:27], v[42:43], v[26:27]
	v_cndmask_b32_e32 v25, v25, v45, vcc
	v_cndmask_b32_e32 v24, v24, v44, vcc
	v_cndmask_b32_e32 v27, v27, v47, vcc
	v_cndmask_b32_e32 v26, v26, v46, vcc
	global_store_dwordx2 v[28:29], v[24:25], off
	global_store_dwordx2 v[40:41], v[26:27], off
	v_lshl_add_u64 v[24:25], v[120:121], 0, v[32:33]
	v_lshl_add_u64 v[24:25], v[24:25], 0, v[128:129]
	v_add_co_u32_e64 v36, s[10:11], s8, v24
	s_nop 0
	v_addc_co_u32_e64 v37, s[10:11], 0, v25, s[10:11]
	v_mul_f32_e32 v29, v22, v34
	v_mul_f32_e32 v26, v21, v34
	v_cndmask_b32_e32 v21, v20, v29, vcc
	v_cndmask_b32_e32 v22, v26, v23, vcc
	s_nop 0
	v_mov_b32_dpp v21, v21 quad_perm:[1,0,3,2] row_mask:0xf bank_mask:0xf bound_ctrl:1
	v_mov_b32_dpp v27, v22 quad_perm:[1,0,3,2] row_mask:0xf bank_mask:0xf bound_ctrl:1
	v_mov_b32_e32 v28, v21
	v_mov_b32_e32 v22, v27
	s_waitcnt vmcnt(30)
	v_mov_b64_e32 v[30:31], v[210:211]
	v_mov_b64_e32 v[38:39], v[212:213]
	v_pk_add_f32 v[40:41], v[20:21], v[30:31]
	v_pk_add_f32 v[20:21], v[30:31], v[28:29]
	v_pk_add_f32 v[42:43], v[26:27], v[38:39]
	v_pk_add_f32 v[22:23], v[38:39], v[22:23]
	v_cndmask_b32_e32 v21, v21, v41, vcc
	v_cndmask_b32_e32 v20, v20, v40, vcc
	v_cndmask_b32_e32 v23, v23, v43, vcc
	v_cndmask_b32_e32 v22, v22, v42, vcc
	global_store_dwordx2 v[24:25], v[20:21], off
	global_store_dwordx2 v[36:37], v[22:23], off
	v_lshl_add_u64 v[20:21], v[116:117], 0, v[32:33]
	v_lshl_add_u64 v[20:21], v[20:21], 0, v[128:129]
	v_add_co_u32_e64 v28, s[10:11], s8, v20
	s_nop 0
	v_addc_co_u32_e64 v29, s[10:11], 0, v21, s[10:11]
	v_mul_f32_e32 v25, v18, v34
	v_mul_f32_e32 v22, v17, v34
	v_cndmask_b32_e32 v17, v16, v25, vcc
	v_cndmask_b32_e32 v18, v22, v19, vcc
	s_nop 0
	v_mov_b32_dpp v17, v17 quad_perm:[1,0,3,2] row_mask:0xf bank_mask:0xf bound_ctrl:1
	v_mov_b32_dpp v23, v18 quad_perm:[1,0,3,2] row_mask:0xf bank_mask:0xf bound_ctrl:1
	v_mov_b32_e32 v24, v17
	v_mov_b32_e32 v18, v23
	s_waitcnt vmcnt(30)
	v_mov_b64_e32 v[26:27], v[214:215]
	v_mov_b64_e32 v[30:31], v[216:217]
	v_pk_add_f32 v[36:37], v[16:17], v[26:27]
	v_pk_add_f32 v[16:17], v[26:27], v[24:25]
	v_pk_add_f32 v[38:39], v[22:23], v[30:31]
	v_pk_add_f32 v[18:19], v[30:31], v[18:19]
	v_cndmask_b32_e32 v17, v17, v37, vcc
	v_cndmask_b32_e32 v16, v16, v36, vcc
	v_cndmask_b32_e32 v19, v19, v39, vcc
	v_cndmask_b32_e32 v18, v18, v38, vcc
	global_store_dwordx2 v[20:21], v[16:17], off
	global_store_dwordx2 v[28:29], v[18:19], off
	v_lshl_add_u64 v[16:17], v[112:113], 0, v[32:33]
	v_lshl_add_u64 v[16:17], v[16:17], 0, v[128:129]
	v_add_co_u32_e64 v24, s[10:11], s8, v16
	s_nop 0
	v_addc_co_u32_e64 v25, s[10:11], 0, v17, s[10:11]
	v_mul_f32_e32 v21, v14, v34
	v_mul_f32_e32 v18, v13, v34
	v_cndmask_b32_e32 v13, v12, v21, vcc
	v_cndmask_b32_e32 v14, v18, v15, vcc
	s_nop 0
	v_mov_b32_dpp v13, v13 quad_perm:[1,0,3,2] row_mask:0xf bank_mask:0xf bound_ctrl:1
	v_mov_b32_dpp v19, v14 quad_perm:[1,0,3,2] row_mask:0xf bank_mask:0xf bound_ctrl:1
	v_mov_b32_e32 v20, v13
	v_mov_b32_e32 v14, v19
	s_waitcnt vmcnt(30)
	v_mov_b64_e32 v[22:23], v[218:219]
	v_mov_b64_e32 v[26:27], v[220:221]
	v_pk_add_f32 v[28:29], v[12:13], v[22:23]
	v_pk_add_f32 v[12:13], v[22:23], v[20:21]
	v_pk_add_f32 v[30:31], v[18:19], v[26:27]
	v_pk_add_f32 v[14:15], v[26:27], v[14:15]
	v_cndmask_b32_e32 v13, v13, v29, vcc
	v_cndmask_b32_e32 v12, v12, v28, vcc
	v_cndmask_b32_e32 v15, v15, v31, vcc
	v_cndmask_b32_e32 v14, v14, v30, vcc
	global_store_dwordx2 v[16:17], v[12:13], off
	global_store_dwordx2 v[24:25], v[14:15], off
	v_lshl_add_u64 v[12:13], v[108:109], 0, v[32:33]
	v_lshl_add_u64 v[12:13], v[12:13], 0, v[128:129]
	v_add_co_u32_e64 v20, s[10:11], s8, v12
	s_nop 0
	v_addc_co_u32_e64 v21, s[10:11], 0, v13, s[10:11]
	v_mul_f32_e32 v17, v10, v34
	v_mul_f32_e32 v14, v9, v34
	v_cndmask_b32_e32 v9, v8, v17, vcc
	v_cndmask_b32_e32 v10, v14, v11, vcc
	s_nop 0
	v_mov_b32_dpp v9, v9 quad_perm:[1,0,3,2] row_mask:0xf bank_mask:0xf bound_ctrl:1
	v_mov_b32_dpp v15, v10 quad_perm:[1,0,3,2] row_mask:0xf bank_mask:0xf bound_ctrl:1
	v_mov_b32_e32 v16, v9
	v_mov_b32_e32 v10, v15
	s_waitcnt vmcnt(30)
	v_mov_b64_e32 v[18:19], v[222:223]
	v_mov_b64_e32 v[22:23], v[224:225]
	v_pk_add_f32 v[24:25], v[8:9], v[18:19]
	v_pk_add_f32 v[8:9], v[18:19], v[16:17]
	v_pk_add_f32 v[26:27], v[14:15], v[22:23]
	v_pk_add_f32 v[10:11], v[22:23], v[10:11]
	v_cndmask_b32_e32 v9, v9, v25, vcc
	v_cndmask_b32_e32 v8, v8, v24, vcc
	v_cndmask_b32_e32 v11, v11, v27, vcc
	v_cndmask_b32_e32 v10, v10, v26, vcc
	global_store_dwordx2 v[12:13], v[8:9], off
	global_store_dwordx2 v[20:21], v[10:11], off
	v_lshl_add_u64 v[8:9], v[104:105], 0, v[32:33]
	v_lshl_add_u64 v[8:9], v[8:9], 0, v[128:129]
	v_add_co_u32_e64 v16, s[10:11], s8, v8
	s_nop 0
	v_addc_co_u32_e64 v17, s[10:11], 0, v9, s[10:11]
	v_mul_f32_e32 v13, v6, v34
	v_mul_f32_e32 v10, v5, v34
	v_cndmask_b32_e32 v5, v4, v13, vcc
	v_cndmask_b32_e32 v6, v10, v7, vcc
	s_nop 0
	v_mov_b32_dpp v5, v5 quad_perm:[1,0,3,2] row_mask:0xf bank_mask:0xf bound_ctrl:1
	v_mov_b32_dpp v11, v6 quad_perm:[1,0,3,2] row_mask:0xf bank_mask:0xf bound_ctrl:1
	v_mov_b32_e32 v12, v5
	v_mov_b32_e32 v6, v11
	s_waitcnt vmcnt(30)
	v_mov_b64_e32 v[14:15], v[226:227]
	v_mov_b64_e32 v[18:19], v[228:229]
	v_pk_add_f32 v[20:21], v[4:5], v[14:15]
	v_pk_add_f32 v[4:5], v[14:15], v[12:13]
	v_pk_add_f32 v[22:23], v[10:11], v[18:19]
	v_pk_add_f32 v[6:7], v[18:19], v[6:7]
	v_cndmask_b32_e32 v5, v5, v21, vcc
	v_cndmask_b32_e32 v4, v4, v20, vcc
	v_cndmask_b32_e32 v7, v7, v23, vcc
	v_cndmask_b32_e32 v6, v6, v22, vcc
	global_store_dwordx2 v[8:9], v[4:5], off
	global_store_dwordx2 v[16:17], v[6:7], off
	v_lshl_add_u64 v[4:5], v[100:101], 0, v[32:33]
	v_lshl_add_u64 v[4:5], v[4:5], 0, v[128:129]
	v_add_co_u32_e64 v12, s[10:11], s8, v4
	s_nop 0
	v_addc_co_u32_e64 v13, s[10:11], 0, v5, s[10:11]
	v_mul_f32_e32 v9, v2, v34
	v_mul_f32_e32 v6, v1, v34
	v_cndmask_b32_e32 v1, v0, v9, vcc
	v_cndmask_b32_e32 v2, v6, v3, vcc
	s_mov_b32 s10, s64
	v_mov_b32_dpp v1, v1 quad_perm:[1,0,3,2] row_mask:0xf bank_mask:0xf bound_ctrl:1
	v_mov_b32_dpp v7, v2 quad_perm:[1,0,3,2] row_mask:0xf bank_mask:0xf bound_ctrl:1
	v_mov_b32_e32 v8, v1
	v_mov_b32_e32 v2, v7
	s_waitcnt vmcnt(30)
	v_mov_b64_e32 v[10:11], v[230:231]
	v_mov_b64_e32 v[14:15], v[232:233]
	v_pk_add_f32 v[16:17], v[0:1], v[10:11]
	v_pk_add_f32 v[0:1], v[10:11], v[8:9]
	v_pk_add_f32 v[18:19], v[6:7], v[14:15]
	v_pk_add_f32 v[2:3], v[14:15], v[2:3]
	v_cndmask_b32_e32 v1, v1, v17, vcc
	v_cndmask_b32_e32 v0, v0, v16, vcc
	v_cndmask_b32_e32 v3, v3, v19, vcc
	v_cndmask_b32_e32 v2, v2, v18, vcc
	global_store_dwordx2 v[4:5], v[0:1], off
	global_store_dwordx2 v[12:13], v[2:3], off
	s_waitcnt vmcnt(0)
	s_andn2_b64 vcc, exec, s[72:73]
	s_waitcnt lgkmcnt(0)
	s_barrier
	s_cbranch_vccz .LBB0_876

; DI float dppx1(float v) { return __int_as_float(__builtin_amdgcn_update_dpp(0, __float_as_int(v), 0xB1, 0xF, 0xF, true)); }
; DI void rmw_pair_f32(float* xo_even, const float* xi_even, long ld, bool odd, float v0, float v1, float v2, float v3) {
;   const float sx = odd ? v0 : v2, sy = odd ? v1 : v3;
;   const float rx = dppx1(sx), ry = dppx1(sy);
;   const long off = odd ? 2 * ld : 0;
;   const float2 a0 = *(const float2*)(xi_even + off), a1 = *(const float2*)(xi_even + off + ld);
;   float2 o0, o1;
;   if (odd) { o0 = float2{a0.x + rx, a0.y + v2}; o1 = float2{a1.x + ry, a1.y + v3}; }
;   else     { o0 = float2{a0.x + v0, a0.y + rx}; o1 = float2{a1.x + v1, a1.y + ry}; }
;   *(float2*)(xo_even + off) = o0;
;   *(float2*)(xo_even + off + ld) = o1;
; }
; __global__ void __launch_bounds__(NTHR) fwd_kernel(Params pk) {
;     ...
;           const int b = (pm * 256) >> 13;
; #pragma unroll
;           for (int bj = 0; bj < 2; ++bj)
; #pragma unroll
;             for (int n = 0; n < 2; ++n) {
;               const int col = pn * 256 + bj * 128 + wc * 32 + n * 16 + fr;
;               const float gv = 0.5f * gate[(long)b * 9216 + col];
; #pragma unroll
;               for (int ai = 0; ai < 2; ++ai)
; #pragma unroll
;                 for (int m = 0; m < 4; ++m) {
;                   const long row0 = (long)pm * 256 + ai * 128 + wr * 64 + m * 16 + fq * 4;
;                   const f32x4 a = acc[ai][bj][m][n];
;                   rmw_pair_f32(xo + row0 * DM + (col & ~1), xin + row0 * DM + (col & ~1), DM, col & 1, gv * a[0], gv * a[1], gv * a[2], gv * a[3]);
;                   asm volatile("" ::: "memory");
;                 }
.LBB0_1004:
	s_ashr_i32 s4, s10, 5
	s_lshl_b32 s3, s3, 8
	s_ashr_i32 s11, s10, 31
	v_lshl_or_b32 v138, v150, 5, s3
	s_mul_hi_i32 s3, s4, 0x9000
	s_mul_i32 s64, s4, 0x9000
	s_lshl_b64 s[4:5], s[10:11], 8
	v_ashrrev_i32_e32 v133, 31, v132
	v_or_b32_e32 v134, v138, v144
	v_lshl_add_u64 v[130:131], s[4:5], 0, v[132:133]
	s_add_u32 s4, s8, s64
	v_ashrrev_i32_e32 v135, 31, v134
	s_addc_u32 s5, s9, s3
	v_lshl_add_u64 v[136:137], v[134:135], 2, s[4:5]
	v_lshl_or_b32 v130, v149, 2, v130
	global_load_dword v244, v[136:137], off
	global_load_dword v245, v[136:137], off offset:64
	global_load_dword v246, v[136:137], off offset:512
	global_load_dword v247, v[136:137], off offset:576
	v_bitop3_b32 v132, v138, s75, v144 bitop3:0xc8
	v_ashrrev_i32_e32 v133, 31, v132
	v_lshlrev_b64 v[130:131], 12, v[130:131]
	v_bfe_i32 v128, v142, 0, 1
	v_lshl_add_u64 v[130:131], s[12:13], 0, v[130:131]
	v_lshlrev_b64 v[138:139], 2, v[132:133]
	v_and_b32_e32 v128, 0x2000, v128
	v_lshl_add_u64 v[132:133], v[130:131], 0, v[138:139]
	v_lshl_add_u64 v[144:145], v[132:133], 0, v[128:129]
	v_add_co_u32_e32 v146, vcc, s73, v144
	v_and_b32_e32 v155, 1, v142
	s_nop 0
	v_addc_co_u32_e32 v147, vcc, 0, v145, vcc
	v_mov_b64_e32 v[248:249], v[144:145]
	global_load_dwordx2 v[168:169], v[248:249], off
	s_mov_b32 s98, 0x1000
	s_mov_b32 s99, 0
	v_lshl_add_u64 v[250:251], v[248:249], 0, s[98:99]
	global_load_dwordx2 v[170:171], v[250:251], off
	s_mov_b32 s98, 0x10000
	s_mov_b32 s99, 0
	v_lshl_add_u64 v[250:251], v[248:249], 0, s[98:99]
	global_load_dwordx2 v[172:173], v[250:251], off
	s_mov_b32 s98, 0x11000
	s_mov_b32 s99, 0
	v_lshl_add_u64 v[250:251], v[248:249], 0, s[98:99]
	global_load_dwordx2 v[174:175], v[250:251], off
	s_mov_b32 s98, 0x20000
	s_mov_b32 s99, 0
	v_lshl_add_u64 v[250:251], v[248:249], 0, s[98:99]
	global_load_dwordx2 v[176:177], v[250:251], off
	s_mov_b32 s98, 0x21000
	s_mov_b32 s99, 0
	v_lshl_add_u64 v[250:251], v[248:249], 0, s[98:99]
	global_load_dwordx2 v[178:179], v[250:251], off
	s_mov_b32 s98, 0x30000
	s_mov_b32 s99, 0
	v_lshl_add_u64 v[250:251], v[248:249], 0, s[98:99]
	global_load_dwordx2 v[180:181], v[250:251], off
	s_mov_b32 s98, 0x31000
	s_mov_b32 s99, 0
	v_lshl_add_u64 v[250:251], v[248:249], 0, s[98:99]
	global_load_dwordx2 v[182:183], v[250:251], off
	s_mov_b32 s98, 0x80000
	s_mov_b32 s99, 0
	v_lshl_add_u64 v[250:251], v[248:249], 0, s[98:99]
	global_load_dwordx2 v[184:185], v[250:251], off
	s_mov_b32 s98, 0x81000
	s_mov_b32 s99, 0
	v_lshl_add_u64 v[250:251], v[248:249], 0, s[98:99]
	global_load_dwordx2 v[186:187], v[250:251], off
	s_mov_b32 s98, 0x90000
	s_mov_b32 s99, 0
	v_lshl_add_u64 v[250:251], v[248:249], 0, s[98:99]
	global_load_dwordx2 v[188:189], v[250:251], off
	s_mov_b32 s98, 0x91000
	s_mov_b32 s99, 0
	v_lshl_add_u64 v[250:251], v[248:249], 0, s[98:99]
	global_load_dwordx2 v[190:191], v[250:251], off
	s_mov_b32 s98, 0xa0000
	s_mov_b32 s99, 0
	v_lshl_add_u64 v[250:251], v[248:249], 0, s[98:99]
	global_load_dwordx2 v[192:193], v[250:251], off
	s_mov_b32 s98, 0xa1000
	s_mov_b32 s99, 0
	v_lshl_add_u64 v[250:251], v[248:249], 0, s[98:99]
	global_load_dwordx2 v[196:197], v[250:251], off
	s_mov_b32 s98, 0xb0000
	s_mov_b32 s99, 0
	v_lshl_add_u64 v[250:251], v[248:249], 0, s[98:99]
	global_load_dwordx2 v[198:199], v[250:251], off
	s_mov_b32 s98, 0xb1000
	s_mov_b32 s99, 0
	v_lshl_add_u64 v[250:251], v[248:249], 0, s[98:99]
	global_load_dwordx2 v[200:201], v[250:251], off
	s_mov_b32 s98, 0x40
	s_mov_b32 s99, 0
	v_lshl_add_u64 v[250:251], v[248:249], 0, s[98:99]
	global_load_dwordx2 v[202:203], v[250:251], off
	s_mov_b32 s98, 0x1040
	s_mov_b32 s99, 0
	v_lshl_add_u64 v[250:251], v[248:249], 0, s[98:99]
	global_load_dwordx2 v[204:205], v[250:251], off
	s_mov_b32 s98, 0x10040
	s_mov_b32 s99, 0
	v_lshl_add_u64 v[250:251], v[248:249], 0, s[98:99]
	global_load_dwordx2 v[206:207], v[250:251], off
	s_mov_b32 s98, 0x11040
	s_mov_b32 s99, 0
	v_lshl_add_u64 v[250:251], v[248:249], 0, s[98:99]
	global_load_dwordx2 v[208:209], v[250:251], off
	s_mov_b32 s98, 0x20040
	s_mov_b32 s99, 0
	v_lshl_add_u64 v[250:251], v[248:249], 0, s[98:99]
	global_load_dwordx2 v[210:211], v[250:251], off
	s_mov_b32 s98, 0x21040
	s_mov_b32 s99, 0
	v_lshl_add_u64 v[250:251], v[248:249], 0, s[98:99]
	global_load_dwordx2 v[212:213], v[250:251], off
	s_mov_b32 s98, 0x30040
	s_mov_b32 s99, 0
	v_lshl_add_u64 v[250:251], v[248:249], 0, s[98:99]
	global_load_dwordx2 v[214:215], v[250:251], off
	s_mov_b32 s98, 0x31040
	s_mov_b32 s99, 0
	v_lshl_add_u64 v[250:251], v[248:249], 0, s[98:99]
	global_load_dwordx2 v[216:217], v[250:251], off
	s_mov_b32 s98, 0x80040
	s_mov_b32 s99, 0
	v_lshl_add_u64 v[250:251], v[248:249], 0, s[98:99]
	global_load_dwordx2 v[218:219], v[250:251], off
	s_mov_b32 s98, 0x81040
	s_mov_b32 s99, 0
	v_lshl_add_u64 v[250:251], v[248:249], 0, s[98:99]
	global_load_dwordx2 v[220:221], v[250:251], off
	s_mov_b32 s98, 0x90040
	s_mov_b32 s99, 0
	v_lshl_add_u64 v[250:251], v[248:249], 0, s[98:99]
	global_load_dwordx2 v[222:223], v[250:251], off
	s_mov_b32 s98, 0x91040
	s_mov_b32 s99, 0
	v_lshl_add_u64 v[250:251], v[248:249], 0, s[98:99]
	global_load_dwordx2 v[224:225], v[250:251], off
	s_mov_b32 s98, 0xa0040
	s_mov_b32 s99, 0
	v_lshl_add_u64 v[250:251], v[248:249], 0, s[98:99]
	global_load_dwordx2 v[226:227], v[250:251], off
	s_mov_b32 s98, 0xa1040
	s_mov_b32 s99, 0
	v_lshl_add_u64 v[250:251], v[248:249], 0, s[98:99]
	global_load_dwordx2 v[228:229], v[250:251], off
	s_mov_b32 s98, 0xb0040
	s_mov_b32 s99, 0
	v_lshl_add_u64 v[250:251], v[248:249], 0, s[98:99]
	global_load_dwordx2 v[230:231], v[250:251], off
	s_mov_b32 s98, 0xb1040
	s_mov_b32 s99, 0
	v_lshl_add_u64 v[250:251], v[248:249], 0, s[98:99]
	global_load_dwordx2 v[232:233], v[250:251], off
	v_cmp_eq_u32_e64 s[10:11], 0, v155
	v_lshl_add_u64 v[132:133], v[130:131], 0, s[46:47]
	v_lshl_add_u64 v[142:143], v[132:133], 0, v[138:139]
	v_lshl_add_u64 v[142:143], v[142:143], 0, v[128:129]
	v_add_co_u32_e32 v152, vcc, s73, v142
	s_mov_b64 s[70:71], 0
	s_nop 0
	v_addc_co_u32_e32 v153, vcc, 0, v143, vcc
	s_mov_b32 s3, s81
	s_mov_b64 s[68:69], s[60:61]
	s_mov_b64 s[66:67], s[58:59]
	s_waitcnt vmcnt(30)
; DI float dppx1(float v) { return __int_as_float(__builtin_amdgcn_update_dpp(0, __float_as_int(v), 0xB1, 0xF, 0xF, true)); }
; DI void rmw_pair_f32(float* xo_even, const float* xi_even, long ld, bool odd, float v0, float v1, float v2, float v3) {
;   const float sx = odd ? v0 : v2, sy = odd ? v1 : v3;
;   const float rx = dppx1(sx), ry = dppx1(sy);
;   const long off = odd ? 2 * ld : 0;
;   const float2 a0 = *(const float2*)(xi_even + off), a1 = *(const float2*)(xi_even + off + ld);
;   float2 o0, o1;
;   if (odd) { o0 = float2{a0.x + rx, a0.y + v2}; o1 = float2{a1.x + ry, a1.y + v3}; }
;   else     { o0 = float2{a0.x + v0, a0.y + rx}; o1 = float2{a1.x + v1, a1.y + ry}; }
;   *(float2*)(xo_even + off) = o0;
;   *(float2*)(xo_even + off + ld) = o1;
; }
; __global__ void __launch_bounds__(NTHR) fwd_kernel(Params pk) {
;     ...
;           for (int bj = 0; bj < 2; ++bj)
; #pragma unroll
;             for (int n = 0; n < 2; ++n) {
;               const int col = pn * 256 + bj * 128 + wc * 32 + n * 16 + fr;
;               const float gv = 0.5f * gate[(long)b * 9216 + col];
; #pragma unroll
;               for (int ai = 0; ai < 2; ++ai)
; #pragma unroll
;                 for (int m = 0; m < 4; ++m) {
;                   const long row0 = (long)pm * 256 + ai * 128 + wr * 64 + m * 16 + fq * 4;
;                   const f32x4 a = acc[ai][bj][m][n];
;                   rmw_pair_f32(xo + row0 * DM + (col & ~1), xin + row0 * DM + (col & ~1), DM, col & 1, gv * a[0], gv * a[1], gv * a[2], gv * a[3]);
;                   asm volatile("" ::: "memory");
;                 }
	v_mov_b64_e32 v[148:149], v[168:169]
	v_mov_b64_e32 v[150:151], v[170:171]
	v_mov_b32_e32 v135, v244
	v_mul_f32_e32 v135, 0.5, v135
	v_mul_f32_e32 v124, v124, v135
	v_mul_f32_e32 v157, v126, v135
	v_mul_f32_e32 v154, v125, v135
	v_mul_f32_e32 v127, v127, v135
	v_cndmask_b32_e64 v125, v124, v157, s[10:11]
	v_cndmask_b32_e64 v126, v154, v127, s[10:11]
	v_mul_f32_e32 v120, v120, v135
	v_mov_b32_dpp v125, v125 quad_perm:[1,0,3,2] row_mask:0xf bank_mask:0xf bound_ctrl:1
	v_mov_b32_dpp v155, v126 quad_perm:[1,0,3,2] row_mask:0xf bank_mask:0xf bound_ctrl:1
	v_mov_b32_e32 v156, v125
	v_mov_b32_e32 v126, v155
	v_mul_f32_e32 v123, v123, v135
	v_mul_f32_e32 v116, v116, v135
	v_pk_add_f32 v[158:159], v[124:125], v[148:149]
	v_pk_add_f32 v[124:125], v[148:149], v[156:157]
	v_pk_add_f32 v[160:161], v[154:155], v[150:151]
	v_pk_add_f32 v[126:127], v[150:151], v[126:127]
	v_cndmask_b32_e64 v125, v125, v159, s[10:11]
	v_cndmask_b32_e64 v124, v124, v158, s[10:11]
	v_cndmask_b32_e64 v127, v127, v161, s[10:11]
	v_cndmask_b32_e64 v126, v126, v160, s[10:11]
	global_store_dwordx2 v[144:145], v[124:125], off
	global_store_dwordx2 v[146:147], v[126:127], off
	v_mul_f32_e32 v155, v122, v135
	v_mul_f32_e32 v150, v121, v135
	v_cndmask_b32_e64 v121, v120, v155, s[10:11]
	v_cndmask_b32_e64 v122, v150, v123, s[10:11]
	v_lshl_add_u64 v[124:125], v[130:131], 0, s[48:49]
	v_mov_b32_dpp v121, v121 quad_perm:[1,0,3,2] row_mask:0xf bank_mask:0xf bound_ctrl:1
	v_mov_b32_dpp v151, v122 quad_perm:[1,0,3,2] row_mask:0xf bank_mask:0xf bound_ctrl:1
	v_mov_b32_e32 v154, v121
	v_mov_b32_e32 v122, v151
	v_lshl_add_u64 v[146:147], v[124:125], 0, v[138:139]
	v_lshl_add_u64 v[146:147], v[146:147], 0, v[128:129]
	v_add_co_u32_e32 v148, vcc, s73, v146
	v_mul_f32_e32 v119, v119, v135
	s_nop 0
	v_addc_co_u32_e32 v149, vcc, 0, v147, vcc
	v_mul_f32_e32 v112, v112, v135
	v_mul_f32_e32 v115, v115, v135
	v_mul_f32_e32 v108, v108, v135
	v_mul_f32_e32 v111, v111, v135
	v_mul_f32_e32 v104, v104, v135
	v_mul_f32_e32 v107, v107, v135
	v_mul_f32_e32 v100, v100, v135
	v_mul_f32_e32 v103, v103, v135
	v_mul_f32_e32 v96, v96, v135
	v_mul_f32_e32 v99, v99, v135
	s_waitcnt vmcnt(30)
	v_mov_b64_e32 v[126:127], v[172:173]
	v_mov_b64_e32 v[144:145], v[174:175]
	v_pk_add_f32 v[120:121], v[120:121], v[126:127]
	v_pk_add_f32 v[126:127], v[126:127], v[154:155]
	v_pk_add_f32 v[150:151], v[150:151], v[144:145]
	v_pk_add_f32 v[122:123], v[144:145], v[122:123]
	v_cndmask_b32_e64 v121, v127, v121, s[10:11]
	v_cndmask_b32_e64 v120, v126, v120, s[10:11]
	v_cndmask_b32_e64 v123, v123, v151, s[10:11]
	v_cndmask_b32_e64 v122, v122, v150, s[10:11]
	global_store_dwordx2 v[142:143], v[120:121], off
	global_store_dwordx2 v[152:153], v[122:123], off
	v_mul_f32_e32 v153, v118, v135
	v_mul_f32_e32 v150, v117, v135
	v_cndmask_b32_e64 v117, v116, v153, s[10:11]
	v_cndmask_b32_e64 v118, v150, v119, s[10:11]
	v_lshl_add_u64 v[120:121], v[130:131], 0, s[50:51]
	v_mov_b32_dpp v117, v117 quad_perm:[1,0,3,2] row_mask:0xf bank_mask:0xf bound_ctrl:1
	v_mov_b32_dpp v151, v118 quad_perm:[1,0,3,2] row_mask:0xf bank_mask:0xf bound_ctrl:1
	v_mov_b32_e32 v152, v117
	v_mov_b32_e32 v118, v151
	v_lshl_add_u64 v[142:143], v[120:121], 0, v[138:139]
	v_lshl_add_u64 v[142:143], v[142:143], 0, v[128:129]
	v_add_co_u32_e32 v144, vcc, s73, v142
	s_waitcnt vmcnt(30)
	v_mov_b64_e32 v[122:123], v[176:177]
	v_mov_b64_e32 v[126:127], v[178:179]
	v_pk_add_f32 v[116:117], v[116:117], v[122:123]
	v_pk_add_f32 v[122:123], v[122:123], v[152:153]
	v_pk_add_f32 v[150:151], v[150:151], v[126:127]
	v_pk_add_f32 v[118:119], v[126:127], v[118:119]
	v_cndmask_b32_e64 v117, v123, v117, s[10:11]
	v_cndmask_b32_e64 v116, v122, v116, s[10:11]
	v_cndmask_b32_e64 v119, v119, v151, s[10:11]
	v_cndmask_b32_e64 v118, v118, v150, s[10:11]
	global_store_dwordx2 v[146:147], v[116:117], off
	global_store_dwordx2 v[148:149], v[118:119], off
	v_addc_co_u32_e32 v145, vcc, 0, v143, vcc
	v_mul_f32_e32 v151, v114, v135
	v_mul_f32_e32 v148, v113, v135
	v_cndmask_b32_e64 v113, v112, v151, s[10:11]
	v_cndmask_b32_e64 v114, v148, v115, s[10:11]
	v_lshl_add_u64 v[116:117], v[130:131], 0, s[52:53]
	v_mov_b32_dpp v113, v113 quad_perm:[1,0,3,2] row_mask:0xf bank_mask:0xf bound_ctrl:1
	v_mov_b32_dpp v149, v114 quad_perm:[1,0,3,2] row_mask:0xf bank_mask:0xf bound_ctrl:1
	v_mov_b32_e32 v150, v113
	v_mov_b32_e32 v114, v149
	v_lshl_add_u64 v[126:127], v[116:117], 0, v[138:139]
	v_lshl_add_u64 v[126:127], v[126:127], 0, v[128:129]
	v_add_co_u32_e32 v146, vcc, s73, v126
	s_waitcnt vmcnt(30)
	v_mov_b64_e32 v[118:119], v[180:181]
	v_mov_b64_e32 v[122:123], v[182:183]
	v_pk_add_f32 v[112:113], v[112:113], v[118:119]
	v_pk_add_f32 v[118:119], v[118:119], v[150:151]
	v_pk_add_f32 v[148:149], v[148:149], v[122:123]
	v_pk_add_f32 v[114:115], v[122:123], v[114:115]
	v_cndmask_b32_e64 v113, v119, v113, s[10:11]
	v_cndmask_b32_e64 v112, v118, v112, s[10:11]
	v_cndmask_b32_e64 v115, v115, v149, s[10:11]
	v_cndmask_b32_e64 v114, v114, v148, s[10:11]
	global_store_dwordx2 v[142:143], v[112:113], off
	global_store_dwordx2 v[144:145], v[114:115], off
	v_addc_co_u32_e32 v147, vcc, 0, v127, vcc
	v_mul_f32_e32 v149, v110, v135
	v_mul_f32_e32 v144, v109, v135
	v_cndmask_b32_e64 v109, v108, v149, s[10:11]
	v_cndmask_b32_e64 v110, v144, v111, s[10:11]
	v_lshl_add_u64 v[112:113], v[130:131], 0, s[54:55]
	v_mov_b32_dpp v109, v109 quad_perm:[1,0,3,2] row_mask:0xf bank_mask:0xf bound_ctrl:1
	v_mov_b32_dpp v145, v110 quad_perm:[1,0,3,2] row_mask:0xf bank_mask:0xf bound_ctrl:1
	v_mov_b32_e32 v148, v109
	v_mov_b32_e32 v110, v145
	v_lshl_add_u64 v[122:123], v[112:113], 0, v[138:139]
	v_lshl_add_u64 v[122:123], v[122:123], 0, v[128:129]
	v_add_co_u32_e32 v142, vcc, s73, v122
	s_waitcnt vmcnt(30)
; DI float dppx1(float v) { return __int_as_float(__builtin_amdgcn_update_dpp(0, __float_as_int(v), 0xB1, 0xF, 0xF, true)); }
; DI void rmw_pair_f32(float* xo_even, const float* xi_even, long ld, bool odd, float v0, float v1, float v2, float v3) {
;   const float sx = odd ? v0 : v2, sy = odd ? v1 : v3;
;   const float rx = dppx1(sx), ry = dppx1(sy);
;   const long off = odd ? 2 * ld : 0;
;   const float2 a0 = *(const float2*)(xi_even + off), a1 = *(const float2*)(xi_even + off + ld);
;   float2 o0, o1;
;   if (odd) { o0 = float2{a0.x + rx, a0.y + v2}; o1 = float2{a1.x + ry, a1.y + v3}; }
;   else     { o0 = float2{a0.x + v0, a0.y + rx}; o1 = float2{a1.x + v1, a1.y + ry}; }
;   *(float2*)(xo_even + off) = o0;
;   *(float2*)(xo_even + off + ld) = o1;
; }
; __global__ void __launch_bounds__(NTHR) fwd_kernel(Params pk) {
;     ...
;           for (int bj = 0; bj < 2; ++bj)
; #pragma unroll
;             for (int n = 0; n < 2; ++n) {
;               const int col = pn * 256 + bj * 128 + wc * 32 + n * 16 + fr;
;               const float gv = 0.5f * gate[(long)b * 9216 + col];
; #pragma unroll
;               for (int ai = 0; ai < 2; ++ai)
; #pragma unroll
;                 for (int m = 0; m < 4; ++m) {
;                   const long row0 = (long)pm * 256 + ai * 128 + wr * 64 + m * 16 + fq * 4;
;                   const f32x4 a = acc[ai][bj][m][n];
;                   rmw_pair_f32(xo + row0 * DM + (col & ~1), xin + row0 * DM + (col & ~1), DM, col & 1, gv * a[0], gv * a[1], gv * a[2], gv * a[3]);
;                   asm volatile("" ::: "memory");
;                 }
	v_mov_b64_e32 v[114:115], v[184:185]
	v_mov_b64_e32 v[118:119], v[186:187]
	v_pk_add_f32 v[108:109], v[108:109], v[114:115]
	v_pk_add_f32 v[114:115], v[114:115], v[148:149]
	v_pk_add_f32 v[144:145], v[144:145], v[118:119]
	v_pk_add_f32 v[110:111], v[118:119], v[110:111]
	v_cndmask_b32_e64 v109, v115, v109, s[10:11]
	v_cndmask_b32_e64 v108, v114, v108, s[10:11]
	v_cndmask_b32_e64 v111, v111, v145, s[10:11]
	v_cndmask_b32_e64 v110, v110, v144, s[10:11]
	global_store_dwordx2 v[126:127], v[108:109], off
	global_store_dwordx2 v[146:147], v[110:111], off
	v_addc_co_u32_e32 v143, vcc, 0, v123, vcc
	v_mul_f32_e32 v147, v106, v135
	v_mul_f32_e32 v144, v105, v135
	v_cndmask_b32_e64 v105, v104, v147, s[10:11]
	v_cndmask_b32_e64 v106, v144, v107, s[10:11]
	v_lshl_add_u64 v[108:109], v[130:131], 0, s[56:57]
	v_mov_b32_dpp v105, v105 quad_perm:[1,0,3,2] row_mask:0xf bank_mask:0xf bound_ctrl:1
	v_mov_b32_dpp v145, v106 quad_perm:[1,0,3,2] row_mask:0xf bank_mask:0xf bound_ctrl:1
	v_mov_b32_e32 v146, v105
	v_mov_b32_e32 v106, v145
	v_lshl_add_u64 v[118:119], v[108:109], 0, v[138:139]
	v_lshl_add_u64 v[118:119], v[118:119], 0, v[128:129]
	v_add_co_u32_e32 v126, vcc, s73, v118
	s_waitcnt vmcnt(30)
	v_mov_b64_e32 v[110:111], v[188:189]
	v_mov_b64_e32 v[114:115], v[190:191]
	v_pk_add_f32 v[104:105], v[104:105], v[110:111]
	v_pk_add_f32 v[110:111], v[110:111], v[146:147]
	v_pk_add_f32 v[144:145], v[144:145], v[114:115]
	v_pk_add_f32 v[106:107], v[114:115], v[106:107]
	v_cndmask_b32_e64 v105, v111, v105, s[10:11]
	v_cndmask_b32_e64 v104, v110, v104, s[10:11]
	v_cndmask_b32_e64 v107, v107, v145, s[10:11]
	v_cndmask_b32_e64 v106, v106, v144, s[10:11]
	global_store_dwordx2 v[122:123], v[104:105], off
	global_store_dwordx2 v[142:143], v[106:107], off
	v_addc_co_u32_e32 v127, vcc, 0, v119, vcc
	v_lshl_add_u64 v[104:105], v[130:131], 0, s[18:19]
	v_mul_f32_e32 v143, v102, v135
	v_lshl_add_u64 v[114:115], v[104:105], 0, v[138:139]
	v_mul_f32_e32 v138, v101, v135
	v_cndmask_b32_e64 v101, v100, v143, s[10:11]
	v_cndmask_b32_e64 v102, v138, v103, s[10:11]
	v_lshl_add_u64 v[114:115], v[114:115], 0, v[128:129]
	v_mov_b32_dpp v101, v101 quad_perm:[1,0,3,2] row_mask:0xf bank_mask:0xf bound_ctrl:1
	v_mov_b32_dpp v139, v102 quad_perm:[1,0,3,2] row_mask:0xf bank_mask:0xf bound_ctrl:1
	v_mov_b32_e32 v142, v101
	v_mov_b32_e32 v102, v139
	v_add_co_u32_e32 v122, vcc, s73, v114
	s_waitcnt vmcnt(30)
	v_mov_b64_e32 v[106:107], v[192:193]
	v_mov_b64_e32 v[110:111], v[196:197]
	v_pk_add_f32 v[100:101], v[100:101], v[106:107]
	v_pk_add_f32 v[106:107], v[106:107], v[142:143]
	v_pk_add_f32 v[138:139], v[138:139], v[110:111]
	v_pk_add_f32 v[102:103], v[110:111], v[102:103]
	v_cndmask_b32_e64 v101, v107, v101, s[10:11]
	v_cndmask_b32_e64 v100, v106, v100, s[10:11]
	v_cndmask_b32_e64 v103, v103, v139, s[10:11]
	v_cndmask_b32_e64 v102, v102, v138, s[10:11]
	global_store_dwordx2 v[118:119], v[100:101], off
	global_store_dwordx2 v[126:127], v[102:103], off
	v_addc_co_u32_e32 v123, vcc, 0, v115, vcc
	v_mul_f32_e32 v119, v98, v135
	v_mul_f32_e32 v110, v97, v135
	v_cndmask_b32_e64 v97, v96, v119, s[10:11]
	v_cndmask_b32_e64 v98, v110, v99, s[10:11]
	v_bitop3_b32 v106, v134, s76, 16 bitop3:0xc8
	v_mov_b32_dpp v97, v97 quad_perm:[1,0,3,2] row_mask:0xf bank_mask:0xf bound_ctrl:1
	v_mov_b32_dpp v111, v98 quad_perm:[1,0,3,2] row_mask:0xf bank_mask:0xf bound_ctrl:1
	v_mov_b32_e32 v118, v97
	v_mov_b32_e32 v98, v111
	v_ashrrev_i32_e32 v107, 31, v106
	s_waitcnt vmcnt(30)
	v_mov_b64_e32 v[100:101], v[198:199]
	v_mov_b64_e32 v[102:103], v[200:201]
	v_pk_add_f32 v[96:97], v[96:97], v[100:101]
	v_pk_add_f32 v[100:101], v[100:101], v[118:119]
	v_pk_add_f32 v[110:111], v[110:111], v[102:103]
	v_pk_add_f32 v[98:99], v[102:103], v[98:99]
	v_cndmask_b32_e64 v97, v101, v97, s[10:11]
	v_cndmask_b32_e64 v96, v100, v96, s[10:11]
	v_cndmask_b32_e64 v99, v99, v111, s[10:11]
	v_cndmask_b32_e64 v98, v98, v110, s[10:11]
	global_store_dwordx2 v[114:115], v[96:97], off
	global_store_dwordx2 v[122:123], v[98:99], off
	v_lshlrev_b64 v[96:97], 2, v[106:107]
	v_lshl_add_u64 v[98:99], v[130:131], 0, v[96:97]
	v_lshl_add_u64 v[100:101], v[98:99], 0, v[128:129]
	v_add_co_u32_e32 v102, vcc, s73, v100
	v_lshl_add_u64 v[98:99], v[132:133], 0, v[96:97]
	s_nop 0
	v_addc_co_u32_e32 v103, vcc, 0, v101, vcc
	s_mov_b32 s98, 0x200
	s_mov_b32 s99, 0
	v_lshl_add_u64 v[250:251], v[248:249], 0, s[98:99]
	global_load_dwordx2 v[168:169], v[250:251], off
	s_mov_b32 s98, 0x1200
	s_mov_b32 s99, 0
	v_lshl_add_u64 v[250:251], v[248:249], 0, s[98:99]
	global_load_dwordx2 v[170:171], v[250:251], off
	s_mov_b32 s98, 0x10200
	s_mov_b32 s99, 0
	v_lshl_add_u64 v[250:251], v[248:249], 0, s[98:99]
	global_load_dwordx2 v[172:173], v[250:251], off
	s_mov_b32 s98, 0x11200
	s_mov_b32 s99, 0
	v_lshl_add_u64 v[250:251], v[248:249], 0, s[98:99]
	global_load_dwordx2 v[174:175], v[250:251], off
	s_mov_b32 s98, 0x20200
	s_mov_b32 s99, 0
	v_lshl_add_u64 v[250:251], v[248:249], 0, s[98:99]
	global_load_dwordx2 v[176:177], v[250:251], off
	s_mov_b32 s98, 0x21200
	s_mov_b32 s99, 0
	v_lshl_add_u64 v[250:251], v[248:249], 0, s[98:99]
	global_load_dwordx2 v[178:179], v[250:251], off
	s_mov_b32 s98, 0x30200
	s_mov_b32 s99, 0
	v_lshl_add_u64 v[250:251], v[248:249], 0, s[98:99]
	global_load_dwordx2 v[180:181], v[250:251], off
	s_mov_b32 s98, 0x31200
	s_mov_b32 s99, 0
	v_lshl_add_u64 v[250:251], v[248:249], 0, s[98:99]
	global_load_dwordx2 v[182:183], v[250:251], off
	s_mov_b32 s98, 0x80200
	s_mov_b32 s99, 0
	v_lshl_add_u64 v[250:251], v[248:249], 0, s[98:99]
	global_load_dwordx2 v[184:185], v[250:251], off
	s_mov_b32 s98, 0x81200
	s_mov_b32 s99, 0
	v_lshl_add_u64 v[250:251], v[248:249], 0, s[98:99]
	global_load_dwordx2 v[186:187], v[250:251], off
	s_mov_b32 s98, 0x90200
	s_mov_b32 s99, 0
	v_lshl_add_u64 v[250:251], v[248:249], 0, s[98:99]
	global_load_dwordx2 v[188:189], v[250:251], off
	s_mov_b32 s98, 0x91200
	s_mov_b32 s99, 0
	v_lshl_add_u64 v[250:251], v[248:249], 0, s[98:99]
	global_load_dwordx2 v[190:191], v[250:251], off
	s_mov_b32 s98, 0xa0200
	s_mov_b32 s99, 0
	v_lshl_add_u64 v[250:251], v[248:249], 0, s[98:99]
	global_load_dwordx2 v[192:193], v[250:251], off
	s_mov_b32 s98, 0xa1200
	s_mov_b32 s99, 0
	v_lshl_add_u64 v[250:251], v[248:249], 0, s[98:99]
	global_load_dwordx2 v[196:197], v[250:251], off
	s_mov_b32 s98, 0xb0200
	s_mov_b32 s99, 0
	v_lshl_add_u64 v[250:251], v[248:249], 0, s[98:99]
	global_load_dwordx2 v[198:199], v[250:251], off
	s_mov_b32 s98, 0xb1200
	s_mov_b32 s99, 0
	v_lshl_add_u64 v[250:251], v[248:249], 0, s[98:99]
	global_load_dwordx2 v[200:201], v[250:251], off
	v_lshl_add_u64 v[114:115], v[98:99], 0, v[128:129]
	v_add_co_u32_e32 v118, vcc, s73, v114
	s_waitcnt vmcnt(46)
; DI float dppx1(float v) { return __int_as_float(__builtin_amdgcn_update_dpp(0, __float_as_int(v), 0xB1, 0xF, 0xF, true)); }
; DI void rmw_pair_f32(float* xo_even, const float* xi_even, long ld, bool odd, float v0, float v1, float v2, float v3) {
;   const float sx = odd ? v0 : v2, sy = odd ? v1 : v3;
;   const float rx = dppx1(sx), ry = dppx1(sy);
;   const long off = odd ? 2 * ld : 0;
;   const float2 a0 = *(const float2*)(xi_even + off), a1 = *(const float2*)(xi_even + off + ld);
;   float2 o0, o1;
;   if (odd) { o0 = float2{a0.x + rx, a0.y + v2}; o1 = float2{a1.x + ry, a1.y + v3}; }
;   else     { o0 = float2{a0.x + v0, a0.y + rx}; o1 = float2{a1.x + v1, a1.y + ry}; }
;   *(float2*)(xo_even + off) = o0;
;   *(float2*)(xo_even + off + ld) = o1;
; }
; __global__ void __launch_bounds__(NTHR) fwd_kernel(Params pk) {
;     ...
;           for (int bj = 0; bj < 2; ++bj)
; #pragma unroll
;             for (int n = 0; n < 2; ++n) {
;               const int col = pn * 256 + bj * 128 + wc * 32 + n * 16 + fr;
;               const float gv = 0.5f * gate[(long)b * 9216 + col];
; #pragma unroll
;               for (int ai = 0; ai < 2; ++ai)
; #pragma unroll
;                 for (int m = 0; m < 4; ++m) {
;                   const long row0 = (long)pm * 256 + ai * 128 + wr * 64 + m * 16 + fq * 4;
;                   const f32x4 a = acc[ai][bj][m][n];
;                   rmw_pair_f32(xo + row0 * DM + (col & ~1), xin + row0 * DM + (col & ~1), DM, col & 1, gv * a[0], gv * a[1], gv * a[2], gv * a[3]);
;                   asm volatile("" ::: "memory");
;                 }
	v_mov_b64_e32 v[106:107], v[202:203]
	v_mov_b64_e32 v[110:111], v[204:205]
	v_mov_b32_e32 v122, v245
	v_mul_f32_e32 v98, 0.5, v122
	v_mul_f32_e32 v92, v92, v98
	v_mul_f32_e32 v127, v94, v98
	v_mul_f32_e32 v122, v93, v98
	v_mul_f32_e32 v95, v95, v98
	v_cndmask_b32_e64 v93, v92, v127, s[10:11]
	v_cndmask_b32_e64 v94, v122, v95, s[10:11]
	v_addc_co_u32_e32 v119, vcc, 0, v115, vcc
	v_mov_b32_dpp v93, v93 quad_perm:[1,0,3,2] row_mask:0xf bank_mask:0xf bound_ctrl:1
	v_mov_b32_dpp v123, v94 quad_perm:[1,0,3,2] row_mask:0xf bank_mask:0xf bound_ctrl:1
	v_mov_b32_e32 v126, v93
	v_pk_add_f32 v[138:139], v[92:93], v[106:107]
	v_mov_b32_e32 v94, v123
	v_pk_add_f32 v[92:93], v[106:107], v[126:127]
	v_pk_add_f32 v[142:143], v[122:123], v[110:111]
	v_pk_add_f32 v[94:95], v[110:111], v[94:95]
	v_cndmask_b32_e64 v93, v93, v139, s[10:11]
	v_cndmask_b32_e64 v92, v92, v138, s[10:11]
	v_cndmask_b32_e64 v95, v95, v143, s[10:11]
	v_cndmask_b32_e64 v94, v94, v142, s[10:11]
	global_store_dwordx2 v[100:101], v[92:93], off
	global_store_dwordx2 v[102:103], v[94:95], off
	v_mul_f32_e32 v88, v88, v98
	v_mul_f32_e32 v111, v90, v98
	v_mul_f32_e32 v106, v89, v98
	v_mul_f32_e32 v91, v91, v98
	v_cndmask_b32_e64 v89, v88, v111, s[10:11]
	v_cndmask_b32_e64 v90, v106, v91, s[10:11]
	v_lshl_add_u64 v[100:101], v[124:125], 0, v[96:97]
	v_mov_b32_dpp v89, v89 quad_perm:[1,0,3,2] row_mask:0xf bank_mask:0xf bound_ctrl:1
	v_mov_b32_dpp v107, v90 quad_perm:[1,0,3,2] row_mask:0xf bank_mask:0xf bound_ctrl:1
	v_mov_b32_e32 v110, v89
	v_mov_b32_e32 v90, v107
	v_lshl_add_u64 v[100:101], v[100:101], 0, v[128:129]
	v_add_co_u32_e32 v102, vcc, s73, v100
	v_mul_f32_e32 v84, v84, v98
	s_nop 0
	v_addc_co_u32_e32 v103, vcc, 0, v101, vcc
	v_mul_f32_e32 v87, v87, v98
	v_mul_f32_e32 v80, v80, v98
	v_mul_f32_e32 v83, v83, v98
	v_mul_f32_e32 v76, v76, v98
	v_mul_f32_e32 v79, v79, v98
	v_mul_f32_e32 v72, v72, v98
	v_mul_f32_e32 v75, v75, v98
	v_mul_f32_e32 v68, v68, v98
	v_mul_f32_e32 v71, v71, v98
	v_mul_f32_e32 v64, v64, v98
	v_mul_f32_e32 v67, v67, v98
	s_waitcnt vmcnt(46)
	v_mov_b64_e32 v[92:93], v[206:207]
	v_mov_b64_e32 v[94:95], v[208:209]
	v_pk_add_f32 v[88:89], v[88:89], v[92:93]
	v_pk_add_f32 v[92:93], v[92:93], v[110:111]
	v_pk_add_f32 v[106:107], v[106:107], v[94:95]
	v_pk_add_f32 v[90:91], v[94:95], v[90:91]
	v_cndmask_b32_e64 v89, v93, v89, s[10:11]
	v_cndmask_b32_e64 v88, v92, v88, s[10:11]
	v_cndmask_b32_e64 v91, v91, v107, s[10:11]
	v_cndmask_b32_e64 v90, v90, v106, s[10:11]
	global_store_dwordx2 v[114:115], v[88:89], off
	global_store_dwordx2 v[118:119], v[90:91], off
	v_mul_f32_e32 v111, v86, v98
	v_mul_f32_e32 v106, v85, v98
	v_cndmask_b32_e64 v85, v84, v111, s[10:11]
	v_cndmask_b32_e64 v86, v106, v87, s[10:11]
	v_lshl_add_u64 v[92:93], v[120:121], 0, v[96:97]
	v_mov_b32_dpp v85, v85 quad_perm:[1,0,3,2] row_mask:0xf bank_mask:0xf bound_ctrl:1
	v_mov_b32_dpp v107, v86 quad_perm:[1,0,3,2] row_mask:0xf bank_mask:0xf bound_ctrl:1
	v_mov_b32_e32 v110, v85
	v_mov_b32_e32 v86, v107
	v_lshl_add_u64 v[92:93], v[92:93], 0, v[128:129]
	v_add_co_u32_e32 v94, vcc, s73, v92
	s_waitcnt vmcnt(46)
	v_mov_b64_e32 v[88:89], v[210:211]
	v_mov_b64_e32 v[90:91], v[212:213]
	v_pk_add_f32 v[84:85], v[84:85], v[88:89]
	v_pk_add_f32 v[88:89], v[88:89], v[110:111]
	v_pk_add_f32 v[106:107], v[106:107], v[90:91]
	v_pk_add_f32 v[86:87], v[90:91], v[86:87]
	v_cndmask_b32_e64 v85, v89, v85, s[10:11]
	v_cndmask_b32_e64 v84, v88, v84, s[10:11]
	v_cndmask_b32_e64 v87, v87, v107, s[10:11]
	v_cndmask_b32_e64 v86, v86, v106, s[10:11]
	global_store_dwordx2 v[100:101], v[84:85], off
	global_store_dwordx2 v[102:103], v[86:87], off
	v_addc_co_u32_e32 v95, vcc, 0, v93, vcc
	v_mul_f32_e32 v103, v82, v98
	v_mul_f32_e32 v100, v81, v98
	v_cndmask_b32_e64 v81, v80, v103, s[10:11]
	v_cndmask_b32_e64 v82, v100, v83, s[10:11]
	v_lshl_add_u64 v[88:89], v[116:117], 0, v[96:97]
	v_mov_b32_dpp v81, v81 quad_perm:[1,0,3,2] row_mask:0xf bank_mask:0xf bound_ctrl:1
	v_mov_b32_dpp v101, v82 quad_perm:[1,0,3,2] row_mask:0xf bank_mask:0xf bound_ctrl:1
	v_mov_b32_e32 v102, v81
	v_mov_b32_e32 v82, v101
	v_lshl_add_u64 v[88:89], v[88:89], 0, v[128:129]
	v_add_co_u32_e32 v90, vcc, s73, v88
	s_waitcnt vmcnt(46)
	v_mov_b64_e32 v[84:85], v[214:215]
	v_mov_b64_e32 v[86:87], v[216:217]
	v_pk_add_f32 v[80:81], v[80:81], v[84:85]
	v_pk_add_f32 v[84:85], v[84:85], v[102:103]
	v_pk_add_f32 v[100:101], v[100:101], v[86:87]
	v_pk_add_f32 v[82:83], v[86:87], v[82:83]
	v_cndmask_b32_e64 v81, v85, v81, s[10:11]
	v_cndmask_b32_e64 v80, v84, v80, s[10:11]
	v_cndmask_b32_e64 v83, v83, v101, s[10:11]
	v_cndmask_b32_e64 v82, v82, v100, s[10:11]
	global_store_dwordx2 v[92:93], v[80:81], off
	global_store_dwordx2 v[94:95], v[82:83], off
	v_addc_co_u32_e32 v91, vcc, 0, v89, vcc
	v_mul_f32_e32 v95, v78, v98
	v_mul_f32_e32 v92, v77, v98
	v_cndmask_b32_e64 v77, v76, v95, s[10:11]
	v_cndmask_b32_e64 v78, v92, v79, s[10:11]
	v_lshl_add_u64 v[84:85], v[112:113], 0, v[96:97]
	v_mov_b32_dpp v77, v77 quad_perm:[1,0,3,2] row_mask:0xf bank_mask:0xf bound_ctrl:1
	v_mov_b32_dpp v93, v78 quad_perm:[1,0,3,2] row_mask:0xf bank_mask:0xf bound_ctrl:1
	v_mov_b32_e32 v94, v77
	v_mov_b32_e32 v78, v93
	v_lshl_add_u64 v[84:85], v[84:85], 0, v[128:129]
	v_add_co_u32_e32 v86, vcc, s73, v84
	s_waitcnt vmcnt(46)
; DI float dppx1(float v) { return __int_as_float(__builtin_amdgcn_update_dpp(0, __float_as_int(v), 0xB1, 0xF, 0xF, true)); }
; DI void rmw_pair_f32(float* xo_even, const float* xi_even, long ld, bool odd, float v0, float v1, float v2, float v3) {
;   const float sx = odd ? v0 : v2, sy = odd ? v1 : v3;
;   const float rx = dppx1(sx), ry = dppx1(sy);
;   const long off = odd ? 2 * ld : 0;
;   const float2 a0 = *(const float2*)(xi_even + off), a1 = *(const float2*)(xi_even + off + ld);
;   float2 o0, o1;
;   if (odd) { o0 = float2{a0.x + rx, a0.y + v2}; o1 = float2{a1.x + ry, a1.y + v3}; }
;   else     { o0 = float2{a0.x + v0, a0.y + rx}; o1 = float2{a1.x + v1, a1.y + ry}; }
;   *(float2*)(xo_even + off) = o0;
;   *(float2*)(xo_even + off + ld) = o1;
; }
; __global__ void __launch_bounds__(NTHR) fwd_kernel(Params pk) {
;     ...
;           for (int bj = 0; bj < 2; ++bj)
; #pragma unroll
;             for (int n = 0; n < 2; ++n) {
;               const int col = pn * 256 + bj * 128 + wc * 32 + n * 16 + fr;
;               const float gv = 0.5f * gate[(long)b * 9216 + col];
; #pragma unroll
;               for (int ai = 0; ai < 2; ++ai)
; #pragma unroll
;                 for (int m = 0; m < 4; ++m) {
;                   const long row0 = (long)pm * 256 + ai * 128 + wr * 64 + m * 16 + fq * 4;
;                   const f32x4 a = acc[ai][bj][m][n];
;                   rmw_pair_f32(xo + row0 * DM + (col & ~1), xin + row0 * DM + (col & ~1), DM, col & 1, gv * a[0], gv * a[1], gv * a[2], gv * a[3]);
;                   asm volatile("" ::: "memory");
;                 }
	v_mov_b64_e32 v[80:81], v[218:219]
	v_mov_b64_e32 v[82:83], v[220:221]
	v_pk_add_f32 v[76:77], v[76:77], v[80:81]
	v_pk_add_f32 v[80:81], v[80:81], v[94:95]
	v_pk_add_f32 v[92:93], v[92:93], v[82:83]
	v_pk_add_f32 v[78:79], v[82:83], v[78:79]
	v_cndmask_b32_e64 v77, v81, v77, s[10:11]
	v_cndmask_b32_e64 v76, v80, v76, s[10:11]
	v_cndmask_b32_e64 v79, v79, v93, s[10:11]
	v_cndmask_b32_e64 v78, v78, v92, s[10:11]
	global_store_dwordx2 v[88:89], v[76:77], off
	global_store_dwordx2 v[90:91], v[78:79], off
	v_addc_co_u32_e32 v87, vcc, 0, v85, vcc
	v_mul_f32_e32 v91, v74, v98
	v_mul_f32_e32 v88, v73, v98
	v_cndmask_b32_e64 v73, v72, v91, s[10:11]
	v_cndmask_b32_e64 v74, v88, v75, s[10:11]
	v_lshl_add_u64 v[80:81], v[108:109], 0, v[96:97]
	v_mov_b32_dpp v73, v73 quad_perm:[1,0,3,2] row_mask:0xf bank_mask:0xf bound_ctrl:1
	v_mov_b32_dpp v89, v74 quad_perm:[1,0,3,2] row_mask:0xf bank_mask:0xf bound_ctrl:1
	v_mov_b32_e32 v90, v73
	v_mov_b32_e32 v74, v89
	v_lshl_add_u64 v[80:81], v[80:81], 0, v[128:129]
	v_add_co_u32_e32 v82, vcc, s73, v80
	s_waitcnt vmcnt(46)
	v_mov_b64_e32 v[76:77], v[222:223]
	v_mov_b64_e32 v[78:79], v[224:225]
	v_pk_add_f32 v[72:73], v[72:73], v[76:77]
	v_pk_add_f32 v[76:77], v[76:77], v[90:91]
	v_pk_add_f32 v[88:89], v[88:89], v[78:79]
	v_pk_add_f32 v[74:75], v[78:79], v[74:75]
	v_cndmask_b32_e64 v73, v77, v73, s[10:11]
	v_cndmask_b32_e64 v72, v76, v72, s[10:11]
	v_cndmask_b32_e64 v75, v75, v89, s[10:11]
	v_cndmask_b32_e64 v74, v74, v88, s[10:11]
	global_store_dwordx2 v[84:85], v[72:73], off
	global_store_dwordx2 v[86:87], v[74:75], off
	v_addc_co_u32_e32 v83, vcc, 0, v81, vcc
	v_mul_f32_e32 v87, v70, v98
	v_mul_f32_e32 v84, v69, v98
	v_cndmask_b32_e64 v69, v68, v87, s[10:11]
	v_cndmask_b32_e64 v70, v84, v71, s[10:11]
	v_lshl_add_u64 v[76:77], v[104:105], 0, v[96:97]
	v_mov_b32_dpp v69, v69 quad_perm:[1,0,3,2] row_mask:0xf bank_mask:0xf bound_ctrl:1
	v_mov_b32_dpp v85, v70 quad_perm:[1,0,3,2] row_mask:0xf bank_mask:0xf bound_ctrl:1
	v_mov_b32_e32 v86, v69
	v_mov_b32_e32 v70, v85
	v_lshl_add_u64 v[76:77], v[76:77], 0, v[128:129]
	v_add_co_u32_e32 v78, vcc, s73, v76
	s_waitcnt vmcnt(46)
	v_mov_b64_e32 v[72:73], v[226:227]
	v_mov_b64_e32 v[74:75], v[228:229]
	v_pk_add_f32 v[68:69], v[68:69], v[72:73]
	v_pk_add_f32 v[72:73], v[72:73], v[86:87]
	v_pk_add_f32 v[84:85], v[84:85], v[74:75]
	v_pk_add_f32 v[70:71], v[74:75], v[70:71]
	v_cndmask_b32_e64 v69, v73, v69, s[10:11]
	v_cndmask_b32_e64 v68, v72, v68, s[10:11]
	v_cndmask_b32_e64 v71, v71, v85, s[10:11]
	v_cndmask_b32_e64 v70, v70, v84, s[10:11]
	global_store_dwordx2 v[80:81], v[68:69], off
	global_store_dwordx2 v[82:83], v[70:71], off
	v_addc_co_u32_e32 v79, vcc, 0, v77, vcc
	v_mul_f32_e32 v81, v66, v98
	v_mul_f32_e32 v74, v65, v98
	v_cndmask_b32_e64 v65, v64, v81, s[10:11]
	v_cndmask_b32_e64 v66, v74, v67, s[10:11]
	v_bitop3_b32 v72, v134, s77, v140 bitop3:0xc8
	v_mov_b32_dpp v65, v65 quad_perm:[1,0,3,2] row_mask:0xf bank_mask:0xf bound_ctrl:1
	v_mov_b32_dpp v75, v66 quad_perm:[1,0,3,2] row_mask:0xf bank_mask:0xf bound_ctrl:1
	v_mov_b32_e32 v80, v65
	v_mov_b32_e32 v66, v75
	v_ashrrev_i32_e32 v73, 31, v72
	s_waitcnt vmcnt(46)
	v_mov_b64_e32 v[68:69], v[230:231]
	v_mov_b64_e32 v[70:71], v[232:233]
	v_pk_add_f32 v[64:65], v[64:65], v[68:69]
	v_pk_add_f32 v[68:69], v[68:69], v[80:81]
	v_pk_add_f32 v[74:75], v[74:75], v[70:71]
	v_pk_add_f32 v[66:67], v[70:71], v[66:67]
	v_cndmask_b32_e64 v65, v69, v65, s[10:11]
	v_cndmask_b32_e64 v64, v68, v64, s[10:11]
	v_cndmask_b32_e64 v67, v67, v75, s[10:11]
	v_cndmask_b32_e64 v66, v66, v74, s[10:11]
	global_store_dwordx2 v[76:77], v[64:65], off
	global_store_dwordx2 v[78:79], v[66:67], off
	v_lshlrev_b64 v[64:65], 2, v[72:73]
	v_lshl_add_u64 v[66:67], v[130:131], 0, v[64:65]
	v_lshl_add_u64 v[68:69], v[66:67], 0, v[128:129]
	v_add_co_u32_e32 v70, vcc, s73, v68
	v_lshl_add_u64 v[66:67], v[132:133], 0, v[64:65]
	s_nop 0
	v_addc_co_u32_e32 v71, vcc, 0, v69, vcc
	s_mov_b32 s98, 0x240
	s_mov_b32 s99, 0
	v_lshl_add_u64 v[250:251], v[248:249], 0, s[98:99]
	global_load_dwordx2 v[202:203], v[250:251], off
	s_mov_b32 s98, 0x1240
	s_mov_b32 s99, 0
	v_lshl_add_u64 v[250:251], v[248:249], 0, s[98:99]
	global_load_dwordx2 v[204:205], v[250:251], off
	s_mov_b32 s98, 0x10240
	s_mov_b32 s99, 0
	v_lshl_add_u64 v[250:251], v[248:249], 0, s[98:99]
	global_load_dwordx2 v[206:207], v[250:251], off
	s_mov_b32 s98, 0x11240
	s_mov_b32 s99, 0
	v_lshl_add_u64 v[250:251], v[248:249], 0, s[98:99]
	global_load_dwordx2 v[208:209], v[250:251], off
	s_mov_b32 s98, 0x20240
	s_mov_b32 s99, 0
	v_lshl_add_u64 v[250:251], v[248:249], 0, s[98:99]
	global_load_dwordx2 v[210:211], v[250:251], off
	s_mov_b32 s98, 0x21240
	s_mov_b32 s99, 0
	v_lshl_add_u64 v[250:251], v[248:249], 0, s[98:99]
	global_load_dwordx2 v[212:213], v[250:251], off
	s_mov_b32 s98, 0x30240
	s_mov_b32 s99, 0
	v_lshl_add_u64 v[250:251], v[248:249], 0, s[98:99]
	global_load_dwordx2 v[214:215], v[250:251], off
	s_mov_b32 s98, 0x31240
	s_mov_b32 s99, 0
	v_lshl_add_u64 v[250:251], v[248:249], 0, s[98:99]
	global_load_dwordx2 v[216:217], v[250:251], off
	s_mov_b32 s98, 0x80240
	s_mov_b32 s99, 0
	v_lshl_add_u64 v[250:251], v[248:249], 0, s[98:99]
	global_load_dwordx2 v[218:219], v[250:251], off
	s_mov_b32 s98, 0x81240
	s_mov_b32 s99, 0
	v_lshl_add_u64 v[250:251], v[248:249], 0, s[98:99]
	global_load_dwordx2 v[220:221], v[250:251], off
	s_mov_b32 s98, 0x90240
	s_mov_b32 s99, 0
	v_lshl_add_u64 v[250:251], v[248:249], 0, s[98:99]
	global_load_dwordx2 v[222:223], v[250:251], off
	s_mov_b32 s98, 0x91240
	s_mov_b32 s99, 0
	v_lshl_add_u64 v[250:251], v[248:249], 0, s[98:99]
	global_load_dwordx2 v[224:225], v[250:251], off
	s_mov_b32 s98, 0xa0240
	s_mov_b32 s99, 0
	v_lshl_add_u64 v[250:251], v[248:249], 0, s[98:99]
	global_load_dwordx2 v[226:227], v[250:251], off
	s_mov_b32 s98, 0xa1240
	s_mov_b32 s99, 0
	v_lshl_add_u64 v[250:251], v[248:249], 0, s[98:99]
	global_load_dwordx2 v[228:229], v[250:251], off
	s_mov_b32 s98, 0xb0240
	s_mov_b32 s99, 0
	v_lshl_add_u64 v[250:251], v[248:249], 0, s[98:99]
	global_load_dwordx2 v[230:231], v[250:251], off
	s_mov_b32 s98, 0xb1240
	s_mov_b32 s99, 0
	v_lshl_add_u64 v[250:251], v[248:249], 0, s[98:99]
	global_load_dwordx2 v[232:233], v[250:251], off
	v_lshl_add_u64 v[76:77], v[66:67], 0, v[128:129]
	v_add_co_u32_e32 v78, vcc, s73, v76
	s_waitcnt vmcnt(46)
; DI float dppx1(float v) { return __int_as_float(__builtin_amdgcn_update_dpp(0, __float_as_int(v), 0xB1, 0xF, 0xF, true)); }
; DI void rmw_pair_f32(float* xo_even, const float* xi_even, long ld, bool odd, float v0, float v1, float v2, float v3) {
;   const float sx = odd ? v0 : v2, sy = odd ? v1 : v3;
;   const float rx = dppx1(sx), ry = dppx1(sy);
;   const long off = odd ? 2 * ld : 0;
;   const float2 a0 = *(const float2*)(xi_even + off), a1 = *(const float2*)(xi_even + off + ld);
;   float2 o0, o1;
;   if (odd) { o0 = float2{a0.x + rx, a0.y + v2}; o1 = float2{a1.x + ry, a1.y + v3}; }
;   else     { o0 = float2{a0.x + v0, a0.y + rx}; o1 = float2{a1.x + v1, a1.y + ry}; }
;   *(float2*)(xo_even + off) = o0;
;   *(float2*)(xo_even + off + ld) = o1;
; }
; __global__ void __launch_bounds__(NTHR) fwd_kernel(Params pk) {
;     ...
;           for (int bj = 0; bj < 2; ++bj)
; #pragma unroll
;             for (int n = 0; n < 2; ++n) {
;               const int col = pn * 256 + bj * 128 + wc * 32 + n * 16 + fr;
;               const float gv = 0.5f * gate[(long)b * 9216 + col];
; #pragma unroll
;               for (int ai = 0; ai < 2; ++ai)
; #pragma unroll
;                 for (int m = 0; m < 4; ++m) {
;                   const long row0 = (long)pm * 256 + ai * 128 + wr * 64 + m * 16 + fq * 4;
;                   const f32x4 a = acc[ai][bj][m][n];
;                   rmw_pair_f32(xo + row0 * DM + (col & ~1), xin + row0 * DM + (col & ~1), DM, col & 1, gv * a[0], gv * a[1], gv * a[2], gv * a[3]);
;                   asm volatile("" ::: "memory");
;                 }
	v_mov_b64_e32 v[72:73], v[168:169]
	v_mov_b64_e32 v[74:75], v[170:171]
	v_mov_b32_e32 v80, v246
	v_mul_f32_e32 v66, 0.5, v80
	v_mul_f32_e32 v60, v60, v66
	v_mul_f32_e32 v83, v62, v66
	v_mul_f32_e32 v80, v61, v66
	v_mul_f32_e32 v63, v63, v66
	v_cndmask_b32_e64 v61, v60, v83, s[10:11]
	v_cndmask_b32_e64 v62, v80, v63, s[10:11]
	v_addc_co_u32_e32 v79, vcc, 0, v77, vcc
	v_mov_b32_dpp v61, v61 quad_perm:[1,0,3,2] row_mask:0xf bank_mask:0xf bound_ctrl:1
	v_mov_b32_dpp v81, v62 quad_perm:[1,0,3,2] row_mask:0xf bank_mask:0xf bound_ctrl:1
	v_mov_b32_e32 v82, v61
	v_pk_add_f32 v[84:85], v[60:61], v[72:73]
	v_mov_b32_e32 v62, v81
	v_pk_add_f32 v[60:61], v[72:73], v[82:83]
	v_pk_add_f32 v[86:87], v[80:81], v[74:75]
	v_pk_add_f32 v[62:63], v[74:75], v[62:63]
	v_cndmask_b32_e64 v61, v61, v85, s[10:11]
	v_cndmask_b32_e64 v60, v60, v84, s[10:11]
	v_cndmask_b32_e64 v63, v63, v87, s[10:11]
	v_cndmask_b32_e64 v62, v62, v86, s[10:11]
	global_store_dwordx2 v[68:69], v[60:61], off
	global_store_dwordx2 v[70:71], v[62:63], off
	v_mul_f32_e32 v56, v56, v66
	v_mul_f32_e32 v75, v58, v66
	v_mul_f32_e32 v72, v57, v66
	v_mul_f32_e32 v59, v59, v66
	v_cndmask_b32_e64 v57, v56, v75, s[10:11]
	v_cndmask_b32_e64 v58, v72, v59, s[10:11]
	v_lshl_add_u64 v[68:69], v[124:125], 0, v[64:65]
	v_mov_b32_dpp v57, v57 quad_perm:[1,0,3,2] row_mask:0xf bank_mask:0xf bound_ctrl:1
	v_mov_b32_dpp v73, v58 quad_perm:[1,0,3,2] row_mask:0xf bank_mask:0xf bound_ctrl:1
	v_mov_b32_e32 v74, v57
	v_mov_b32_e32 v58, v73
	v_lshl_add_u64 v[68:69], v[68:69], 0, v[128:129]
	v_add_co_u32_e32 v70, vcc, s73, v68
	v_mul_f32_e32 v52, v52, v66
	s_nop 0
	v_addc_co_u32_e32 v71, vcc, 0, v69, vcc
	v_mul_f32_e32 v55, v55, v66
	v_mul_f32_e32 v48, v48, v66
	v_mul_f32_e32 v51, v51, v66
	v_mul_f32_e32 v44, v44, v66
	v_mul_f32_e32 v47, v47, v66
	v_mul_f32_e32 v40, v40, v66
	v_mul_f32_e32 v43, v43, v66
	v_mul_f32_e32 v36, v36, v66
	v_mul_f32_e32 v39, v39, v66
	v_mul_f32_e32 v32, v32, v66
	v_mul_f32_e32 v35, v35, v66
	s_waitcnt vmcnt(46)
	v_mov_b64_e32 v[60:61], v[172:173]
	v_mov_b64_e32 v[62:63], v[174:175]
	v_pk_add_f32 v[56:57], v[56:57], v[60:61]
	v_pk_add_f32 v[60:61], v[60:61], v[74:75]
	v_pk_add_f32 v[72:73], v[72:73], v[62:63]
	v_pk_add_f32 v[58:59], v[62:63], v[58:59]
	v_cndmask_b32_e64 v57, v61, v57, s[10:11]
	v_cndmask_b32_e64 v56, v60, v56, s[10:11]
	v_cndmask_b32_e64 v59, v59, v73, s[10:11]
	v_cndmask_b32_e64 v58, v58, v72, s[10:11]
	global_store_dwordx2 v[76:77], v[56:57], off
	global_store_dwordx2 v[78:79], v[58:59], off
	v_mul_f32_e32 v75, v54, v66
	v_mul_f32_e32 v72, v53, v66
	v_cndmask_b32_e64 v53, v52, v75, s[10:11]
	v_cndmask_b32_e64 v54, v72, v55, s[10:11]
	v_lshl_add_u64 v[60:61], v[120:121], 0, v[64:65]
	v_mov_b32_dpp v53, v53 quad_perm:[1,0,3,2] row_mask:0xf bank_mask:0xf bound_ctrl:1
	v_mov_b32_dpp v73, v54 quad_perm:[1,0,3,2] row_mask:0xf bank_mask:0xf bound_ctrl:1
	v_mov_b32_e32 v74, v53
	v_mov_b32_e32 v54, v73
	v_lshl_add_u64 v[60:61], v[60:61], 0, v[128:129]
	v_add_co_u32_e32 v62, vcc, s73, v60
	s_waitcnt vmcnt(46)
	v_mov_b64_e32 v[56:57], v[176:177]
	v_mov_b64_e32 v[58:59], v[178:179]
	v_pk_add_f32 v[52:53], v[52:53], v[56:57]
	v_pk_add_f32 v[56:57], v[56:57], v[74:75]
	v_pk_add_f32 v[72:73], v[72:73], v[58:59]
	v_pk_add_f32 v[54:55], v[58:59], v[54:55]
	v_cndmask_b32_e64 v53, v57, v53, s[10:11]
	v_cndmask_b32_e64 v52, v56, v52, s[10:11]
	v_cndmask_b32_e64 v55, v55, v73, s[10:11]
	v_cndmask_b32_e64 v54, v54, v72, s[10:11]
	global_store_dwordx2 v[68:69], v[52:53], off
	global_store_dwordx2 v[70:71], v[54:55], off
	v_addc_co_u32_e32 v63, vcc, 0, v61, vcc
	v_mul_f32_e32 v71, v50, v66
	v_mul_f32_e32 v68, v49, v66
	v_cndmask_b32_e64 v49, v48, v71, s[10:11]
	v_cndmask_b32_e64 v50, v68, v51, s[10:11]
	v_lshl_add_u64 v[56:57], v[116:117], 0, v[64:65]
	v_mov_b32_dpp v49, v49 quad_perm:[1,0,3,2] row_mask:0xf bank_mask:0xf bound_ctrl:1
	v_mov_b32_dpp v69, v50 quad_perm:[1,0,3,2] row_mask:0xf bank_mask:0xf bound_ctrl:1
	v_mov_b32_e32 v70, v49
	v_mov_b32_e32 v50, v69
	v_lshl_add_u64 v[56:57], v[56:57], 0, v[128:129]
	v_add_co_u32_e32 v58, vcc, s73, v56
	s_waitcnt vmcnt(46)
	v_mov_b64_e32 v[52:53], v[180:181]
	v_mov_b64_e32 v[54:55], v[182:183]
	v_pk_add_f32 v[48:49], v[48:49], v[52:53]
	v_pk_add_f32 v[52:53], v[52:53], v[70:71]
	v_pk_add_f32 v[68:69], v[68:69], v[54:55]
	v_pk_add_f32 v[50:51], v[54:55], v[50:51]
	v_cndmask_b32_e64 v49, v53, v49, s[10:11]
	v_cndmask_b32_e64 v48, v52, v48, s[10:11]
	v_cndmask_b32_e64 v51, v51, v69, s[10:11]
	v_cndmask_b32_e64 v50, v50, v68, s[10:11]
	global_store_dwordx2 v[60:61], v[48:49], off
	global_store_dwordx2 v[62:63], v[50:51], off
	v_addc_co_u32_e32 v59, vcc, 0, v57, vcc
	v_mul_f32_e32 v63, v46, v66
	v_mul_f32_e32 v60, v45, v66
	v_cndmask_b32_e64 v45, v44, v63, s[10:11]
	v_cndmask_b32_e64 v46, v60, v47, s[10:11]
	v_lshl_add_u64 v[52:53], v[112:113], 0, v[64:65]
	v_mov_b32_dpp v45, v45 quad_perm:[1,0,3,2] row_mask:0xf bank_mask:0xf bound_ctrl:1
	v_mov_b32_dpp v61, v46 quad_perm:[1,0,3,2] row_mask:0xf bank_mask:0xf bound_ctrl:1
	v_mov_b32_e32 v62, v45
	v_mov_b32_e32 v46, v61
	v_lshl_add_u64 v[52:53], v[52:53], 0, v[128:129]
	v_add_co_u32_e32 v54, vcc, s73, v52
	s_waitcnt vmcnt(46)
; DI float dppx1(float v) { return __int_as_float(__builtin_amdgcn_update_dpp(0, __float_as_int(v), 0xB1, 0xF, 0xF, true)); }
; DI void rmw_pair_f32(float* xo_even, const float* xi_even, long ld, bool odd, float v0, float v1, float v2, float v3) {
;   const float sx = odd ? v0 : v2, sy = odd ? v1 : v3;
;   const float rx = dppx1(sx), ry = dppx1(sy);
;   const long off = odd ? 2 * ld : 0;
;   const float2 a0 = *(const float2*)(xi_even + off), a1 = *(const float2*)(xi_even + off + ld);
;   float2 o0, o1;
;   if (odd) { o0 = float2{a0.x + rx, a0.y + v2}; o1 = float2{a1.x + ry, a1.y + v3}; }
;   else     { o0 = float2{a0.x + v0, a0.y + rx}; o1 = float2{a1.x + v1, a1.y + ry}; }
;   *(float2*)(xo_even + off) = o0;
;   *(float2*)(xo_even + off + ld) = o1;
; }
; __global__ void __launch_bounds__(NTHR) fwd_kernel(Params pk) {
;     ...
;           for (int bj = 0; bj < 2; ++bj)
; #pragma unroll
;             for (int n = 0; n < 2; ++n) {
;               const int col = pn * 256 + bj * 128 + wc * 32 + n * 16 + fr;
;               const float gv = 0.5f * gate[(long)b * 9216 + col];
; #pragma unroll
;               for (int ai = 0; ai < 2; ++ai)
; #pragma unroll
;                 for (int m = 0; m < 4; ++m) {
;                   const long row0 = (long)pm * 256 + ai * 128 + wr * 64 + m * 16 + fq * 4;
;                   const f32x4 a = acc[ai][bj][m][n];
;                   rmw_pair_f32(xo + row0 * DM + (col & ~1), xin + row0 * DM + (col & ~1), DM, col & 1, gv * a[0], gv * a[1], gv * a[2], gv * a[3]);
;                   asm volatile("" ::: "memory");
;                 }
	v_mov_b64_e32 v[48:49], v[184:185]
	v_mov_b64_e32 v[50:51], v[186:187]
	v_pk_add_f32 v[44:45], v[44:45], v[48:49]
	v_pk_add_f32 v[48:49], v[48:49], v[62:63]
	v_pk_add_f32 v[60:61], v[60:61], v[50:51]
	v_pk_add_f32 v[46:47], v[50:51], v[46:47]
	v_cndmask_b32_e64 v45, v49, v45, s[10:11]
	v_cndmask_b32_e64 v44, v48, v44, s[10:11]
	v_cndmask_b32_e64 v47, v47, v61, s[10:11]
	v_cndmask_b32_e64 v46, v46, v60, s[10:11]
	global_store_dwordx2 v[56:57], v[44:45], off
	global_store_dwordx2 v[58:59], v[46:47], off
	v_addc_co_u32_e32 v55, vcc, 0, v53, vcc
	v_mul_f32_e32 v59, v42, v66
	v_mul_f32_e32 v56, v41, v66
	v_cndmask_b32_e64 v41, v40, v59, s[10:11]
	v_cndmask_b32_e64 v42, v56, v43, s[10:11]
	v_lshl_add_u64 v[48:49], v[108:109], 0, v[64:65]
	v_mov_b32_dpp v41, v41 quad_perm:[1,0,3,2] row_mask:0xf bank_mask:0xf bound_ctrl:1
	v_mov_b32_dpp v57, v42 quad_perm:[1,0,3,2] row_mask:0xf bank_mask:0xf bound_ctrl:1
	v_mov_b32_e32 v58, v41
	v_mov_b32_e32 v42, v57
	v_lshl_add_u64 v[48:49], v[48:49], 0, v[128:129]
	v_add_co_u32_e32 v50, vcc, s73, v48
	s_waitcnt vmcnt(46)
	v_mov_b64_e32 v[44:45], v[188:189]
	v_mov_b64_e32 v[46:47], v[190:191]
	v_pk_add_f32 v[40:41], v[40:41], v[44:45]
	v_pk_add_f32 v[44:45], v[44:45], v[58:59]
	v_pk_add_f32 v[56:57], v[56:57], v[46:47]
	v_pk_add_f32 v[42:43], v[46:47], v[42:43]
	v_cndmask_b32_e64 v41, v45, v41, s[10:11]
	v_cndmask_b32_e64 v40, v44, v40, s[10:11]
	v_cndmask_b32_e64 v43, v43, v57, s[10:11]
	v_cndmask_b32_e64 v42, v42, v56, s[10:11]
	global_store_dwordx2 v[52:53], v[40:41], off
	global_store_dwordx2 v[54:55], v[42:43], off
	v_addc_co_u32_e32 v51, vcc, 0, v49, vcc
	v_mul_f32_e32 v55, v38, v66
	v_mul_f32_e32 v52, v37, v66
	v_cndmask_b32_e64 v37, v36, v55, s[10:11]
	v_cndmask_b32_e64 v38, v52, v39, s[10:11]
	v_lshl_add_u64 v[44:45], v[104:105], 0, v[64:65]
	v_mov_b32_dpp v37, v37 quad_perm:[1,0,3,2] row_mask:0xf bank_mask:0xf bound_ctrl:1
	v_mov_b32_dpp v53, v38 quad_perm:[1,0,3,2] row_mask:0xf bank_mask:0xf bound_ctrl:1
	v_mov_b32_e32 v54, v37
	v_mov_b32_e32 v38, v53
	v_lshl_add_u64 v[44:45], v[44:45], 0, v[128:129]
	v_add_co_u32_e32 v46, vcc, s73, v44
	s_waitcnt vmcnt(46)
	v_mov_b64_e32 v[40:41], v[192:193]
	v_mov_b64_e32 v[42:43], v[196:197]
	v_pk_add_f32 v[36:37], v[36:37], v[40:41]
	v_pk_add_f32 v[40:41], v[40:41], v[54:55]
	v_pk_add_f32 v[52:53], v[52:53], v[42:43]
	v_pk_add_f32 v[38:39], v[42:43], v[38:39]
	v_cndmask_b32_e64 v37, v41, v37, s[10:11]
	v_cndmask_b32_e64 v36, v40, v36, s[10:11]
	v_cndmask_b32_e64 v39, v39, v53, s[10:11]
	v_cndmask_b32_e64 v38, v38, v52, s[10:11]
	global_store_dwordx2 v[48:49], v[36:37], off
	global_store_dwordx2 v[50:51], v[38:39], off
	v_addc_co_u32_e32 v47, vcc, 0, v45, vcc
	v_mul_f32_e32 v49, v34, v66
	v_mul_f32_e32 v42, v33, v66
	v_cndmask_b32_e64 v33, v32, v49, s[10:11]
	v_cndmask_b32_e64 v34, v42, v35, s[10:11]
	v_bitop3_b32 v40, v134, -2, v141 bitop3:0xc8
	v_mov_b32_dpp v33, v33 quad_perm:[1,0,3,2] row_mask:0xf bank_mask:0xf bound_ctrl:1
	v_mov_b32_dpp v43, v34 quad_perm:[1,0,3,2] row_mask:0xf bank_mask:0xf bound_ctrl:1
	v_mov_b32_e32 v48, v33
	v_mov_b32_e32 v34, v43
	v_ashrrev_i32_e32 v41, 31, v40
	s_waitcnt vmcnt(46)
	v_mov_b64_e32 v[36:37], v[198:199]
	v_mov_b64_e32 v[38:39], v[200:201]
	v_pk_add_f32 v[32:33], v[32:33], v[36:37]
	v_pk_add_f32 v[36:37], v[36:37], v[48:49]
	v_pk_add_f32 v[42:43], v[42:43], v[38:39]
	v_pk_add_f32 v[34:35], v[38:39], v[34:35]
	v_cndmask_b32_e64 v33, v37, v33, s[10:11]
	v_cndmask_b32_e64 v32, v36, v32, s[10:11]
	v_cndmask_b32_e64 v35, v35, v43, s[10:11]
	v_cndmask_b32_e64 v34, v34, v42, s[10:11]
	global_store_dwordx2 v[44:45], v[32:33], off
	global_store_dwordx2 v[46:47], v[34:35], off
	v_lshlrev_b64 v[32:33], 2, v[40:41]
	v_lshl_add_u64 v[34:35], v[130:131], 0, v[32:33]
	v_lshl_add_u64 v[36:37], v[34:35], 0, v[128:129]
	v_add_co_u32_e32 v38, vcc, s73, v36
	v_lshl_add_u64 v[34:35], v[132:133], 0, v[32:33]
	s_nop 0
	v_addc_co_u32_e32 v39, vcc, 0, v37, vcc
	v_lshl_add_u64 v[44:45], v[34:35], 0, v[128:129]
	v_add_co_u32_e32 v46, vcc, s73, v44
	s_waitcnt vmcnt(30)
	v_mov_b64_e32 v[40:41], v[202:203]
	v_mov_b64_e32 v[42:43], v[204:205]
	v_mov_b32_e32 v48, v247
	v_mul_f32_e32 v34, 0.5, v48
	v_mul_f32_e32 v28, v28, v34
	v_mul_f32_e32 v51, v30, v34
	v_mul_f32_e32 v48, v29, v34
	v_mul_f32_e32 v31, v31, v34
	v_cndmask_b32_e64 v29, v28, v51, s[10:11]
	v_cndmask_b32_e64 v30, v48, v31, s[10:11]
	v_addc_co_u32_e32 v47, vcc, 0, v45, vcc
	v_mov_b32_dpp v29, v29 quad_perm:[1,0,3,2] row_mask:0xf bank_mask:0xf bound_ctrl:1
	v_mov_b32_dpp v49, v30 quad_perm:[1,0,3,2] row_mask:0xf bank_mask:0xf bound_ctrl:1
	v_mov_b32_e32 v50, v29
	v_pk_add_f32 v[52:53], v[28:29], v[40:41]
	v_mov_b32_e32 v30, v49
	v_pk_add_f32 v[28:29], v[40:41], v[50:51]
	v_pk_add_f32 v[54:55], v[48:49], v[42:43]
	v_pk_add_f32 v[30:31], v[42:43], v[30:31]
	v_cndmask_b32_e64 v29, v29, v53, s[10:11]
	v_cndmask_b32_e64 v28, v28, v52, s[10:11]
	v_cndmask_b32_e64 v31, v31, v55, s[10:11]
	v_cndmask_b32_e64 v30, v30, v54, s[10:11]
	global_store_dwordx2 v[36:37], v[28:29], off
	global_store_dwordx2 v[38:39], v[30:31], off
	v_mul_f32_e32 v24, v24, v34
	v_mul_f32_e32 v43, v26, v34
	v_mul_f32_e32 v40, v25, v34
	v_mul_f32_e32 v27, v27, v34
	v_cndmask_b32_e64 v25, v24, v43, s[10:11]
	v_cndmask_b32_e64 v26, v40, v27, s[10:11]
	v_lshl_add_u64 v[36:37], v[124:125], 0, v[32:33]
	v_mov_b32_dpp v25, v25 quad_perm:[1,0,3,2] row_mask:0xf bank_mask:0xf bound_ctrl:1
	v_mov_b32_dpp v41, v26 quad_perm:[1,0,3,2] row_mask:0xf bank_mask:0xf bound_ctrl:1
	v_mov_b32_e32 v42, v25
	v_mov_b32_e32 v26, v41
	v_lshl_add_u64 v[36:37], v[36:37], 0, v[128:129]
	v_add_co_u32_e32 v38, vcc, s73, v36
	v_mul_f32_e32 v20, v20, v34
	s_nop 0
	v_addc_co_u32_e32 v39, vcc, 0, v37, vcc
	v_mul_f32_e32 v23, v23, v34
	v_mul_f32_e32 v16, v16, v34
	v_mul_f32_e32 v19, v19, v34
	v_mul_f32_e32 v12, v12, v34
	v_mul_f32_e32 v15, v15, v34
	v_mul_f32_e32 v8, v8, v34
	v_mul_f32_e32 v11, v11, v34
	v_mul_f32_e32 v4, v4, v34
	v_mul_f32_e32 v7, v7, v34
	v_mul_f32_e32 v0, v0, v34
	v_mul_f32_e32 v3, v3, v34
	s_waitcnt vmcnt(30)
; DI float dppx1(float v) { return __int_as_float(__builtin_amdgcn_update_dpp(0, __float_as_int(v), 0xB1, 0xF, 0xF, true)); }
; DI void rmw_pair_f32(float* xo_even, const float* xi_even, long ld, bool odd, float v0, float v1, float v2, float v3) {
;   const float sx = odd ? v0 : v2, sy = odd ? v1 : v3;
;   const float rx = dppx1(sx), ry = dppx1(sy);
;   const long off = odd ? 2 * ld : 0;
;   const float2 a0 = *(const float2*)(xi_even + off), a1 = *(const float2*)(xi_even + off + ld);
;   float2 o0, o1;
;   if (odd) { o0 = float2{a0.x + rx, a0.y + v2}; o1 = float2{a1.x + ry, a1.y + v3}; }
;   else     { o0 = float2{a0.x + v0, a0.y + rx}; o1 = float2{a1.x + v1, a1.y + ry}; }
;   *(float2*)(xo_even + off) = o0;
;   *(float2*)(xo_even + off + ld) = o1;
; }
; __global__ void __launch_bounds__(NTHR) fwd_kernel(Params pk) {
;     ...
;           for (int bj = 0; bj < 2; ++bj)
; #pragma unroll
;             for (int n = 0; n < 2; ++n) {
;               const int col = pn * 256 + bj * 128 + wc * 32 + n * 16 + fr;
;               const float gv = 0.5f * gate[(long)b * 9216 + col];
; #pragma unroll
;               for (int ai = 0; ai < 2; ++ai)
; #pragma unroll
;                 for (int m = 0; m < 4; ++m) {
;                   const long row0 = (long)pm * 256 + ai * 128 + wr * 64 + m * 16 + fq * 4;
;                   const f32x4 a = acc[ai][bj][m][n];
;                   rmw_pair_f32(xo + row0 * DM + (col & ~1), xin + row0 * DM + (col & ~1), DM, col & 1, gv * a[0], gv * a[1], gv * a[2], gv * a[3]);
;                   asm volatile("" ::: "memory");
;                 }
	v_mov_b64_e32 v[28:29], v[206:207]
	v_mov_b64_e32 v[30:31], v[208:209]
	v_pk_add_f32 v[24:25], v[24:25], v[28:29]
	v_pk_add_f32 v[28:29], v[28:29], v[42:43]
	v_pk_add_f32 v[40:41], v[40:41], v[30:31]
	v_pk_add_f32 v[26:27], v[30:31], v[26:27]
	v_cndmask_b32_e64 v25, v29, v25, s[10:11]
	v_cndmask_b32_e64 v24, v28, v24, s[10:11]
	v_cndmask_b32_e64 v27, v27, v41, s[10:11]
	v_cndmask_b32_e64 v26, v26, v40, s[10:11]
	global_store_dwordx2 v[44:45], v[24:25], off
	global_store_dwordx2 v[46:47], v[26:27], off
	v_mul_f32_e32 v43, v22, v34
	v_mul_f32_e32 v40, v21, v34
	v_cndmask_b32_e64 v21, v20, v43, s[10:11]
	v_cndmask_b32_e64 v22, v40, v23, s[10:11]
	v_lshl_add_u64 v[28:29], v[120:121], 0, v[32:33]
	v_mov_b32_dpp v21, v21 quad_perm:[1,0,3,2] row_mask:0xf bank_mask:0xf bound_ctrl:1
	v_mov_b32_dpp v41, v22 quad_perm:[1,0,3,2] row_mask:0xf bank_mask:0xf bound_ctrl:1
	v_mov_b32_e32 v42, v21
	v_mov_b32_e32 v22, v41
	v_lshl_add_u64 v[28:29], v[28:29], 0, v[128:129]
	v_add_co_u32_e32 v30, vcc, s73, v28
	s_waitcnt vmcnt(30)
	v_mov_b64_e32 v[24:25], v[210:211]
	v_mov_b64_e32 v[26:27], v[212:213]
	v_pk_add_f32 v[20:21], v[20:21], v[24:25]
	v_pk_add_f32 v[24:25], v[24:25], v[42:43]
	v_pk_add_f32 v[40:41], v[40:41], v[26:27]
	v_pk_add_f32 v[22:23], v[26:27], v[22:23]
	v_cndmask_b32_e64 v21, v25, v21, s[10:11]
	v_cndmask_b32_e64 v20, v24, v20, s[10:11]
	v_cndmask_b32_e64 v23, v23, v41, s[10:11]
	v_cndmask_b32_e64 v22, v22, v40, s[10:11]
	global_store_dwordx2 v[36:37], v[20:21], off
	global_store_dwordx2 v[38:39], v[22:23], off
	v_addc_co_u32_e32 v31, vcc, 0, v29, vcc
	v_mul_f32_e32 v39, v18, v34
	v_mul_f32_e32 v36, v17, v34
	v_cndmask_b32_e64 v17, v16, v39, s[10:11]
	v_cndmask_b32_e64 v18, v36, v19, s[10:11]
	v_lshl_add_u64 v[24:25], v[116:117], 0, v[32:33]
	v_mov_b32_dpp v17, v17 quad_perm:[1,0,3,2] row_mask:0xf bank_mask:0xf bound_ctrl:1
	v_mov_b32_dpp v37, v18 quad_perm:[1,0,3,2] row_mask:0xf bank_mask:0xf bound_ctrl:1
	v_mov_b32_e32 v38, v17
	v_mov_b32_e32 v18, v37
	v_lshl_add_u64 v[24:25], v[24:25], 0, v[128:129]
	v_add_co_u32_e32 v26, vcc, s73, v24
	s_waitcnt vmcnt(30)
	v_mov_b64_e32 v[20:21], v[214:215]
	v_mov_b64_e32 v[22:23], v[216:217]
	v_pk_add_f32 v[16:17], v[16:17], v[20:21]
	v_pk_add_f32 v[20:21], v[20:21], v[38:39]
	v_pk_add_f32 v[36:37], v[36:37], v[22:23]
	v_pk_add_f32 v[18:19], v[22:23], v[18:19]
	v_cndmask_b32_e64 v17, v21, v17, s[10:11]
	v_cndmask_b32_e64 v16, v20, v16, s[10:11]
	v_cndmask_b32_e64 v19, v19, v37, s[10:11]
	v_cndmask_b32_e64 v18, v18, v36, s[10:11]
	global_store_dwordx2 v[28:29], v[16:17], off
	global_store_dwordx2 v[30:31], v[18:19], off
	v_addc_co_u32_e32 v27, vcc, 0, v25, vcc
	v_mul_f32_e32 v31, v14, v34
	v_mul_f32_e32 v28, v13, v34
	v_cndmask_b32_e64 v13, v12, v31, s[10:11]
	v_cndmask_b32_e64 v14, v28, v15, s[10:11]
	v_lshl_add_u64 v[20:21], v[112:113], 0, v[32:33]
	v_mov_b32_dpp v13, v13 quad_perm:[1,0,3,2] row_mask:0xf bank_mask:0xf bound_ctrl:1
	v_mov_b32_dpp v29, v14 quad_perm:[1,0,3,2] row_mask:0xf bank_mask:0xf bound_ctrl:1
	v_mov_b32_e32 v30, v13
	v_mov_b32_e32 v14, v29
	v_lshl_add_u64 v[20:21], v[20:21], 0, v[128:129]
	v_add_co_u32_e32 v22, vcc, s73, v20
	s_waitcnt vmcnt(30)
	v_mov_b64_e32 v[16:17], v[218:219]
	v_mov_b64_e32 v[18:19], v[220:221]
	v_pk_add_f32 v[12:13], v[12:13], v[16:17]
	v_pk_add_f32 v[16:17], v[16:17], v[30:31]
	v_pk_add_f32 v[28:29], v[28:29], v[18:19]
	v_pk_add_f32 v[14:15], v[18:19], v[14:15]
	v_cndmask_b32_e64 v13, v17, v13, s[10:11]
	v_cndmask_b32_e64 v12, v16, v12, s[10:11]
	v_cndmask_b32_e64 v15, v15, v29, s[10:11]
	v_cndmask_b32_e64 v14, v14, v28, s[10:11]
	global_store_dwordx2 v[24:25], v[12:13], off
	global_store_dwordx2 v[26:27], v[14:15], off
	v_addc_co_u32_e32 v23, vcc, 0, v21, vcc
	v_mul_f32_e32 v27, v10, v34
	v_mul_f32_e32 v24, v9, v34
	v_cndmask_b32_e64 v9, v8, v27, s[10:11]
	v_cndmask_b32_e64 v10, v24, v11, s[10:11]
	v_lshl_add_u64 v[16:17], v[108:109], 0, v[32:33]
	v_mov_b32_dpp v9, v9 quad_perm:[1,0,3,2] row_mask:0xf bank_mask:0xf bound_ctrl:1
	v_mov_b32_dpp v25, v10 quad_perm:[1,0,3,2] row_mask:0xf bank_mask:0xf bound_ctrl:1
	v_mov_b32_e32 v26, v9
	v_mov_b32_e32 v10, v25
	v_lshl_add_u64 v[16:17], v[16:17], 0, v[128:129]
	v_add_co_u32_e32 v18, vcc, s73, v16
	s_waitcnt vmcnt(30)
	v_mov_b64_e32 v[12:13], v[222:223]
	v_mov_b64_e32 v[14:15], v[224:225]
	v_pk_add_f32 v[8:9], v[8:9], v[12:13]
	v_pk_add_f32 v[12:13], v[12:13], v[26:27]
	v_pk_add_f32 v[24:25], v[24:25], v[14:15]
	v_pk_add_f32 v[10:11], v[14:15], v[10:11]
	v_cndmask_b32_e64 v9, v13, v9, s[10:11]
	v_cndmask_b32_e64 v8, v12, v8, s[10:11]
	v_cndmask_b32_e64 v11, v11, v25, s[10:11]
	v_cndmask_b32_e64 v10, v10, v24, s[10:11]
	global_store_dwordx2 v[20:21], v[8:9], off
	global_store_dwordx2 v[22:23], v[10:11], off
	v_addc_co_u32_e32 v19, vcc, 0, v17, vcc
	v_mul_f32_e32 v23, v6, v34
	v_mul_f32_e32 v20, v5, v34
	v_cndmask_b32_e64 v5, v4, v23, s[10:11]
	v_cndmask_b32_e64 v6, v20, v7, s[10:11]
	v_lshl_add_u64 v[12:13], v[104:105], 0, v[32:33]
	v_mov_b32_dpp v5, v5 quad_perm:[1,0,3,2] row_mask:0xf bank_mask:0xf bound_ctrl:1
	v_mov_b32_dpp v21, v6 quad_perm:[1,0,3,2] row_mask:0xf bank_mask:0xf bound_ctrl:1
	v_mov_b32_e32 v22, v5
	v_mov_b32_e32 v6, v21
	v_lshl_add_u64 v[12:13], v[12:13], 0, v[128:129]
	v_add_co_u32_e32 v14, vcc, s73, v12
	s_waitcnt vmcnt(30)
	v_mov_b64_e32 v[8:9], v[226:227]
	v_mov_b64_e32 v[10:11], v[228:229]
	v_pk_add_f32 v[4:5], v[4:5], v[8:9]
	v_pk_add_f32 v[8:9], v[8:9], v[22:23]
	v_pk_add_f32 v[20:21], v[20:21], v[10:11]
	v_pk_add_f32 v[6:7], v[10:11], v[6:7]
	v_cndmask_b32_e64 v5, v9, v5, s[10:11]
	v_cndmask_b32_e64 v4, v8, v4, s[10:11]
	v_cndmask_b32_e64 v7, v7, v21, s[10:11]
	v_cndmask_b32_e64 v6, v6, v20, s[10:11]
	global_store_dwordx2 v[16:17], v[4:5], off
	global_store_dwordx2 v[18:19], v[6:7], off
	v_addc_co_u32_e32 v15, vcc, 0, v13, vcc
	v_mul_f32_e32 v11, v2, v34
	v_mul_f32_e32 v8, v1, v34
	v_cndmask_b32_e64 v1, v0, v11, s[10:11]
	v_cndmask_b32_e64 v2, v8, v3, s[10:11]
	s_andn2_b64 vcc, exec, s[62:63]
	v_mov_b32_dpp v1, v1 quad_perm:[1,0,3,2] row_mask:0xf bank_mask:0xf bound_ctrl:1
	v_mov_b32_dpp v9, v2 quad_perm:[1,0,3,2] row_mask:0xf bank_mask:0xf bound_ctrl:1
	v_mov_b32_e32 v10, v1
	v_mov_b32_e32 v2, v9
	s_waitcnt vmcnt(30)
	v_mov_b64_e32 v[4:5], v[230:231]
	v_mov_b64_e32 v[6:7], v[232:233]
	v_pk_add_f32 v[0:1], v[0:1], v[4:5]
	v_pk_add_f32 v[4:5], v[4:5], v[10:11]
	v_pk_add_f32 v[8:9], v[8:9], v[6:7]
	v_pk_add_f32 v[2:3], v[6:7], v[2:3]
	v_cndmask_b32_e64 v1, v5, v1, s[10:11]
	v_cndmask_b32_e64 v0, v4, v0, s[10:11]
	v_cndmask_b32_e64 v3, v3, v9, s[10:11]
	v_cndmask_b32_e64 v2, v2, v8, s[10:11]
	global_store_dwordx2 v[12:13], v[0:1], off
	global_store_dwordx2 v[14:15], v[2:3], off
	s_waitcnt vmcnt(0)
	s_mov_b32 s10, s80
	s_waitcnt lgkmcnt(0)
	s_barrier
	s_cbranch_vccz .LBB0_1025
